# GEMM MFMA clusters: extra momentary priority drops (every 8 MFMAs) so the co-resident loading wave gets issue windows
# speedup vs baseline: 1.0104x; 1.0022x over previous
.Lh9_17:
	global_load_lds_dwordx4 v[176:177], off
	v_lshl_add_u64 v[176:177], v[136:137], 0, s[8:9]
	s_add_i32 m0, s17, 0xe000
	s_nop 0
	global_load_lds_dwordx4 v[176:177], off
	s_waitcnt vmcnt(8)
	s_waitcnt lgkmcnt(0)
	s_barrier
	s_cmp_eq_u32 s32, 2
	s_cbranch_scc1 .Lh9_18
	s_setprio 1
	s_waitcnt lgkmcnt(0)
	v_mfma_f32_16x16x32_bf16 v[126:129], v[144:147], v[208:211], v[126:129]
	v_mfma_f32_16x16x32_bf16 v[122:125], v[152:155], v[208:211], v[122:125]
	v_mfma_f32_16x16x32_bf16 v[118:121], v[144:147], v[216:219], v[118:121]
	v_mfma_f32_16x16x32_bf16 v[114:117], v[152:155], v[216:219], v[114:117]
	v_mfma_f32_16x16x32_bf16 v[102:105], v[144:147], v[224:227], v[102:105]
	v_mfma_f32_16x16x32_bf16 v[98:101], v[152:155], v[224:227], v[98:101]
	v_mfma_f32_16x16x32_bf16 v[86:89], v[144:147], v[232:235], v[86:89]
	v_mfma_f32_16x16x32_bf16 v[82:85], v[152:155], v[232:235], v[82:85]
	s_setprio 0
	s_setprio 1
	v_mfma_f32_16x16x32_bf16 v[126:129], v[148:151], v[212:215], v[126:129]
	v_mfma_f32_16x16x32_bf16 v[122:125], v[158:161], v[212:215], v[122:125]
	v_mfma_f32_16x16x32_bf16 v[118:121], v[148:151], v[220:223], v[118:121]
	v_mfma_f32_16x16x32_bf16 v[114:117], v[158:161], v[220:223], v[114:117]
	v_mfma_f32_16x16x32_bf16 v[102:105], v[148:151], v[228:231], v[102:105]
	v_mfma_f32_16x16x32_bf16 v[98:101], v[158:161], v[228:231], v[98:101]
	v_mfma_f32_16x16x32_bf16 v[86:89], v[148:151], v[236:239], v[86:89]
	v_mfma_f32_16x16x32_bf16 v[82:85], v[158:161], v[236:239], v[82:85]
	s_setprio 0
	s_setprio 1
	v_mfma_f32_16x16x32_bf16 v[110:113], v[162:165], v[208:211], v[110:113]
	v_mfma_f32_16x16x32_bf16 v[106:109], v[200:203], v[208:211], v[106:109]
	v_mfma_f32_16x16x32_bf16 v[94:97], v[162:165], v[216:219], v[94:97]
	v_mfma_f32_16x16x32_bf16 v[90:93], v[200:203], v[216:219], v[90:93]
	v_mfma_f32_16x16x32_bf16 v[78:81], v[162:165], v[224:227], v[78:81]
	v_mfma_f32_16x16x32_bf16 v[74:77], v[200:203], v[224:227], v[74:77]
	v_mfma_f32_16x16x32_bf16 v[70:73], v[162:165], v[232:235], v[70:73]
	v_mfma_f32_16x16x32_bf16 v[66:69], v[200:203], v[232:235], v[66:69]
	s_setprio 0
	s_setprio 1
	v_mfma_f32_16x16x32_bf16 v[110:113], v[196:199], v[212:215], v[110:113]
	v_mfma_f32_16x16x32_bf16 v[106:109], v[204:207], v[212:215], v[106:109]
	v_mfma_f32_16x16x32_bf16 v[94:97], v[196:199], v[220:223], v[94:97]
	v_mfma_f32_16x16x32_bf16 v[90:93], v[204:207], v[220:223], v[90:93]
	v_mfma_f32_16x16x32_bf16 v[78:81], v[196:199], v[228:231], v[78:81]
	v_mfma_f32_16x16x32_bf16 v[74:77], v[204:207], v[228:231], v[74:77]
	v_mfma_f32_16x16x32_bf16 v[70:73], v[196:199], v[236:239], v[70:73]
	v_mfma_f32_16x16x32_bf16 v[66:69], v[204:207], v[236:239], v[66:69]
	s_setprio 0

.Lh9_19:
	global_load_lds_dwordx4 v[176:177], off
	s_add_i32 m0, s20, 0x2000
	s_add_u32 s62, s18, 0xb0000
	v_lshl_add_u64 v[178:179], s[18:19], 0, v[134:135]
	s_addc_u32 s63, s19, 0
	s_add_i32 s20, s59, s16
	global_load_lds_dwordx4 v[178:179], off
	v_lshl_add_u64 v[194:195], s[62:63], 0, v[0:1]
	s_mov_b32 m0, s20
	v_lshl_add_u64 v[240:241], s[40:41], 0, v[132:133]
	global_load_lds_dwordx4 v[194:195], off
	v_lshl_add_u64 v[194:195], s[62:63], 0, v[134:135]
	s_add_i32 m0, s20, 0x2000
	s_nop 0
	global_load_lds_dwordx4 v[194:195], off
	v_lshl_add_u64 v[194:195], s[40:41], 0, v[130:131]
	s_mov_b32 m0, s17
	s_nop 0
	global_load_lds_dwordx4 v[194:195], off
	s_mov_b32 m0, s28
	s_nop 0
	global_load_lds_dwordx4 v[240:241], off
	s_waitcnt vmcnt(8)
	s_waitcnt lgkmcnt(0)
	s_barrier
	s_cmp_eq_u32 s32, 1
	s_cbranch_scc1 .Lh9_20
	s_setprio 1
	s_waitcnt lgkmcnt(0)
	v_mfma_f32_16x16x32_bf16 v[62:65], v[144:147], v[208:211], v[62:65]
	v_mfma_f32_16x16x32_bf16 v[58:61], v[152:155], v[208:211], v[58:61]
	v_mfma_f32_16x16x32_bf16 v[54:57], v[144:147], v[216:219], v[54:57]
	v_mfma_f32_16x16x32_bf16 v[50:53], v[152:155], v[216:219], v[50:53]
	v_mfma_f32_16x16x32_bf16 v[38:41], v[144:147], v[224:227], v[38:41]
	v_mfma_f32_16x16x32_bf16 v[34:37], v[152:155], v[224:227], v[34:37]
	v_mfma_f32_16x16x32_bf16 v[22:25], v[144:147], v[232:235], v[22:25]
	v_mfma_f32_16x16x32_bf16 v[18:21], v[152:155], v[232:235], v[18:21]
	s_setprio 0
	s_setprio 1
	v_mfma_f32_16x16x32_bf16 v[62:65], v[148:151], v[212:215], v[62:65]
	v_mfma_f32_16x16x32_bf16 v[58:61], v[158:161], v[212:215], v[58:61]
	v_mfma_f32_16x16x32_bf16 v[54:57], v[148:151], v[220:223], v[54:57]
	v_mfma_f32_16x16x32_bf16 v[50:53], v[158:161], v[220:223], v[50:53]
	v_mfma_f32_16x16x32_bf16 v[38:41], v[148:151], v[228:231], v[38:41]
	v_mfma_f32_16x16x32_bf16 v[34:37], v[158:161], v[228:231], v[34:37]
	v_mfma_f32_16x16x32_bf16 v[22:25], v[148:151], v[236:239], v[22:25]
	v_mfma_f32_16x16x32_bf16 v[18:21], v[158:161], v[236:239], v[18:21]
	s_setprio 0
	s_setprio 1
	v_mfma_f32_16x16x32_bf16 v[46:49], v[162:165], v[208:211], v[46:49]
	v_mfma_f32_16x16x32_bf16 v[42:45], v[200:203], v[208:211], v[42:45]
	v_mfma_f32_16x16x32_bf16 v[30:33], v[162:165], v[216:219], v[30:33]
	v_mfma_f32_16x16x32_bf16 v[26:29], v[200:203], v[216:219], v[26:29]
	v_mfma_f32_16x16x32_bf16 v[14:17], v[162:165], v[224:227], v[14:17]
	v_mfma_f32_16x16x32_bf16 v[10:13], v[200:203], v[224:227], v[10:13]
	v_mfma_f32_16x16x32_bf16 v[6:9], v[162:165], v[232:235], v[6:9]
	v_mfma_f32_16x16x32_bf16 v[2:5], v[200:203], v[232:235], v[2:5]
	s_setprio 0
	s_setprio 1
	v_mfma_f32_16x16x32_bf16 v[46:49], v[196:199], v[212:215], v[46:49]
	v_mfma_f32_16x16x32_bf16 v[42:45], v[204:207], v[212:215], v[42:45]
	v_mfma_f32_16x16x32_bf16 v[30:33], v[196:199], v[220:223], v[30:33]
	v_mfma_f32_16x16x32_bf16 v[26:29], v[204:207], v[220:223], v[26:29]
	v_mfma_f32_16x16x32_bf16 v[14:17], v[196:199], v[228:231], v[14:17]
	v_mfma_f32_16x16x32_bf16 v[10:13], v[204:207], v[228:231], v[10:13]
	v_mfma_f32_16x16x32_bf16 v[6:9], v[196:199], v[236:239], v[6:9]
	v_mfma_f32_16x16x32_bf16 v[2:5], v[204:207], v[236:239], v[2:5]
	s_setprio 0

.Lh9_21:
	global_load_lds_dwordx4 v[242:243], off
	v_lshl_add_u64 v[242:243], s[40:41], 0, v[132:133]
	s_mov_b32 m0, s43
	s_nop 0
	global_load_lds_dwordx4 v[242:243], off
	s_waitcnt vmcnt(8)
	s_waitcnt lgkmcnt(0)
	s_barrier
	s_cmp_eq_u32 s32, 2
	s_cbranch_scc1 .Lh9_22
	s_setprio 1
	s_waitcnt lgkmcnt(0)
	v_mfma_f32_16x16x32_bf16 v[126:129], v[144:147], v[208:211], v[126:129]
	v_mfma_f32_16x16x32_bf16 v[122:125], v[152:155], v[208:211], v[122:125]
	v_mfma_f32_16x16x32_bf16 v[118:121], v[144:147], v[216:219], v[118:121]
	v_mfma_f32_16x16x32_bf16 v[114:117], v[152:155], v[216:219], v[114:117]
	v_mfma_f32_16x16x32_bf16 v[102:105], v[144:147], v[224:227], v[102:105]
	v_mfma_f32_16x16x32_bf16 v[98:101], v[152:155], v[224:227], v[98:101]
	v_mfma_f32_16x16x32_bf16 v[86:89], v[144:147], v[232:235], v[86:89]
	v_mfma_f32_16x16x32_bf16 v[82:85], v[152:155], v[232:235], v[82:85]
	s_setprio 0
	s_setprio 1
	v_mfma_f32_16x16x32_bf16 v[126:129], v[148:151], v[212:215], v[126:129]
	v_mfma_f32_16x16x32_bf16 v[122:125], v[158:161], v[212:215], v[122:125]
	v_mfma_f32_16x16x32_bf16 v[118:121], v[148:151], v[220:223], v[118:121]
	v_mfma_f32_16x16x32_bf16 v[114:117], v[158:161], v[220:223], v[114:117]
	v_mfma_f32_16x16x32_bf16 v[102:105], v[148:151], v[228:231], v[102:105]
	v_mfma_f32_16x16x32_bf16 v[98:101], v[158:161], v[228:231], v[98:101]
	v_mfma_f32_16x16x32_bf16 v[86:89], v[148:151], v[236:239], v[86:89]
	v_mfma_f32_16x16x32_bf16 v[82:85], v[158:161], v[236:239], v[82:85]
	s_setprio 0
	s_setprio 1
	v_mfma_f32_16x16x32_bf16 v[110:113], v[162:165], v[208:211], v[110:113]
	v_mfma_f32_16x16x32_bf16 v[106:109], v[200:203], v[208:211], v[106:109]
	v_mfma_f32_16x16x32_bf16 v[94:97], v[162:165], v[216:219], v[94:97]
	v_mfma_f32_16x16x32_bf16 v[90:93], v[200:203], v[216:219], v[90:93]
	v_mfma_f32_16x16x32_bf16 v[78:81], v[162:165], v[224:227], v[78:81]
	v_mfma_f32_16x16x32_bf16 v[74:77], v[200:203], v[224:227], v[74:77]
	v_mfma_f32_16x16x32_bf16 v[70:73], v[162:165], v[232:235], v[70:73]
	v_mfma_f32_16x16x32_bf16 v[66:69], v[200:203], v[232:235], v[66:69]
	s_setprio 0
	s_setprio 1
	v_mfma_f32_16x16x32_bf16 v[110:113], v[196:199], v[212:215], v[110:113]
	v_mfma_f32_16x16x32_bf16 v[106:109], v[204:207], v[212:215], v[106:109]
	v_mfma_f32_16x16x32_bf16 v[94:97], v[196:199], v[220:223], v[94:97]
	v_mfma_f32_16x16x32_bf16 v[90:93], v[204:207], v[220:223], v[90:93]
	v_mfma_f32_16x16x32_bf16 v[78:81], v[196:199], v[228:231], v[78:81]
	v_mfma_f32_16x16x32_bf16 v[74:77], v[204:207], v[228:231], v[74:77]
	v_mfma_f32_16x16x32_bf16 v[70:73], v[196:199], v[236:239], v[70:73]
	v_mfma_f32_16x16x32_bf16 v[66:69], v[204:207], v[236:239], v[66:69]
	s_setprio 0

.Lh9_23:
	global_load_lds_dwordx4 v[176:177], off
	s_add_i32 m0, s20, 0x2000
	s_add_u32 s18, s18, 0xb0080
	v_lshl_add_u64 v[176:177], v[178:179], 0, s[24:25]
	s_addc_u32 s19, s19, 0
	s_add_i32 s20, s59, s16
	global_load_lds_dwordx4 v[176:177], off
	v_lshl_add_u64 v[176:177], s[18:19], 0, v[0:1]
	s_mov_b32 m0, s20
	s_nop 0
	global_load_lds_dwordx4 v[176:177], off
	v_lshl_add_u64 v[176:177], s[18:19], 0, v[134:135]
	s_add_i32 m0, s20, 0x2000
	s_nop 0
	global_load_lds_dwordx4 v[176:177], off
	v_lshl_add_u64 v[176:177], v[194:195], 0, s[24:25]
	s_mov_b32 m0, s46
	s_nop 0
	global_load_lds_dwordx4 v[176:177], off
	v_lshl_add_u64 v[176:177], v[240:241], 0, s[24:25]
	s_mov_b32 m0, s47
	s_nop 0
	global_load_lds_dwordx4 v[176:177], off
	s_waitcnt vmcnt(8)
	s_waitcnt lgkmcnt(0)
	s_barrier
	s_cmp_eq_u32 s32, 1
	s_cbranch_scc1 .Lh9_24
	s_setprio 1
	s_waitcnt lgkmcnt(0)
	v_mfma_f32_16x16x32_bf16 v[62:65], v[144:147], v[208:211], v[62:65]
	v_mfma_f32_16x16x32_bf16 v[58:61], v[152:155], v[208:211], v[58:61]
	v_mfma_f32_16x16x32_bf16 v[54:57], v[144:147], v[216:219], v[54:57]
	v_mfma_f32_16x16x32_bf16 v[50:53], v[152:155], v[216:219], v[50:53]
	v_mfma_f32_16x16x32_bf16 v[38:41], v[144:147], v[224:227], v[38:41]
	v_mfma_f32_16x16x32_bf16 v[34:37], v[152:155], v[224:227], v[34:37]
	v_mfma_f32_16x16x32_bf16 v[22:25], v[144:147], v[232:235], v[22:25]
	v_mfma_f32_16x16x32_bf16 v[18:21], v[152:155], v[232:235], v[18:21]
	s_setprio 0
	s_setprio 1
	v_mfma_f32_16x16x32_bf16 v[62:65], v[148:151], v[212:215], v[62:65]
	v_mfma_f32_16x16x32_bf16 v[58:61], v[158:161], v[212:215], v[58:61]
	v_mfma_f32_16x16x32_bf16 v[54:57], v[148:151], v[220:223], v[54:57]
	v_mfma_f32_16x16x32_bf16 v[50:53], v[158:161], v[220:223], v[50:53]
	v_mfma_f32_16x16x32_bf16 v[38:41], v[148:151], v[228:231], v[38:41]
	v_mfma_f32_16x16x32_bf16 v[34:37], v[158:161], v[228:231], v[34:37]
	v_mfma_f32_16x16x32_bf16 v[22:25], v[148:151], v[236:239], v[22:25]
	v_mfma_f32_16x16x32_bf16 v[18:21], v[158:161], v[236:239], v[18:21]
	s_setprio 0
	s_setprio 1
	v_mfma_f32_16x16x32_bf16 v[46:49], v[162:165], v[208:211], v[46:49]
	v_mfma_f32_16x16x32_bf16 v[42:45], v[200:203], v[208:211], v[42:45]
	v_mfma_f32_16x16x32_bf16 v[30:33], v[162:165], v[216:219], v[30:33]
	v_mfma_f32_16x16x32_bf16 v[26:29], v[200:203], v[216:219], v[26:29]
	v_mfma_f32_16x16x32_bf16 v[14:17], v[162:165], v[224:227], v[14:17]
	v_mfma_f32_16x16x32_bf16 v[10:13], v[200:203], v[224:227], v[10:13]
	v_mfma_f32_16x16x32_bf16 v[6:9], v[162:165], v[232:235], v[6:9]
	v_mfma_f32_16x16x32_bf16 v[2:5], v[200:203], v[232:235], v[2:5]
	s_setprio 0
	s_setprio 1
	v_mfma_f32_16x16x32_bf16 v[46:49], v[196:199], v[212:215], v[46:49]
	v_mfma_f32_16x16x32_bf16 v[42:45], v[204:207], v[212:215], v[42:45]
	v_mfma_f32_16x16x32_bf16 v[30:33], v[196:199], v[220:223], v[30:33]
	v_mfma_f32_16x16x32_bf16 v[26:29], v[204:207], v[220:223], v[26:29]
	v_mfma_f32_16x16x32_bf16 v[14:17], v[196:199], v[228:231], v[14:17]
	v_mfma_f32_16x16x32_bf16 v[10:13], v[204:207], v[228:231], v[10:13]
	v_mfma_f32_16x16x32_bf16 v[6:9], v[196:199], v[236:239], v[6:9]
	v_mfma_f32_16x16x32_bf16 v[2:5], v[204:207], v[236:239], v[2:5]
	s_setprio 0

.LBB0_81:
	s_add_u32 s20, s94, 0xfce78080
	s_addc_u32 s59, s95, -1
	s_cmp_lg_u32 s58, 12
	s_cselect_b32 s20, s20, 0
	s_cselect_b32 s59, s59, 0
	s_add_u32 vcc_lo, s40, s20
	s_addc_u32 vcc_hi, s41, s59
	s_add_i32 s82, 0, 0x10000
	s_add_u32 s96, s42, s20
	v_add_u32_e32 v143, s82, v141
	s_addc_u32 s97, s43, s59
	s_add_i32 s20, 0, 0x14000
	ds_read_b128 v[144:147], v143
	ds_read_b128 v[148:151], v143 offset:1024
	ds_read_b128 v[152:155], v143 offset:2048
	ds_read_b128 v[158:161], v143 offset:3072
	v_add_u32_e32 v143, s20, v141
	ds_read_b128 v[162:165], v143
	ds_read_b128 v[196:199], v143 offset:1024
	ds_read_b128 v[200:203], v143 offset:2048
	ds_read_b128 v[204:207], v143 offset:3072
	v_lshl_add_u64 v[176:177], v[138:139], 0, s[94:95]
	s_add_i32 m0, s16, 0xc000
	ds_read_b128 v[208:211], v142
	ds_read_b128 v[212:215], v142 offset:1024
	ds_read_b128 v[216:219], v142 offset:2048
	ds_read_b128 v[220:223], v142 offset:3072
	ds_read_b128 v[224:227], v142 offset:4096
	ds_read_b128 v[228:231], v142 offset:5120
	ds_read_b128 v[232:235], v142 offset:6144
	ds_read_b128 v[236:239], v142 offset:7168
	global_load_lds_dwordx4 v[176:177], off
	v_lshl_add_u64 v[176:177], v[136:137], 0, s[94:95]
	s_add_i32 m0, s16, 0xe000
	s_nop 0
	global_load_lds_dwordx4 v[176:177], off
	s_waitcnt vmcnt(8)
	s_waitcnt lgkmcnt(0)
	s_barrier
	s_setprio 1
	s_waitcnt lgkmcnt(0)
	v_mfma_f32_16x16x32_bf16 v[126:129], v[144:147], v[208:211], v[126:129]
	v_mfma_f32_16x16x32_bf16 v[122:125], v[152:155], v[208:211], v[122:125]
	v_mfma_f32_16x16x32_bf16 v[118:121], v[144:147], v[216:219], v[118:121]
	v_mfma_f32_16x16x32_bf16 v[114:117], v[152:155], v[216:219], v[114:117]
	v_mfma_f32_16x16x32_bf16 v[102:105], v[144:147], v[224:227], v[102:105]
	v_mfma_f32_16x16x32_bf16 v[98:101], v[152:155], v[224:227], v[98:101]
	v_mfma_f32_16x16x32_bf16 v[86:89], v[144:147], v[232:235], v[86:89]
	v_mfma_f32_16x16x32_bf16 v[82:85], v[152:155], v[232:235], v[82:85]
	s_setprio 0
	s_setprio 1
	v_mfma_f32_16x16x32_bf16 v[126:129], v[148:151], v[212:215], v[126:129]
	v_mfma_f32_16x16x32_bf16 v[122:125], v[158:161], v[212:215], v[122:125]
	v_mfma_f32_16x16x32_bf16 v[118:121], v[148:151], v[220:223], v[118:121]
	v_mfma_f32_16x16x32_bf16 v[114:117], v[158:161], v[220:223], v[114:117]
	v_mfma_f32_16x16x32_bf16 v[102:105], v[148:151], v[228:231], v[102:105]
	v_mfma_f32_16x16x32_bf16 v[98:101], v[158:161], v[228:231], v[98:101]
	v_mfma_f32_16x16x32_bf16 v[86:89], v[148:151], v[236:239], v[86:89]
	v_mfma_f32_16x16x32_bf16 v[82:85], v[158:161], v[236:239], v[82:85]
	s_setprio 0
	s_setprio 1
	v_mfma_f32_16x16x32_bf16 v[110:113], v[162:165], v[208:211], v[110:113]
	v_mfma_f32_16x16x32_bf16 v[106:109], v[200:203], v[208:211], v[106:109]
	v_mfma_f32_16x16x32_bf16 v[94:97], v[162:165], v[216:219], v[94:97]
	v_mfma_f32_16x16x32_bf16 v[90:93], v[200:203], v[216:219], v[90:93]
	v_mfma_f32_16x16x32_bf16 v[78:81], v[162:165], v[224:227], v[78:81]
	v_mfma_f32_16x16x32_bf16 v[74:77], v[200:203], v[224:227], v[74:77]
	v_mfma_f32_16x16x32_bf16 v[70:73], v[162:165], v[232:235], v[70:73]
	v_mfma_f32_16x16x32_bf16 v[66:69], v[200:203], v[232:235], v[66:69]
	s_setprio 0
	s_setprio 1
	v_mfma_f32_16x16x32_bf16 v[110:113], v[196:199], v[212:215], v[110:113]
	v_mfma_f32_16x16x32_bf16 v[106:109], v[204:207], v[212:215], v[106:109]
	v_mfma_f32_16x16x32_bf16 v[94:97], v[196:199], v[220:223], v[94:97]
	v_mfma_f32_16x16x32_bf16 v[90:93], v[204:207], v[220:223], v[90:93]
	v_mfma_f32_16x16x32_bf16 v[78:81], v[196:199], v[228:231], v[78:81]
	v_mfma_f32_16x16x32_bf16 v[74:77], v[204:207], v[228:231], v[74:77]
	v_mfma_f32_16x16x32_bf16 v[70:73], v[196:199], v[236:239], v[70:73]
	v_mfma_f32_16x16x32_bf16 v[66:69], v[204:207], v[236:239], v[66:69]
	s_setprio 0
	s_barrier
	s_add_i32 s59, s82, s3
	v_lshl_add_u64 v[176:177], s[96:97], 0, v[0:1]
	s_mov_b32 m0, s59
	ds_read_b128 v[208:211], v142 offset:16384
	ds_read_b128 v[212:215], v142 offset:17408
	ds_read_b128 v[216:219], v142 offset:18432
	ds_read_b128 v[220:223], v142 offset:19456
	ds_read_b128 v[224:227], v142 offset:20480
	ds_read_b128 v[228:231], v142 offset:21504
	ds_read_b128 v[232:235], v142 offset:22528
	ds_read_b128 v[236:239], v142 offset:23552
	global_load_lds_dwordx4 v[176:177], off
	s_add_i32 m0, s59, 0x2000
	s_add_u32 s82, s96, 0x580000
	v_lshl_add_u64 v[178:179], s[96:97], 0, v[134:135]
	s_addc_u32 s83, s97, 0
	s_add_i32 s20, s20, s3
	global_load_lds_dwordx4 v[178:179], off
	v_lshl_add_u64 v[194:195], s[82:83], 0, v[0:1]
	s_mov_b32 m0, s20
	v_lshl_add_u64 v[240:241], vcc, 0, v[132:133]
	global_load_lds_dwordx4 v[194:195], off
	v_lshl_add_u64 v[194:195], s[82:83], 0, v[134:135]
	s_add_i32 m0, s20, 0x2000
	s_nop 0
	global_load_lds_dwordx4 v[194:195], off
	v_lshl_add_u64 v[194:195], vcc, 0, v[130:131]
	s_mov_b32 m0, s16
	s_nop 0
	global_load_lds_dwordx4 v[194:195], off
	s_mov_b32 m0, s17
	s_nop 0
	global_load_lds_dwordx4 v[240:241], off
	s_waitcnt vmcnt(8)
	s_waitcnt lgkmcnt(0)
	s_barrier
	s_setprio 1
	s_waitcnt lgkmcnt(0)
	v_mfma_f32_16x16x32_bf16 v[62:65], v[144:147], v[208:211], v[62:65]
	v_mfma_f32_16x16x32_bf16 v[58:61], v[152:155], v[208:211], v[58:61]
	v_mfma_f32_16x16x32_bf16 v[54:57], v[144:147], v[216:219], v[54:57]
	v_mfma_f32_16x16x32_bf16 v[50:53], v[152:155], v[216:219], v[50:53]
	v_mfma_f32_16x16x32_bf16 v[38:41], v[144:147], v[224:227], v[38:41]
	v_mfma_f32_16x16x32_bf16 v[34:37], v[152:155], v[224:227], v[34:37]
	v_mfma_f32_16x16x32_bf16 v[22:25], v[144:147], v[232:235], v[22:25]
	v_mfma_f32_16x16x32_bf16 v[18:21], v[152:155], v[232:235], v[18:21]
	s_setprio 0
	s_setprio 1
	v_mfma_f32_16x16x32_bf16 v[62:65], v[148:151], v[212:215], v[62:65]
	v_mfma_f32_16x16x32_bf16 v[58:61], v[158:161], v[212:215], v[58:61]
	v_mfma_f32_16x16x32_bf16 v[54:57], v[148:151], v[220:223], v[54:57]
	v_mfma_f32_16x16x32_bf16 v[50:53], v[158:161], v[220:223], v[50:53]
	v_mfma_f32_16x16x32_bf16 v[38:41], v[148:151], v[228:231], v[38:41]
	v_mfma_f32_16x16x32_bf16 v[34:37], v[158:161], v[228:231], v[34:37]
	v_mfma_f32_16x16x32_bf16 v[22:25], v[148:151], v[236:239], v[22:25]
	v_mfma_f32_16x16x32_bf16 v[18:21], v[158:161], v[236:239], v[18:21]
	s_setprio 0
	s_setprio 1
	v_mfma_f32_16x16x32_bf16 v[46:49], v[162:165], v[208:211], v[46:49]
	v_mfma_f32_16x16x32_bf16 v[42:45], v[200:203], v[208:211], v[42:45]
	v_mfma_f32_16x16x32_bf16 v[30:33], v[162:165], v[216:219], v[30:33]
	v_mfma_f32_16x16x32_bf16 v[26:29], v[200:203], v[216:219], v[26:29]
	v_mfma_f32_16x16x32_bf16 v[14:17], v[162:165], v[224:227], v[14:17]
	v_mfma_f32_16x16x32_bf16 v[10:13], v[200:203], v[224:227], v[10:13]
	v_mfma_f32_16x16x32_bf16 v[6:9], v[162:165], v[232:235], v[6:9]
	v_mfma_f32_16x16x32_bf16 v[2:5], v[200:203], v[232:235], v[2:5]
	s_setprio 0
	s_setprio 1
	v_mfma_f32_16x16x32_bf16 v[46:49], v[196:199], v[212:215], v[46:49]
	v_mfma_f32_16x16x32_bf16 v[42:45], v[204:207], v[212:215], v[42:45]
	v_mfma_f32_16x16x32_bf16 v[30:33], v[196:199], v[220:223], v[30:33]
	v_mfma_f32_16x16x32_bf16 v[26:29], v[204:207], v[220:223], v[26:29]
	v_mfma_f32_16x16x32_bf16 v[14:17], v[196:199], v[228:231], v[14:17]
	v_mfma_f32_16x16x32_bf16 v[10:13], v[204:207], v[228:231], v[10:13]
	v_mfma_f32_16x16x32_bf16 v[6:9], v[196:199], v[236:239], v[6:9]
	v_mfma_f32_16x16x32_bf16 v[2:5], v[204:207], v[236:239], v[2:5]
	s_setprio 0
	s_barrier
	s_add_i32 s20, 0, 0x18000
	v_add_u32_e32 v143, s20, v141
	s_add_i32 s59, 0, 0x1c000
	ds_read_b128 v[144:147], v143
	ds_read_b128 v[148:151], v143 offset:1024
	ds_read_b128 v[152:155], v143 offset:2048
	ds_read_b128 v[158:161], v143 offset:3072
	v_add_u32_e32 v143, s59, v141
	ds_read_b128 v[162:165], v143
	ds_read_b128 v[196:199], v143 offset:1024
	ds_read_b128 v[200:203], v143 offset:2048
	ds_read_b128 v[204:207], v143 offset:3072
	s_add_u32 s82, vcc_lo, 0x40000
	s_addc_u32 s83, vcc_hi, 0
	s_mov_b32 m0, s28
	v_lshl_add_u64 v[242:243], s[82:83], 0, v[130:131]
	ds_read_b128 v[208:211], v142 offset:32768
	ds_read_b128 v[212:215], v142 offset:33792
	ds_read_b128 v[216:219], v142 offset:34816
	ds_read_b128 v[220:223], v142 offset:35840
	ds_read_b128 v[224:227], v142 offset:36864
	ds_read_b128 v[228:231], v142 offset:37888
	ds_read_b128 v[232:235], v142 offset:38912
	ds_read_b128 v[236:239], v142 offset:39936
	global_load_lds_dwordx4 v[242:243], off
	v_lshl_add_u64 v[242:243], s[82:83], 0, v[132:133]
	s_mov_b32 m0, s70
	s_nop 0
	global_load_lds_dwordx4 v[242:243], off
	s_waitcnt vmcnt(8)
	s_waitcnt lgkmcnt(0)
	s_barrier
	s_setprio 1
	s_waitcnt lgkmcnt(0)
	v_mfma_f32_16x16x32_bf16 v[126:129], v[144:147], v[208:211], v[126:129]
	v_mfma_f32_16x16x32_bf16 v[122:125], v[152:155], v[208:211], v[122:125]
	v_mfma_f32_16x16x32_bf16 v[118:121], v[144:147], v[216:219], v[118:121]
	v_mfma_f32_16x16x32_bf16 v[114:117], v[152:155], v[216:219], v[114:117]
	v_mfma_f32_16x16x32_bf16 v[102:105], v[144:147], v[224:227], v[102:105]
	v_mfma_f32_16x16x32_bf16 v[98:101], v[152:155], v[224:227], v[98:101]
	v_mfma_f32_16x16x32_bf16 v[86:89], v[144:147], v[232:235], v[86:89]
	v_mfma_f32_16x16x32_bf16 v[82:85], v[152:155], v[232:235], v[82:85]
	s_setprio 0
	s_setprio 1
	v_mfma_f32_16x16x32_bf16 v[126:129], v[148:151], v[212:215], v[126:129]
	v_mfma_f32_16x16x32_bf16 v[122:125], v[158:161], v[212:215], v[122:125]
	v_mfma_f32_16x16x32_bf16 v[118:121], v[148:151], v[220:223], v[118:121]
	v_mfma_f32_16x16x32_bf16 v[114:117], v[158:161], v[220:223], v[114:117]
	v_mfma_f32_16x16x32_bf16 v[102:105], v[148:151], v[228:231], v[102:105]
	v_mfma_f32_16x16x32_bf16 v[98:101], v[158:161], v[228:231], v[98:101]
	v_mfma_f32_16x16x32_bf16 v[86:89], v[148:151], v[236:239], v[86:89]
	v_mfma_f32_16x16x32_bf16 v[82:85], v[158:161], v[236:239], v[82:85]
	s_setprio 0
	s_setprio 1
	v_mfma_f32_16x16x32_bf16 v[110:113], v[162:165], v[208:211], v[110:113]
	v_mfma_f32_16x16x32_bf16 v[106:109], v[200:203], v[208:211], v[106:109]
	v_mfma_f32_16x16x32_bf16 v[94:97], v[162:165], v[216:219], v[94:97]
	v_mfma_f32_16x16x32_bf16 v[90:93], v[200:203], v[216:219], v[90:93]
	v_mfma_f32_16x16x32_bf16 v[78:81], v[162:165], v[224:227], v[78:81]
	v_mfma_f32_16x16x32_bf16 v[74:77], v[200:203], v[224:227], v[74:77]
	v_mfma_f32_16x16x32_bf16 v[70:73], v[162:165], v[232:235], v[70:73]
	v_mfma_f32_16x16x32_bf16 v[66:69], v[200:203], v[232:235], v[66:69]
	s_setprio 0
	s_setprio 1
	v_mfma_f32_16x16x32_bf16 v[110:113], v[196:199], v[212:215], v[110:113]
	v_mfma_f32_16x16x32_bf16 v[106:109], v[204:207], v[212:215], v[106:109]
	v_mfma_f32_16x16x32_bf16 v[94:97], v[196:199], v[220:223], v[94:97]
	v_mfma_f32_16x16x32_bf16 v[90:93], v[204:207], v[220:223], v[90:93]
	v_mfma_f32_16x16x32_bf16 v[78:81], v[196:199], v[228:231], v[78:81]
	v_mfma_f32_16x16x32_bf16 v[74:77], v[204:207], v[228:231], v[74:77]
	v_mfma_f32_16x16x32_bf16 v[70:73], v[196:199], v[236:239], v[70:73]
	v_mfma_f32_16x16x32_bf16 v[66:69], v[204:207], v[236:239], v[66:69]
	s_setprio 0
	s_barrier
	s_add_i32 s20, s20, s3
	v_lshl_add_u64 v[176:177], v[176:177], 0, s[24:25]
	s_mov_b32 m0, s20
	ds_read_b128 v[208:211], v142 offset:49152
	ds_read_b128 v[212:215], v142 offset:50176
	ds_read_b128 v[216:219], v142 offset:51200
	ds_read_b128 v[220:223], v142 offset:52224
	ds_read_b128 v[224:227], v142 offset:53248
	ds_read_b128 v[228:231], v142 offset:54272
	ds_read_b128 v[232:235], v142 offset:55296
	ds_read_b128 v[236:239], v142 offset:56320
	global_load_lds_dwordx4 v[176:177], off
	s_add_i32 m0, s20, 0x2000
	s_add_u32 s82, s96, 0x580080
	v_lshl_add_u64 v[176:177], v[178:179], 0, s[24:25]
	s_addc_u32 s83, s97, 0
	s_add_i32 s20, s59, s3
	global_load_lds_dwordx4 v[176:177], off
	v_lshl_add_u64 v[176:177], s[82:83], 0, v[0:1]
	s_mov_b32 m0, s20
	s_nop 0
	global_load_lds_dwordx4 v[176:177], off
	v_lshl_add_u64 v[176:177], s[82:83], 0, v[134:135]
	s_add_i32 m0, s20, 0x2000
	s_nop 0
	global_load_lds_dwordx4 v[176:177], off
	v_lshl_add_u64 v[176:177], v[194:195], 0, s[24:25]
	s_mov_b32 m0, s86
	s_nop 0
	global_load_lds_dwordx4 v[176:177], off
	v_lshl_add_u64 v[176:177], v[240:241], 0, s[24:25]
	s_mov_b32 m0, s87
	s_nop 0
	global_load_lds_dwordx4 v[176:177], off
	s_waitcnt vmcnt(8)
	s_waitcnt lgkmcnt(0)
	s_barrier
	s_setprio 1
	s_waitcnt lgkmcnt(0)
	v_mfma_f32_16x16x32_bf16 v[62:65], v[144:147], v[208:211], v[62:65]
	v_mfma_f32_16x16x32_bf16 v[58:61], v[152:155], v[208:211], v[58:61]
	v_mfma_f32_16x16x32_bf16 v[54:57], v[144:147], v[216:219], v[54:57]
	v_mfma_f32_16x16x32_bf16 v[50:53], v[152:155], v[216:219], v[50:53]
	v_mfma_f32_16x16x32_bf16 v[38:41], v[144:147], v[224:227], v[38:41]
	v_mfma_f32_16x16x32_bf16 v[34:37], v[152:155], v[224:227], v[34:37]
	v_mfma_f32_16x16x32_bf16 v[22:25], v[144:147], v[232:235], v[22:25]
	v_mfma_f32_16x16x32_bf16 v[18:21], v[152:155], v[232:235], v[18:21]
	s_setprio 0
	s_setprio 1
	v_mfma_f32_16x16x32_bf16 v[62:65], v[148:151], v[212:215], v[62:65]
	v_mfma_f32_16x16x32_bf16 v[58:61], v[158:161], v[212:215], v[58:61]
	v_mfma_f32_16x16x32_bf16 v[54:57], v[148:151], v[220:223], v[54:57]
	v_mfma_f32_16x16x32_bf16 v[50:53], v[158:161], v[220:223], v[50:53]
	v_mfma_f32_16x16x32_bf16 v[38:41], v[148:151], v[228:231], v[38:41]
	v_mfma_f32_16x16x32_bf16 v[34:37], v[158:161], v[228:231], v[34:37]
	v_mfma_f32_16x16x32_bf16 v[22:25], v[148:151], v[236:239], v[22:25]
	v_mfma_f32_16x16x32_bf16 v[18:21], v[158:161], v[236:239], v[18:21]
	s_setprio 0
	s_setprio 1
	v_mfma_f32_16x16x32_bf16 v[46:49], v[162:165], v[208:211], v[46:49]
	v_mfma_f32_16x16x32_bf16 v[42:45], v[200:203], v[208:211], v[42:45]
	v_mfma_f32_16x16x32_bf16 v[30:33], v[162:165], v[216:219], v[30:33]
	v_mfma_f32_16x16x32_bf16 v[26:29], v[200:203], v[216:219], v[26:29]
	v_mfma_f32_16x16x32_bf16 v[14:17], v[162:165], v[224:227], v[14:17]
	v_mfma_f32_16x16x32_bf16 v[10:13], v[200:203], v[224:227], v[10:13]
	v_mfma_f32_16x16x32_bf16 v[6:9], v[162:165], v[232:235], v[6:9]
	v_mfma_f32_16x16x32_bf16 v[2:5], v[200:203], v[232:235], v[2:5]
	s_setprio 0
	s_setprio 1
	v_mfma_f32_16x16x32_bf16 v[46:49], v[196:199], v[212:215], v[46:49]
	v_mfma_f32_16x16x32_bf16 v[42:45], v[204:207], v[212:215], v[42:45]
	v_mfma_f32_16x16x32_bf16 v[30:33], v[196:199], v[220:223], v[30:33]
	v_mfma_f32_16x16x32_bf16 v[26:29], v[204:207], v[220:223], v[26:29]
	v_mfma_f32_16x16x32_bf16 v[14:17], v[196:199], v[228:231], v[14:17]
	v_mfma_f32_16x16x32_bf16 v[10:13], v[204:207], v[228:231], v[10:13]
	v_mfma_f32_16x16x32_bf16 v[6:9], v[196:199], v[236:239], v[6:9]
	v_mfma_f32_16x16x32_bf16 v[2:5], v[204:207], v[236:239], v[2:5]
	s_setprio 0
	s_barrier
	s_add_i32 s58, s58, 2
	s_add_u32 s94, s94, 0x100
	s_addc_u32 s95, s95, 0
	s_cmp_gt_u32 s58, 13
	s_cbranch_scc0 .LBB0_81
	s_waitcnt vmcnt(0)
	s_cmpk_lt_u32 s1, 0x100
	s_cbranch_scc0 .LBB0_84
	s_barrier

.LBB0_173:
	s_add_u32 s20, s18, 0xf5678080
	s_addc_u32 s40, s19, -1
	s_cmp_lg_u32 s47, 12
	s_cselect_b32 s20, s20, 0
	s_cselect_b32 s41, s40, 0
	s_add_u32 s42, s2, s20
	s_addc_u32 s43, s3, s41
	s_add_i32 s52, 0, 0x10000
	s_add_u32 s40, s8, s20
	v_add_u32_e32 v143, s52, v141
	s_addc_u32 s41, s9, s41
	s_add_i32 s20, 0, 0x14000
	ds_read_b128 v[144:147], v143
	ds_read_b128 v[148:151], v143 offset:1024
	ds_read_b128 v[152:155], v143 offset:2048
	ds_read_b128 v[158:161], v143 offset:3072
	v_add_u32_e32 v143, s20, v141
	ds_read_b128 v[162:165], v143
	ds_read_b128 v[196:199], v143 offset:1024
	ds_read_b128 v[200:203], v143 offset:2048
	ds_read_b128 v[204:207], v143 offset:3072
	v_lshl_add_u64 v[176:177], v[138:139], 0, s[18:19]
	s_add_i32 m0, s12, 0xc000
	ds_read_b128 v[208:211], v142
	ds_read_b128 v[212:215], v142 offset:1024
	ds_read_b128 v[216:219], v142 offset:2048
	ds_read_b128 v[220:223], v142 offset:3072
	ds_read_b128 v[224:227], v142 offset:4096
	ds_read_b128 v[228:231], v142 offset:5120
	ds_read_b128 v[232:235], v142 offset:6144
	ds_read_b128 v[236:239], v142 offset:7168
	global_load_lds_dwordx4 v[176:177], off
	v_lshl_add_u64 v[176:177], v[136:137], 0, s[18:19]
	s_add_i32 m0, s12, 0xe000
	s_nop 0
	global_load_lds_dwordx4 v[176:177], off
	s_waitcnt vmcnt(8)
	s_waitcnt lgkmcnt(0)
	s_barrier
	s_setprio 1
	s_waitcnt lgkmcnt(0)
	v_mfma_f32_16x16x32_bf16 v[126:129], v[144:147], v[208:211], v[126:129]
	v_mfma_f32_16x16x32_bf16 v[122:125], v[152:155], v[208:211], v[122:125]
	v_mfma_f32_16x16x32_bf16 v[118:121], v[144:147], v[216:219], v[118:121]
	v_mfma_f32_16x16x32_bf16 v[114:117], v[152:155], v[216:219], v[114:117]
	v_mfma_f32_16x16x32_bf16 v[102:105], v[144:147], v[224:227], v[102:105]
	v_mfma_f32_16x16x32_bf16 v[98:101], v[152:155], v[224:227], v[98:101]
	v_mfma_f32_16x16x32_bf16 v[86:89], v[144:147], v[232:235], v[86:89]
	v_mfma_f32_16x16x32_bf16 v[82:85], v[152:155], v[232:235], v[82:85]
	s_setprio 0
	s_setprio 1
	v_mfma_f32_16x16x32_bf16 v[126:129], v[148:151], v[212:215], v[126:129]
	v_mfma_f32_16x16x32_bf16 v[122:125], v[158:161], v[212:215], v[122:125]
	v_mfma_f32_16x16x32_bf16 v[118:121], v[148:151], v[220:223], v[118:121]
	v_mfma_f32_16x16x32_bf16 v[114:117], v[158:161], v[220:223], v[114:117]
	v_mfma_f32_16x16x32_bf16 v[102:105], v[148:151], v[228:231], v[102:105]
	v_mfma_f32_16x16x32_bf16 v[98:101], v[158:161], v[228:231], v[98:101]
	v_mfma_f32_16x16x32_bf16 v[86:89], v[148:151], v[236:239], v[86:89]
	v_mfma_f32_16x16x32_bf16 v[82:85], v[158:161], v[236:239], v[82:85]
	s_setprio 0
	s_setprio 1
	v_mfma_f32_16x16x32_bf16 v[110:113], v[162:165], v[208:211], v[110:113]
	v_mfma_f32_16x16x32_bf16 v[106:109], v[200:203], v[208:211], v[106:109]
	v_mfma_f32_16x16x32_bf16 v[94:97], v[162:165], v[216:219], v[94:97]
	v_mfma_f32_16x16x32_bf16 v[90:93], v[200:203], v[216:219], v[90:93]
	v_mfma_f32_16x16x32_bf16 v[78:81], v[162:165], v[224:227], v[78:81]
	v_mfma_f32_16x16x32_bf16 v[74:77], v[200:203], v[224:227], v[74:77]
	v_mfma_f32_16x16x32_bf16 v[70:73], v[162:165], v[232:235], v[70:73]
	v_mfma_f32_16x16x32_bf16 v[66:69], v[200:203], v[232:235], v[66:69]
	s_setprio 0
	s_setprio 1
	v_mfma_f32_16x16x32_bf16 v[110:113], v[196:199], v[212:215], v[110:113]
	v_mfma_f32_16x16x32_bf16 v[106:109], v[204:207], v[212:215], v[106:109]
	v_mfma_f32_16x16x32_bf16 v[94:97], v[196:199], v[220:223], v[94:97]
	v_mfma_f32_16x16x32_bf16 v[90:93], v[204:207], v[220:223], v[90:93]
	v_mfma_f32_16x16x32_bf16 v[78:81], v[196:199], v[228:231], v[78:81]
	v_mfma_f32_16x16x32_bf16 v[74:77], v[204:207], v[228:231], v[74:77]
	v_mfma_f32_16x16x32_bf16 v[70:73], v[196:199], v[236:239], v[70:73]
	v_mfma_f32_16x16x32_bf16 v[66:69], v[204:207], v[236:239], v[66:69]
	s_setprio 0
	s_barrier
	s_add_i32 s52, s52, s11
	v_lshl_add_u64 v[176:177], s[40:41], 0, v[0:1]
	s_mov_b32 m0, s52
	ds_read_b128 v[208:211], v142 offset:16384
	ds_read_b128 v[212:215], v142 offset:17408
	ds_read_b128 v[216:219], v142 offset:18432
	ds_read_b128 v[220:223], v142 offset:19456
	ds_read_b128 v[224:227], v142 offset:20480
	ds_read_b128 v[228:231], v142 offset:21504
	ds_read_b128 v[232:235], v142 offset:22528
	ds_read_b128 v[236:239], v142 offset:23552
	global_load_lds_dwordx4 v[176:177], off
	s_add_i32 m0, s52, 0x2000
	s_add_u32 s52, s40, 0x40000
	v_lshl_add_u64 v[178:179], s[40:41], 0, v[134:135]
	s_addc_u32 s53, s41, 0
	s_add_i32 s20, s20, s11
	global_load_lds_dwordx4 v[178:179], off
	v_lshl_add_u64 v[194:195], s[52:53], 0, v[0:1]
	s_mov_b32 m0, s20
	v_lshl_add_u64 v[240:241], s[42:43], 0, v[132:133]
	global_load_lds_dwordx4 v[194:195], off
	v_lshl_add_u64 v[194:195], s[52:53], 0, v[134:135]
	s_add_i32 m0, s20, 0x2000
	s_nop 0
	global_load_lds_dwordx4 v[194:195], off
	v_lshl_add_u64 v[194:195], s[42:43], 0, v[130:131]
	s_mov_b32 m0, s12
	s_nop 0
	global_load_lds_dwordx4 v[194:195], off
	s_mov_b32 m0, s13
	s_nop 0
	global_load_lds_dwordx4 v[240:241], off
	s_waitcnt vmcnt(8)
	s_waitcnt lgkmcnt(0)
	s_barrier
	s_setprio 1
	s_waitcnt lgkmcnt(0)
	v_mfma_f32_16x16x32_bf16 v[62:65], v[144:147], v[208:211], v[62:65]
	v_mfma_f32_16x16x32_bf16 v[58:61], v[152:155], v[208:211], v[58:61]
	v_mfma_f32_16x16x32_bf16 v[54:57], v[144:147], v[216:219], v[54:57]
	v_mfma_f32_16x16x32_bf16 v[50:53], v[152:155], v[216:219], v[50:53]
	v_mfma_f32_16x16x32_bf16 v[38:41], v[144:147], v[224:227], v[38:41]
	v_mfma_f32_16x16x32_bf16 v[34:37], v[152:155], v[224:227], v[34:37]
	v_mfma_f32_16x16x32_bf16 v[22:25], v[144:147], v[232:235], v[22:25]
	v_mfma_f32_16x16x32_bf16 v[18:21], v[152:155], v[232:235], v[18:21]
	s_setprio 0
	s_setprio 1
	v_mfma_f32_16x16x32_bf16 v[62:65], v[148:151], v[212:215], v[62:65]
	v_mfma_f32_16x16x32_bf16 v[58:61], v[158:161], v[212:215], v[58:61]
	v_mfma_f32_16x16x32_bf16 v[54:57], v[148:151], v[220:223], v[54:57]
	v_mfma_f32_16x16x32_bf16 v[50:53], v[158:161], v[220:223], v[50:53]
	v_mfma_f32_16x16x32_bf16 v[38:41], v[148:151], v[228:231], v[38:41]
	v_mfma_f32_16x16x32_bf16 v[34:37], v[158:161], v[228:231], v[34:37]
	v_mfma_f32_16x16x32_bf16 v[22:25], v[148:151], v[236:239], v[22:25]
	v_mfma_f32_16x16x32_bf16 v[18:21], v[158:161], v[236:239], v[18:21]
	s_setprio 0
	s_setprio 1
	v_mfma_f32_16x16x32_bf16 v[46:49], v[162:165], v[208:211], v[46:49]
	v_mfma_f32_16x16x32_bf16 v[42:45], v[200:203], v[208:211], v[42:45]
	v_mfma_f32_16x16x32_bf16 v[30:33], v[162:165], v[216:219], v[30:33]
	v_mfma_f32_16x16x32_bf16 v[26:29], v[200:203], v[216:219], v[26:29]
	v_mfma_f32_16x16x32_bf16 v[14:17], v[162:165], v[224:227], v[14:17]
	v_mfma_f32_16x16x32_bf16 v[10:13], v[200:203], v[224:227], v[10:13]
	v_mfma_f32_16x16x32_bf16 v[6:9], v[162:165], v[232:235], v[6:9]
	v_mfma_f32_16x16x32_bf16 v[2:5], v[200:203], v[232:235], v[2:5]
	s_setprio 0
	s_setprio 1
	v_mfma_f32_16x16x32_bf16 v[46:49], v[196:199], v[212:215], v[46:49]
	v_mfma_f32_16x16x32_bf16 v[42:45], v[204:207], v[212:215], v[42:45]
	v_mfma_f32_16x16x32_bf16 v[30:33], v[196:199], v[220:223], v[30:33]
	v_mfma_f32_16x16x32_bf16 v[26:29], v[204:207], v[220:223], v[26:29]
	v_mfma_f32_16x16x32_bf16 v[14:17], v[196:199], v[228:231], v[14:17]
	v_mfma_f32_16x16x32_bf16 v[10:13], v[204:207], v[228:231], v[10:13]
	v_mfma_f32_16x16x32_bf16 v[6:9], v[196:199], v[236:239], v[6:9]
	v_mfma_f32_16x16x32_bf16 v[2:5], v[204:207], v[236:239], v[2:5]
	s_setprio 0
	s_barrier
	s_add_i32 s20, 0, 0x18000
	v_add_u32_e32 v143, s20, v141
	s_add_i32 s52, 0, 0x1c000
	ds_read_b128 v[144:147], v143
	ds_read_b128 v[148:151], v143 offset:1024
	ds_read_b128 v[152:155], v143 offset:2048
	ds_read_b128 v[158:161], v143 offset:3072
	v_add_u32_e32 v143, s52, v141
	ds_read_b128 v[162:165], v143
	ds_read_b128 v[196:199], v143 offset:1024
	ds_read_b128 v[200:203], v143 offset:2048
	ds_read_b128 v[204:207], v143 offset:3072
	s_add_u32 s42, s42, 0x40000
	s_addc_u32 s43, s43, 0
	s_mov_b32 m0, s16
	v_lshl_add_u64 v[242:243], s[42:43], 0, v[130:131]
	ds_read_b128 v[208:211], v142 offset:32768
	ds_read_b128 v[212:215], v142 offset:33792
	ds_read_b128 v[216:219], v142 offset:34816
	ds_read_b128 v[220:223], v142 offset:35840
	ds_read_b128 v[224:227], v142 offset:36864
	ds_read_b128 v[228:231], v142 offset:37888
	ds_read_b128 v[232:235], v142 offset:38912
	ds_read_b128 v[236:239], v142 offset:39936
	global_load_lds_dwordx4 v[242:243], off
	v_lshl_add_u64 v[242:243], s[42:43], 0, v[132:133]
	s_mov_b32 m0, s17
	s_nop 0
	global_load_lds_dwordx4 v[242:243], off
	s_waitcnt vmcnt(8)
	s_waitcnt lgkmcnt(0)
	s_barrier
	s_setprio 1
	s_waitcnt lgkmcnt(0)
	v_mfma_f32_16x16x32_bf16 v[126:129], v[144:147], v[208:211], v[126:129]
	v_mfma_f32_16x16x32_bf16 v[122:125], v[152:155], v[208:211], v[122:125]
	v_mfma_f32_16x16x32_bf16 v[118:121], v[144:147], v[216:219], v[118:121]
	v_mfma_f32_16x16x32_bf16 v[114:117], v[152:155], v[216:219], v[114:117]
	v_mfma_f32_16x16x32_bf16 v[102:105], v[144:147], v[224:227], v[102:105]
	v_mfma_f32_16x16x32_bf16 v[98:101], v[152:155], v[224:227], v[98:101]
	v_mfma_f32_16x16x32_bf16 v[86:89], v[144:147], v[232:235], v[86:89]
	v_mfma_f32_16x16x32_bf16 v[82:85], v[152:155], v[232:235], v[82:85]
	s_setprio 0
	s_setprio 1
	v_mfma_f32_16x16x32_bf16 v[126:129], v[148:151], v[212:215], v[126:129]
	v_mfma_f32_16x16x32_bf16 v[122:125], v[158:161], v[212:215], v[122:125]
	v_mfma_f32_16x16x32_bf16 v[118:121], v[148:151], v[220:223], v[118:121]
	v_mfma_f32_16x16x32_bf16 v[114:117], v[158:161], v[220:223], v[114:117]
	v_mfma_f32_16x16x32_bf16 v[102:105], v[148:151], v[228:231], v[102:105]
	v_mfma_f32_16x16x32_bf16 v[98:101], v[158:161], v[228:231], v[98:101]
	v_mfma_f32_16x16x32_bf16 v[86:89], v[148:151], v[236:239], v[86:89]
	v_mfma_f32_16x16x32_bf16 v[82:85], v[158:161], v[236:239], v[82:85]
	s_setprio 0
	s_setprio 1
	v_mfma_f32_16x16x32_bf16 v[110:113], v[162:165], v[208:211], v[110:113]
	v_mfma_f32_16x16x32_bf16 v[106:109], v[200:203], v[208:211], v[106:109]
	v_mfma_f32_16x16x32_bf16 v[94:97], v[162:165], v[216:219], v[94:97]
	v_mfma_f32_16x16x32_bf16 v[90:93], v[200:203], v[216:219], v[90:93]
	v_mfma_f32_16x16x32_bf16 v[78:81], v[162:165], v[224:227], v[78:81]
	v_mfma_f32_16x16x32_bf16 v[74:77], v[200:203], v[224:227], v[74:77]
	v_mfma_f32_16x16x32_bf16 v[70:73], v[162:165], v[232:235], v[70:73]
	v_mfma_f32_16x16x32_bf16 v[66:69], v[200:203], v[232:235], v[66:69]
	s_setprio 0
	s_setprio 1
	v_mfma_f32_16x16x32_bf16 v[110:113], v[196:199], v[212:215], v[110:113]
	v_mfma_f32_16x16x32_bf16 v[106:109], v[204:207], v[212:215], v[106:109]
	v_mfma_f32_16x16x32_bf16 v[94:97], v[196:199], v[220:223], v[94:97]
	v_mfma_f32_16x16x32_bf16 v[90:93], v[204:207], v[220:223], v[90:93]
	v_mfma_f32_16x16x32_bf16 v[78:81], v[196:199], v[228:231], v[78:81]
	v_mfma_f32_16x16x32_bf16 v[74:77], v[204:207], v[228:231], v[74:77]
	v_mfma_f32_16x16x32_bf16 v[70:73], v[196:199], v[236:239], v[70:73]
	v_mfma_f32_16x16x32_bf16 v[66:69], v[204:207], v[236:239], v[66:69]
	s_setprio 0
	s_barrier
	s_add_i32 s20, s20, s11
	v_lshl_add_u64 v[176:177], v[176:177], 0, s[24:25]
	s_mov_b32 m0, s20
	ds_read_b128 v[208:211], v142 offset:49152
	ds_read_b128 v[212:215], v142 offset:50176
	ds_read_b128 v[216:219], v142 offset:51200
	ds_read_b128 v[220:223], v142 offset:52224
	ds_read_b128 v[224:227], v142 offset:53248
	ds_read_b128 v[228:231], v142 offset:54272
	ds_read_b128 v[232:235], v142 offset:55296
	ds_read_b128 v[236:239], v142 offset:56320
	global_load_lds_dwordx4 v[176:177], off
	s_add_i32 m0, s20, 0x2000
	s_add_u32 s40, s40, 0x40080
	v_lshl_add_u64 v[176:177], v[178:179], 0, s[24:25]
	s_addc_u32 s41, s41, 0
	s_add_i32 s20, s52, s11
	global_load_lds_dwordx4 v[176:177], off
	v_lshl_add_u64 v[176:177], s[40:41], 0, v[0:1]
	s_mov_b32 m0, s20
	s_nop 0
	global_load_lds_dwordx4 v[176:177], off
	v_lshl_add_u64 v[176:177], s[40:41], 0, v[134:135]
	s_add_i32 m0, s20, 0x2000
	s_nop 0
	global_load_lds_dwordx4 v[176:177], off
	v_lshl_add_u64 v[176:177], v[194:195], 0, s[24:25]
	s_mov_b32 m0, s28
	s_nop 0
	global_load_lds_dwordx4 v[176:177], off
	v_lshl_add_u64 v[176:177], v[240:241], 0, s[24:25]
	s_mov_b32 m0, s46
	s_nop 0
	global_load_lds_dwordx4 v[176:177], off
	s_waitcnt vmcnt(8)
	s_waitcnt lgkmcnt(0)
	s_barrier
	s_setprio 1
	s_waitcnt lgkmcnt(0)
	v_mfma_f32_16x16x32_bf16 v[62:65], v[144:147], v[208:211], v[62:65]
	v_mfma_f32_16x16x32_bf16 v[58:61], v[152:155], v[208:211], v[58:61]
	v_mfma_f32_16x16x32_bf16 v[54:57], v[144:147], v[216:219], v[54:57]
	v_mfma_f32_16x16x32_bf16 v[50:53], v[152:155], v[216:219], v[50:53]
	v_mfma_f32_16x16x32_bf16 v[38:41], v[144:147], v[224:227], v[38:41]
	v_mfma_f32_16x16x32_bf16 v[34:37], v[152:155], v[224:227], v[34:37]
	v_mfma_f32_16x16x32_bf16 v[22:25], v[144:147], v[232:235], v[22:25]
	v_mfma_f32_16x16x32_bf16 v[18:21], v[152:155], v[232:235], v[18:21]
	s_setprio 0
	s_setprio 1
	v_mfma_f32_16x16x32_bf16 v[62:65], v[148:151], v[212:215], v[62:65]
	v_mfma_f32_16x16x32_bf16 v[58:61], v[158:161], v[212:215], v[58:61]
	v_mfma_f32_16x16x32_bf16 v[54:57], v[148:151], v[220:223], v[54:57]
	v_mfma_f32_16x16x32_bf16 v[50:53], v[158:161], v[220:223], v[50:53]
	v_mfma_f32_16x16x32_bf16 v[38:41], v[148:151], v[228:231], v[38:41]
	v_mfma_f32_16x16x32_bf16 v[34:37], v[158:161], v[228:231], v[34:37]
	v_mfma_f32_16x16x32_bf16 v[22:25], v[148:151], v[236:239], v[22:25]
	v_mfma_f32_16x16x32_bf16 v[18:21], v[158:161], v[236:239], v[18:21]
	s_setprio 0
	s_setprio 1
	v_mfma_f32_16x16x32_bf16 v[46:49], v[162:165], v[208:211], v[46:49]
	v_mfma_f32_16x16x32_bf16 v[42:45], v[200:203], v[208:211], v[42:45]
	v_mfma_f32_16x16x32_bf16 v[30:33], v[162:165], v[216:219], v[30:33]
	v_mfma_f32_16x16x32_bf16 v[26:29], v[200:203], v[216:219], v[26:29]
	v_mfma_f32_16x16x32_bf16 v[14:17], v[162:165], v[224:227], v[14:17]
	v_mfma_f32_16x16x32_bf16 v[10:13], v[200:203], v[224:227], v[10:13]
	v_mfma_f32_16x16x32_bf16 v[6:9], v[162:165], v[232:235], v[6:9]
	v_mfma_f32_16x16x32_bf16 v[2:5], v[200:203], v[232:235], v[2:5]
	s_setprio 0
	s_setprio 1
	v_mfma_f32_16x16x32_bf16 v[46:49], v[196:199], v[212:215], v[46:49]
	v_mfma_f32_16x16x32_bf16 v[42:45], v[204:207], v[212:215], v[42:45]
	v_mfma_f32_16x16x32_bf16 v[30:33], v[196:199], v[220:223], v[30:33]
	v_mfma_f32_16x16x32_bf16 v[26:29], v[204:207], v[220:223], v[26:29]
	v_mfma_f32_16x16x32_bf16 v[14:17], v[196:199], v[228:231], v[14:17]
	v_mfma_f32_16x16x32_bf16 v[10:13], v[204:207], v[228:231], v[10:13]
	v_mfma_f32_16x16x32_bf16 v[6:9], v[196:199], v[236:239], v[6:9]
	v_mfma_f32_16x16x32_bf16 v[2:5], v[204:207], v[236:239], v[2:5]
	s_setprio 0
	s_barrier
	s_add_i32 s47, s47, 2
	s_add_u32 s18, s18, 0x100
	s_addc_u32 s19, s19, 0
	s_cmp_gt_u32 s47, 13
	s_cbranch_scc0 .LBB0_173
	s_waitcnt vmcnt(0)
	s_cmpk_lt_u32 s1, 0x100
	s_cbranch_scc0 .LBB0_169
	s_barrier
	s_branch .LBB0_169

.LBB0_336:
	s_add_u32 s20, s12, s56
	s_addc_u32 s58, s13, s57
	s_cmpk_eq_i32 s56, 0x700
	s_cselect_b64 s[6:7], -1, 0
	s_and_b64 s[10:11], s[6:7], exec
	s_cselect_b32 s62, vcc_lo, s20
	s_cselect_b32 s63, s97, s58
	s_and_b64 s[66:67], s[2:3], s[6:7]
	s_and_b64 s[6:7], s[66:67], exec
	s_cselect_b32 s10, s86, s40
	s_add_u32 s6, s16, s56
	s_addc_u32 s7, s17, s57
	s_add_u32 s11, s6, 0x3148100
	s_addc_u32 s20, s7, 0
	s_cmpk_eq_i32 s56, 0x700
	s_cselect_b64 s[6:7], -1, 0
	s_and_b64 s[6:7], s[6:7], exec
	s_cselect_b32 s58, s10, s11
	s_and_b64 s[6:7], s[66:67], exec
	s_cselect_b32 s10, s93, s41
	s_cmpk_eq_i32 s56, 0x700
	s_cselect_b64 s[84:85], -1, 0
	s_and_b64 s[6:7], s[84:85], exec
	s_cselect_b32 s59, s10, s20
	s_and_b64 s[6:7], s[66:67], exec
	s_mov_b32 s6, 0x20000
	s_cselect_b32 s66, s6, 0x40000
	s_cselect_b32 s10, 9, 10
	s_add_i32 s6, 0, 0x10000
	v_add_u32_e32 v154, s6, v143
	s_add_i32 s7, 0, 0x14000
	ds_read_b128 v[146:149], v154
	ds_read_b128 v[150:153], v154 offset:1024
	ds_read_b128 v[158:161], v154 offset:2048
	ds_read_b128 v[162:165], v154 offset:3072
	v_add_u32_e32 v154, s7, v143
	ds_read_b128 v[196:199], v154
	ds_read_b128 v[200:203], v154 offset:1024
	ds_read_b128 v[204:207], v154 offset:2048
	ds_read_b128 v[208:211], v154 offset:3072
	v_lshlrev_b32_e32 v0, s10, v134
	v_lshlrev_b32_e32 v145, s10, v136
	v_lshlrev_b32_e32 v155, s10, v138
	v_lshlrev_b32_e32 v157, s10, v139
	v_add_lshl_u32 v154, v0, v135, 1
	v_add_lshl_u32 v0, v155, v135, 1
	v_add_lshl_u32 v244, v145, v137, 1
	s_add_i32 s20, s87, 0
	v_lshl_add_u64 v[246:247], v[132:133], 0, s[56:57]
	s_add_i32 m0, s20, 0xc000
	ds_read_b128 v[212:215], v144
	ds_read_b128 v[216:219], v144 offset:1024
	ds_read_b128 v[220:223], v144 offset:2048
	ds_read_b128 v[224:227], v144 offset:3072
	ds_read_b128 v[228:231], v144 offset:4096
	ds_read_b128 v[232:235], v144 offset:5120
	ds_read_b128 v[236:239], v144 offset:6144
	ds_read_b128 v[240:243], v144 offset:7168
	global_load_lds_dwordx4 v[246:247], off
	v_lshl_add_u64 v[246:247], v[130:131], 0, s[56:57]
	s_add_i32 m0, s20, 0xe000
	s_nop 0
	global_load_lds_dwordx4 v[246:247], off
	s_waitcnt vmcnt(8)
	s_waitcnt lgkmcnt(0)
	s_barrier
	s_setprio 1
	s_waitcnt lgkmcnt(0)
	v_mfma_f32_16x16x32_bf16 v[126:129], v[146:149], v[212:215], v[126:129]
	v_mfma_f32_16x16x32_bf16 v[122:125], v[158:161], v[212:215], v[122:125]
	v_mfma_f32_16x16x32_bf16 v[110:113], v[146:149], v[220:223], v[110:113]
	v_mfma_f32_16x16x32_bf16 v[106:109], v[158:161], v[220:223], v[106:109]
	v_mfma_f32_16x16x32_bf16 v[94:97], v[146:149], v[228:231], v[94:97]
	v_mfma_f32_16x16x32_bf16 v[90:93], v[158:161], v[228:231], v[90:93]
	v_mfma_f32_16x16x32_bf16 v[78:81], v[146:149], v[236:239], v[78:81]
	v_mfma_f32_16x16x32_bf16 v[74:77], v[158:161], v[236:239], v[74:77]
	s_setprio 0
	s_setprio 1
	v_mfma_f32_16x16x32_bf16 v[126:129], v[150:153], v[216:219], v[126:129]
	v_mfma_f32_16x16x32_bf16 v[122:125], v[162:165], v[216:219], v[122:125]
	v_mfma_f32_16x16x32_bf16 v[110:113], v[150:153], v[224:227], v[110:113]
	v_mfma_f32_16x16x32_bf16 v[106:109], v[162:165], v[224:227], v[106:109]
	v_mfma_f32_16x16x32_bf16 v[94:97], v[150:153], v[232:235], v[94:97]
	v_mfma_f32_16x16x32_bf16 v[90:93], v[162:165], v[232:235], v[90:93]
	v_mfma_f32_16x16x32_bf16 v[78:81], v[150:153], v[240:243], v[78:81]
	v_mfma_f32_16x16x32_bf16 v[74:77], v[162:165], v[240:243], v[74:77]
	s_setprio 0
	s_setprio 1
	v_mfma_f32_16x16x32_bf16 v[118:121], v[196:199], v[212:215], v[118:121]
	v_mfma_f32_16x16x32_bf16 v[114:117], v[204:207], v[212:215], v[114:117]
	v_mfma_f32_16x16x32_bf16 v[102:105], v[196:199], v[220:223], v[102:105]
	v_mfma_f32_16x16x32_bf16 v[98:101], v[204:207], v[220:223], v[98:101]
	v_mfma_f32_16x16x32_bf16 v[86:89], v[196:199], v[228:231], v[86:89]
	v_mfma_f32_16x16x32_bf16 v[82:85], v[204:207], v[228:231], v[82:85]
	v_mfma_f32_16x16x32_bf16 v[70:73], v[196:199], v[236:239], v[70:73]
	v_mfma_f32_16x16x32_bf16 v[66:69], v[204:207], v[236:239], v[66:69]
	s_setprio 0
	s_setprio 1
	v_mfma_f32_16x16x32_bf16 v[118:121], v[200:203], v[216:219], v[118:121]
	v_mfma_f32_16x16x32_bf16 v[114:117], v[208:211], v[216:219], v[114:117]
	v_mfma_f32_16x16x32_bf16 v[102:105], v[200:203], v[224:227], v[102:105]
	v_mfma_f32_16x16x32_bf16 v[98:101], v[208:211], v[224:227], v[98:101]
	v_mfma_f32_16x16x32_bf16 v[86:89], v[200:203], v[232:235], v[86:89]
	v_mfma_f32_16x16x32_bf16 v[82:85], v[208:211], v[232:235], v[82:85]
	v_mfma_f32_16x16x32_bf16 v[70:73], v[200:203], v[240:243], v[70:73]
	v_mfma_f32_16x16x32_bf16 v[66:69], v[208:211], v[240:243], v[66:69]
	s_setprio 0
	s_barrier
	s_add_i32 s10, s6, s87
	s_mov_b32 m0, s10
	ds_read_b128 v[212:215], v144 offset:16384
	ds_read_b128 v[216:219], v144 offset:17408
	ds_read_b128 v[220:223], v144 offset:18432
	ds_read_b128 v[224:227], v144 offset:19456
	ds_read_b128 v[228:231], v144 offset:20480
	ds_read_b128 v[232:235], v144 offset:21504
	ds_read_b128 v[236:239], v144 offset:22528
	ds_read_b128 v[240:243], v144 offset:23552
	global_load_lds_dwordx4 v0, s[62:63]
	s_add_i32 m0, s10, 0x2000
	v_add_lshl_u32 v246, v157, v137, 1
	v_mov_b32_e32 v247, v1
	s_add_u32 s10, s62, s66
	v_lshl_add_u64 v[248:249], s[62:63], 0, v[0:1]
	v_lshl_add_u64 v[250:251], s[62:63], 0, v[246:247]
	global_load_lds_dwordx4 v246, s[62:63]
	s_addc_u32 s11, s63, 0
	s_add_i32 s62, s7, s87
	s_mov_b32 m0, s62
	v_mov_b32_e32 v155, v1
	global_load_lds_dwordx4 v0, s[10:11]
	s_add_i32 m0, s62, 0x2000
	v_mov_b32_e32 v245, v1
	global_load_lds_dwordx4 v246, s[10:11]
	s_mov_b32 m0, s20
	v_lshl_add_u64 v[194:195], s[10:11], 0, v[0:1]
	global_load_lds_dwordx4 v154, s[58:59]
	s_add_i32 m0, s20, 0x2000
	v_lshl_add_u64 v[176:177], s[10:11], 0, v[246:247]
	global_load_lds_dwordx4 v244, s[58:59]
	s_waitcnt vmcnt(8)
	s_waitcnt lgkmcnt(0)
	v_lshl_add_u64 v[246:247], s[58:59], 0, v[154:155]
	v_lshl_add_u64 v[178:179], s[58:59], 0, v[244:245]
	s_barrier
	s_setprio 1
	s_waitcnt lgkmcnt(0)
	v_mfma_f32_16x16x32_bf16 v[62:65], v[146:149], v[212:215], v[62:65]
	v_mfma_f32_16x16x32_bf16 v[58:61], v[158:161], v[212:215], v[58:61]
	v_mfma_f32_16x16x32_bf16 v[46:49], v[146:149], v[220:223], v[46:49]
	v_mfma_f32_16x16x32_bf16 v[42:45], v[158:161], v[220:223], v[42:45]
	v_mfma_f32_16x16x32_bf16 v[30:33], v[146:149], v[228:231], v[30:33]
	v_mfma_f32_16x16x32_bf16 v[26:29], v[158:161], v[228:231], v[26:29]
	v_mfma_f32_16x16x32_bf16 v[14:17], v[146:149], v[236:239], v[14:17]
	v_mfma_f32_16x16x32_bf16 v[10:13], v[158:161], v[236:239], v[10:13]
	s_setprio 0
	s_setprio 1
	v_mfma_f32_16x16x32_bf16 v[62:65], v[150:153], v[216:219], v[62:65]
	v_mfma_f32_16x16x32_bf16 v[58:61], v[162:165], v[216:219], v[58:61]
	v_mfma_f32_16x16x32_bf16 v[46:49], v[150:153], v[224:227], v[46:49]
	v_mfma_f32_16x16x32_bf16 v[42:45], v[162:165], v[224:227], v[42:45]
	v_mfma_f32_16x16x32_bf16 v[30:33], v[150:153], v[232:235], v[30:33]
	v_mfma_f32_16x16x32_bf16 v[26:29], v[162:165], v[232:235], v[26:29]
	v_mfma_f32_16x16x32_bf16 v[14:17], v[150:153], v[240:243], v[14:17]
	v_mfma_f32_16x16x32_bf16 v[10:13], v[162:165], v[240:243], v[10:13]
	s_setprio 0
	s_setprio 1
	v_mfma_f32_16x16x32_bf16 v[54:57], v[196:199], v[212:215], v[54:57]
	v_mfma_f32_16x16x32_bf16 v[50:53], v[204:207], v[212:215], v[50:53]
	v_mfma_f32_16x16x32_bf16 v[38:41], v[196:199], v[220:223], v[38:41]
	v_mfma_f32_16x16x32_bf16 v[34:37], v[204:207], v[220:223], v[34:37]
	v_mfma_f32_16x16x32_bf16 v[22:25], v[196:199], v[228:231], v[22:25]
	v_mfma_f32_16x16x32_bf16 v[18:21], v[204:207], v[228:231], v[18:21]
	v_mfma_f32_16x16x32_bf16 v[6:9], v[196:199], v[236:239], v[6:9]
	v_mfma_f32_16x16x32_bf16 v[2:5], v[204:207], v[236:239], v[2:5]
	s_setprio 0
	s_setprio 1
	v_mfma_f32_16x16x32_bf16 v[54:57], v[200:203], v[216:219], v[54:57]
	v_mfma_f32_16x16x32_bf16 v[50:53], v[208:211], v[216:219], v[50:53]
	v_mfma_f32_16x16x32_bf16 v[38:41], v[200:203], v[224:227], v[38:41]
	v_mfma_f32_16x16x32_bf16 v[34:37], v[208:211], v[224:227], v[34:37]
	v_mfma_f32_16x16x32_bf16 v[22:25], v[200:203], v[232:235], v[22:25]
	v_mfma_f32_16x16x32_bf16 v[18:21], v[208:211], v[232:235], v[18:21]
	v_mfma_f32_16x16x32_bf16 v[6:9], v[200:203], v[240:243], v[6:9]
	v_mfma_f32_16x16x32_bf16 v[2:5], v[208:211], v[240:243], v[2:5]
	s_setprio 0
	s_barrier
	s_add_i32 s10, 0, 0x18000
	v_add_u32_e32 v0, s10, v143
	s_add_i32 s11, 0, 0x1c000
	ds_read_b128 v[146:149], v0
	ds_read_b128 v[150:153], v0 offset:1024
	ds_read_b128 v[158:161], v0 offset:2048
	ds_read_b128 v[162:165], v0 offset:3072
	v_add_u32_e32 v0, s11, v143
	ds_read_b128 v[196:199], v0
	ds_read_b128 v[200:203], v0 offset:1024
	ds_read_b128 v[204:207], v0 offset:2048
	ds_read_b128 v[208:211], v0 offset:3072
	s_add_u32 s58, s58, s66
	s_addc_u32 s59, s59, 0
	s_add_i32 m0, s20, 0x4000
	ds_read_b128 v[212:215], v144 offset:32768
	ds_read_b128 v[216:219], v144 offset:33792
	ds_read_b128 v[220:223], v144 offset:34816
	ds_read_b128 v[224:227], v144 offset:35840
	ds_read_b128 v[228:231], v144 offset:36864
	ds_read_b128 v[232:235], v144 offset:37888
	ds_read_b128 v[236:239], v144 offset:38912
	ds_read_b128 v[240:243], v144 offset:39936
	global_load_lds_dwordx4 v154, s[58:59]
	s_add_i32 m0, s20, 0x6000
	s_nop 0
	global_load_lds_dwordx4 v244, s[58:59]
	s_waitcnt vmcnt(8)
	s_waitcnt lgkmcnt(0)
	s_barrier
	s_setprio 1
	s_waitcnt lgkmcnt(0)
	v_mfma_f32_16x16x32_bf16 v[126:129], v[146:149], v[212:215], v[126:129]
	v_mfma_f32_16x16x32_bf16 v[122:125], v[158:161], v[212:215], v[122:125]
	v_mfma_f32_16x16x32_bf16 v[110:113], v[146:149], v[220:223], v[110:113]
	v_mfma_f32_16x16x32_bf16 v[106:109], v[158:161], v[220:223], v[106:109]
	v_mfma_f32_16x16x32_bf16 v[94:97], v[146:149], v[228:231], v[94:97]
	v_mfma_f32_16x16x32_bf16 v[90:93], v[158:161], v[228:231], v[90:93]
	v_mfma_f32_16x16x32_bf16 v[78:81], v[146:149], v[236:239], v[78:81]
	v_mfma_f32_16x16x32_bf16 v[74:77], v[158:161], v[236:239], v[74:77]
	s_setprio 0
	s_setprio 1
	v_mfma_f32_16x16x32_bf16 v[126:129], v[150:153], v[216:219], v[126:129]
	v_mfma_f32_16x16x32_bf16 v[122:125], v[162:165], v[216:219], v[122:125]
	v_mfma_f32_16x16x32_bf16 v[110:113], v[150:153], v[224:227], v[110:113]
	v_mfma_f32_16x16x32_bf16 v[106:109], v[162:165], v[224:227], v[106:109]
	v_mfma_f32_16x16x32_bf16 v[94:97], v[150:153], v[232:235], v[94:97]
	v_mfma_f32_16x16x32_bf16 v[90:93], v[162:165], v[232:235], v[90:93]
	v_mfma_f32_16x16x32_bf16 v[78:81], v[150:153], v[240:243], v[78:81]
	v_mfma_f32_16x16x32_bf16 v[74:77], v[162:165], v[240:243], v[74:77]
	s_setprio 0
	s_setprio 1
	v_mfma_f32_16x16x32_bf16 v[118:121], v[196:199], v[212:215], v[118:121]
	v_mfma_f32_16x16x32_bf16 v[114:117], v[204:207], v[212:215], v[114:117]
	v_mfma_f32_16x16x32_bf16 v[102:105], v[196:199], v[220:223], v[102:105]
	v_mfma_f32_16x16x32_bf16 v[98:101], v[204:207], v[220:223], v[98:101]
	v_mfma_f32_16x16x32_bf16 v[86:89], v[196:199], v[228:231], v[86:89]
	v_mfma_f32_16x16x32_bf16 v[82:85], v[204:207], v[228:231], v[82:85]
	v_mfma_f32_16x16x32_bf16 v[70:73], v[196:199], v[236:239], v[70:73]
	v_mfma_f32_16x16x32_bf16 v[66:69], v[204:207], v[236:239], v[66:69]
	s_setprio 0
	s_setprio 1
	v_mfma_f32_16x16x32_bf16 v[118:121], v[200:203], v[216:219], v[118:121]
	v_mfma_f32_16x16x32_bf16 v[114:117], v[208:211], v[216:219], v[114:117]
	v_mfma_f32_16x16x32_bf16 v[102:105], v[200:203], v[224:227], v[102:105]
	v_mfma_f32_16x16x32_bf16 v[98:101], v[208:211], v[224:227], v[98:101]
	v_mfma_f32_16x16x32_bf16 v[86:89], v[200:203], v[232:235], v[86:89]
	v_mfma_f32_16x16x32_bf16 v[82:85], v[208:211], v[232:235], v[82:85]
	v_mfma_f32_16x16x32_bf16 v[70:73], v[200:203], v[240:243], v[70:73]
	v_mfma_f32_16x16x32_bf16 v[66:69], v[208:211], v[240:243], v[66:69]
	s_setprio 0
	s_barrier
	s_add_i32 s58, s10, s87
	v_lshl_add_u64 v[154:155], v[248:249], 0, s[24:25]
	s_mov_b32 m0, s58
	ds_read_b128 v[212:215], v144 offset:49152
	ds_read_b128 v[216:219], v144 offset:50176
	ds_read_b128 v[220:223], v144 offset:51200
	ds_read_b128 v[224:227], v144 offset:52224
	ds_read_b128 v[228:231], v144 offset:53248
	ds_read_b128 v[232:235], v144 offset:54272
	ds_read_b128 v[236:239], v144 offset:55296
	ds_read_b128 v[240:243], v144 offset:56320
	global_load_lds_dwordx4 v[154:155], off
	v_lshl_add_u64 v[154:155], v[250:251], 0, s[24:25]
	s_add_i32 m0, s58, 0x2000
	s_add_i32 s58, s11, s87
	global_load_lds_dwordx4 v[154:155], off
	v_lshl_add_u64 v[154:155], v[194:195], 0, s[24:25]
	s_mov_b32 m0, s58
	s_nop 0
	global_load_lds_dwordx4 v[154:155], off
	v_lshl_add_u64 v[154:155], v[176:177], 0, s[24:25]
	s_add_i32 m0, s58, 0x2000
	s_nop 0
	global_load_lds_dwordx4 v[154:155], off
	v_lshl_add_u64 v[154:155], v[246:247], 0, s[24:25]
	s_add_i32 m0, s20, 0x8000
	s_nop 0
	global_load_lds_dwordx4 v[154:155], off
	v_lshl_add_u64 v[154:155], v[178:179], 0, s[24:25]
	s_add_i32 m0, s20, 0xa000
	s_nop 0
	global_load_lds_dwordx4 v[154:155], off
	s_waitcnt vmcnt(8)
	s_waitcnt lgkmcnt(0)
	s_barrier
	s_setprio 1
	s_waitcnt lgkmcnt(0)
	v_mfma_f32_16x16x32_bf16 v[62:65], v[146:149], v[212:215], v[62:65]
	v_mfma_f32_16x16x32_bf16 v[58:61], v[158:161], v[212:215], v[58:61]
	v_mfma_f32_16x16x32_bf16 v[46:49], v[146:149], v[220:223], v[46:49]
	v_mfma_f32_16x16x32_bf16 v[42:45], v[158:161], v[220:223], v[42:45]
	v_mfma_f32_16x16x32_bf16 v[30:33], v[146:149], v[228:231], v[30:33]
	v_mfma_f32_16x16x32_bf16 v[26:29], v[158:161], v[228:231], v[26:29]
	v_mfma_f32_16x16x32_bf16 v[14:17], v[146:149], v[236:239], v[14:17]
	v_mfma_f32_16x16x32_bf16 v[10:13], v[158:161], v[236:239], v[10:13]
	s_setprio 0
	s_setprio 1
	v_mfma_f32_16x16x32_bf16 v[62:65], v[150:153], v[216:219], v[62:65]
	v_mfma_f32_16x16x32_bf16 v[58:61], v[162:165], v[216:219], v[58:61]
	v_mfma_f32_16x16x32_bf16 v[46:49], v[150:153], v[224:227], v[46:49]
	v_mfma_f32_16x16x32_bf16 v[42:45], v[162:165], v[224:227], v[42:45]
	v_mfma_f32_16x16x32_bf16 v[30:33], v[150:153], v[232:235], v[30:33]
	v_mfma_f32_16x16x32_bf16 v[26:29], v[162:165], v[232:235], v[26:29]
	v_mfma_f32_16x16x32_bf16 v[14:17], v[150:153], v[240:243], v[14:17]
	v_mfma_f32_16x16x32_bf16 v[10:13], v[162:165], v[240:243], v[10:13]
	s_setprio 0
	s_setprio 1
	v_mfma_f32_16x16x32_bf16 v[54:57], v[196:199], v[212:215], v[54:57]
	v_mfma_f32_16x16x32_bf16 v[50:53], v[204:207], v[212:215], v[50:53]
	v_mfma_f32_16x16x32_bf16 v[38:41], v[196:199], v[220:223], v[38:41]
	v_mfma_f32_16x16x32_bf16 v[34:37], v[204:207], v[220:223], v[34:37]
	v_mfma_f32_16x16x32_bf16 v[22:25], v[196:199], v[228:231], v[22:25]
	v_mfma_f32_16x16x32_bf16 v[18:21], v[204:207], v[228:231], v[18:21]
	v_mfma_f32_16x16x32_bf16 v[6:9], v[196:199], v[236:239], v[6:9]
	v_mfma_f32_16x16x32_bf16 v[2:5], v[204:207], v[236:239], v[2:5]
	s_setprio 0
	s_setprio 1
	v_mfma_f32_16x16x32_bf16 v[54:57], v[200:203], v[216:219], v[54:57]
	v_mfma_f32_16x16x32_bf16 v[50:53], v[208:211], v[216:219], v[50:53]
	v_mfma_f32_16x16x32_bf16 v[38:41], v[200:203], v[224:227], v[38:41]
	v_mfma_f32_16x16x32_bf16 v[34:37], v[208:211], v[224:227], v[34:37]
	v_mfma_f32_16x16x32_bf16 v[22:25], v[200:203], v[232:235], v[22:25]
	v_mfma_f32_16x16x32_bf16 v[18:21], v[208:211], v[232:235], v[18:21]
	v_mfma_f32_16x16x32_bf16 v[6:9], v[200:203], v[240:243], v[6:9]
	v_mfma_f32_16x16x32_bf16 v[2:5], v[208:211], v[240:243], v[2:5]
	s_setprio 0
	s_barrier
	s_add_i32 vcc_hi, vcc_hi, 2
	s_add_u32 s56, s56, 0x100
	s_addc_u32 s57, s57, 0
	s_cmp_lt_u32 vcc_hi, 14
	s_cbranch_scc1 .LBB0_336
	v_mul_f32_e32 v0, 0xbfb8aa3b, v126
	v_exp_f32_e32 v0, v0
	v_mul_f32_e32 v126, 0xbfb8aa3b, v127
	v_exp_f32_e32 v132, v126
	v_mul_f32_e32 v128, 0xbfb8aa3b, v128
	v_exp_f32_e32 v128, v128
	v_lshl_add_u32 v130, s96, 16, v142
	v_mul_f32_e32 v129, 0xbfb8aa3b, v129
	v_add_f32_e32 v0, 1.0, v0
	v_ashrrev_i32_e32 v131, 31, v130
	v_exp_f32_e32 v129, v129
	v_rcp_f32_e32 v0, v0
	v_lshl_add_u64 v[126:127], s[0:1], 0, v[130:131]
	v_add_f32_e32 v130, 1.0, v132
	v_rcp_f32_e32 v130, v130
	v_add_f32_e32 v128, 1.0, v128
	v_rcp_f32_e32 v128, v128
	v_add_f32_e32 v129, 1.0, v129
	v_fma_f32 v0, v0, s21, 0.5
	v_rcp_f32_e32 v129, v129
	v_max_f32_e32 v0, 1.0, v0
	v_fma_f32 v130, v130, s21, 0.5
	v_mul_f32_e32 v122, 0xbfb8aa3b, v122
	v_cvt_pk_u8_f32 v0, v0, 0, 0
	v_max_f32_e32 v130, 1.0, v130
	v_fma_f32 v128, v128, s21, 0.5
	v_exp_f32_e32 v122, v122
	v_mul_f32_e32 v123, 0xbfb8aa3b, v123
	v_cvt_pk_u8_f32 v0, v130, 1, v0
	v_max_f32_e32 v128, 1.0, v128
	v_exp_f32_e32 v123, v123
	v_cvt_pk_u8_f32 v0, v128, 2, v0
	v_fma_f32 v128, v129, s21, 0.5
	v_max_f32_e32 v128, 1.0, v128
	v_cvt_pk_u8_f32 v0, v128, 3, v0
	v_add_f32_e32 v122, 1.0, v122
	v_rcp_f32_e32 v122, v122
	global_store_dword v[126:127], v0, off
	v_add_f32_e32 v0, 1.0, v123
	v_rcp_f32_e32 v0, v0
	v_mul_f32_e32 v123, 0xbfb8aa3b, v124
	v_exp_f32_e32 v123, v123
	v_mul_f32_e32 v124, 0xbfb8aa3b, v125
	v_exp_f32_e32 v124, v124
	v_fma_f32 v122, v122, s21, 0.5
	v_max_f32_e32 v122, 1.0, v122
	v_fma_f32 v0, v0, s21, 0.5
	v_cvt_pk_u8_f32 v122, v122, 0, 0
	v_max_f32_e32 v0, 1.0, v0
	v_add_f32_e32 v123, 1.0, v123
	v_rcp_f32_e32 v123, v123
	v_cvt_pk_u8_f32 v0, v0, 1, v122
	v_add_f32_e32 v122, 1.0, v124
	v_rcp_f32_e32 v122, v122
	v_mul_f32_e32 v118, 0xbfb8aa3b, v118
	v_exp_f32_e32 v118, v118
	v_mul_f32_e32 v119, 0xbfb8aa3b, v119
	v_fma_f32 v123, v123, s21, 0.5
	v_exp_f32_e32 v119, v119
	v_max_f32_e32 v123, 1.0, v123
	v_fma_f32 v122, v122, s21, 0.5
	v_cvt_pk_u8_f32 v0, v123, 2, v0
	v_max_f32_e32 v122, 1.0, v122
	v_cvt_pk_u8_f32 v0, v122, 3, v0
	v_add_f32_e32 v118, 1.0, v118
	v_rcp_f32_e32 v118, v118
	global_store_dword v[126:127], v0, off offset:256
	v_add_f32_e32 v0, 1.0, v119
	v_rcp_f32_e32 v0, v0
	v_mul_f32_e32 v119, 0xbfb8aa3b, v120
	v_exp_f32_e32 v119, v119
	v_mul_f32_e32 v120, 0xbfb8aa3b, v121
	v_exp_f32_e32 v120, v120
	v_fma_f32 v118, v118, s21, 0.5
	v_max_f32_e32 v118, 1.0, v118
	v_fma_f32 v0, v0, s21, 0.5
	v_cvt_pk_u8_f32 v118, v118, 0, 0
	v_max_f32_e32 v0, 1.0, v0
	v_add_f32_e32 v119, 1.0, v119
	v_rcp_f32_e32 v119, v119
	v_cvt_pk_u8_f32 v0, v0, 1, v118
	v_add_f32_e32 v118, 1.0, v120
	v_rcp_f32_e32 v118, v118
	v_mul_f32_e32 v114, 0xbfb8aa3b, v114
	v_exp_f32_e32 v114, v114
	v_mul_f32_e32 v115, 0xbfb8aa3b, v115
	v_fma_f32 v119, v119, s21, 0.5
	v_exp_f32_e32 v115, v115
	v_max_f32_e32 v119, 1.0, v119
	v_fma_f32 v118, v118, s21, 0.5
	v_cvt_pk_u8_f32 v0, v119, 2, v0
	v_max_f32_e32 v118, 1.0, v118
	v_cvt_pk_u8_f32 v0, v118, 3, v0
	v_add_f32_e32 v114, 1.0, v114
	v_rcp_f32_e32 v114, v114
	global_store_dword v[126:127], v0, off offset:512
	v_add_f32_e32 v0, 1.0, v115
	v_rcp_f32_e32 v0, v0
	v_mul_f32_e32 v115, 0xbfb8aa3b, v116
	v_exp_f32_e32 v115, v115
	v_mul_f32_e32 v116, 0xbfb8aa3b, v117
	v_exp_f32_e32 v116, v116
	v_fma_f32 v114, v114, s21, 0.5
	v_max_f32_e32 v114, 1.0, v114
	v_fma_f32 v0, v0, s21, 0.5
	v_cvt_pk_u8_f32 v114, v114, 0, 0
	v_max_f32_e32 v0, 1.0, v0
	v_add_f32_e32 v115, 1.0, v115
	v_rcp_f32_e32 v115, v115
	v_cvt_pk_u8_f32 v0, v0, 1, v114
	v_add_f32_e32 v114, 1.0, v116
	v_rcp_f32_e32 v114, v114
	v_mul_f32_e32 v110, 0xbfb8aa3b, v110
	v_exp_f32_e32 v110, v110
	v_mul_f32_e32 v111, 0xbfb8aa3b, v111
	v_fma_f32 v115, v115, s21, 0.5
	v_exp_f32_e32 v111, v111
	v_max_f32_e32 v115, 1.0, v115
	v_fma_f32 v114, v114, s21, 0.5
	v_cvt_pk_u8_f32 v0, v115, 2, v0
	v_max_f32_e32 v114, 1.0, v114
	v_cvt_pk_u8_f32 v0, v114, 3, v0
	v_add_f32_e32 v110, 1.0, v110
	v_rcp_f32_e32 v110, v110
	global_store_dword v[126:127], v0, off offset:768
	v_add_f32_e32 v0, 1.0, v111
	v_rcp_f32_e32 v0, v0
	v_mul_f32_e32 v111, 0xbfb8aa3b, v112
	v_exp_f32_e32 v111, v111
	v_mul_f32_e32 v112, 0xbfb8aa3b, v113
	v_exp_f32_e32 v112, v112
	v_fma_f32 v110, v110, s21, 0.5
	v_max_f32_e32 v110, 1.0, v110
	v_fma_f32 v0, v0, s21, 0.5
	v_cvt_pk_u8_f32 v110, v110, 0, 0
	v_max_f32_e32 v0, 1.0, v0
	v_add_f32_e32 v111, 1.0, v111
	v_rcp_f32_e32 v111, v111
	v_cvt_pk_u8_f32 v0, v0, 1, v110
	v_add_f32_e32 v110, 1.0, v112
	v_rcp_f32_e32 v110, v110
	v_mul_f32_e32 v106, 0xbfb8aa3b, v106
	v_exp_f32_e32 v106, v106
	v_mul_f32_e32 v107, 0xbfb8aa3b, v107
	v_fma_f32 v111, v111, s21, 0.5
	v_exp_f32_e32 v107, v107
	v_max_f32_e32 v111, 1.0, v111
	v_fma_f32 v110, v110, s21, 0.5
	v_cvt_pk_u8_f32 v0, v111, 2, v0
	v_max_f32_e32 v110, 1.0, v110
	v_cvt_pk_u8_f32 v0, v110, 3, v0
	v_add_f32_e32 v106, 1.0, v106
	v_rcp_f32_e32 v106, v106
	global_store_dword v[126:127], v0, off offset:1024
	v_add_f32_e32 v0, 1.0, v107
	v_rcp_f32_e32 v0, v0
	v_mul_f32_e32 v107, 0xbfb8aa3b, v108
	v_exp_f32_e32 v107, v107
	v_mul_f32_e32 v108, 0xbfb8aa3b, v109
	v_exp_f32_e32 v108, v108
	v_fma_f32 v106, v106, s21, 0.5
	v_max_f32_e32 v106, 1.0, v106
	v_fma_f32 v0, v0, s21, 0.5
	v_cvt_pk_u8_f32 v106, v106, 0, 0
	v_max_f32_e32 v0, 1.0, v0
	v_add_f32_e32 v107, 1.0, v107
	v_rcp_f32_e32 v107, v107
	v_cvt_pk_u8_f32 v0, v0, 1, v106
	v_add_f32_e32 v106, 1.0, v108
	v_rcp_f32_e32 v106, v106
	v_mul_f32_e32 v102, 0xbfb8aa3b, v102
	v_exp_f32_e32 v102, v102
	v_mul_f32_e32 v103, 0xbfb8aa3b, v103
	v_fma_f32 v107, v107, s21, 0.5
	v_exp_f32_e32 v103, v103
	v_max_f32_e32 v107, 1.0, v107
	v_fma_f32 v106, v106, s21, 0.5
	v_cvt_pk_u8_f32 v0, v107, 2, v0
	v_max_f32_e32 v106, 1.0, v106
	v_cvt_pk_u8_f32 v0, v106, 3, v0
	v_add_f32_e32 v102, 1.0, v102
	v_rcp_f32_e32 v102, v102
	global_store_dword v[126:127], v0, off offset:1280
	v_add_f32_e32 v0, 1.0, v103
	v_rcp_f32_e32 v0, v0
	v_mul_f32_e32 v103, 0xbfb8aa3b, v104
	v_exp_f32_e32 v103, v103
	v_mul_f32_e32 v104, 0xbfb8aa3b, v105
	v_exp_f32_e32 v104, v104
	v_fma_f32 v102, v102, s21, 0.5
	v_max_f32_e32 v102, 1.0, v102
	v_fma_f32 v0, v0, s21, 0.5
	v_cvt_pk_u8_f32 v102, v102, 0, 0
	v_max_f32_e32 v0, 1.0, v0
	v_add_f32_e32 v103, 1.0, v103
	v_rcp_f32_e32 v103, v103
	v_cvt_pk_u8_f32 v0, v0, 1, v102
	v_add_f32_e32 v102, 1.0, v104
	v_rcp_f32_e32 v102, v102
	v_mul_f32_e32 v98, 0xbfb8aa3b, v98
	v_exp_f32_e32 v98, v98
	v_mul_f32_e32 v99, 0xbfb8aa3b, v99
	v_fma_f32 v103, v103, s21, 0.5
	v_exp_f32_e32 v99, v99
	v_max_f32_e32 v103, 1.0, v103
	v_fma_f32 v102, v102, s21, 0.5
	v_cvt_pk_u8_f32 v0, v103, 2, v0
	v_max_f32_e32 v102, 1.0, v102
	v_cvt_pk_u8_f32 v0, v102, 3, v0
	v_add_f32_e32 v98, 1.0, v98
	v_rcp_f32_e32 v98, v98
	global_store_dword v[126:127], v0, off offset:1536
	v_add_f32_e32 v0, 1.0, v99
	v_rcp_f32_e32 v0, v0
	v_mul_f32_e32 v99, 0xbfb8aa3b, v100
	v_exp_f32_e32 v99, v99
	v_mul_f32_e32 v100, 0xbfb8aa3b, v101
	v_exp_f32_e32 v100, v100
	v_fma_f32 v98, v98, s21, 0.5
	v_max_f32_e32 v98, 1.0, v98
	v_fma_f32 v0, v0, s21, 0.5
	v_cvt_pk_u8_f32 v98, v98, 0, 0
	v_max_f32_e32 v0, 1.0, v0
	v_add_f32_e32 v99, 1.0, v99
	v_rcp_f32_e32 v99, v99
	v_cvt_pk_u8_f32 v0, v0, 1, v98
	v_add_f32_e32 v98, 1.0, v100
	v_rcp_f32_e32 v98, v98
	v_mul_f32_e32 v94, 0xbfb8aa3b, v94
	v_exp_f32_e32 v94, v94
	v_mul_f32_e32 v95, 0xbfb8aa3b, v95
	v_fma_f32 v99, v99, s21, 0.5
	v_exp_f32_e32 v95, v95
	v_max_f32_e32 v99, 1.0, v99
	v_fma_f32 v98, v98, s21, 0.5
	v_cvt_pk_u8_f32 v0, v99, 2, v0
	v_max_f32_e32 v98, 1.0, v98
	v_cvt_pk_u8_f32 v0, v98, 3, v0
	v_add_f32_e32 v94, 1.0, v94
	v_rcp_f32_e32 v94, v94
	global_store_dword v[126:127], v0, off offset:1792
	v_add_f32_e32 v0, 1.0, v95
	v_rcp_f32_e32 v0, v0
	v_mul_f32_e32 v95, 0xbfb8aa3b, v96
	v_exp_f32_e32 v95, v95
	v_mul_f32_e32 v96, 0xbfb8aa3b, v97
	v_exp_f32_e32 v96, v96
	v_fma_f32 v94, v94, s21, 0.5
	v_max_f32_e32 v94, 1.0, v94
	v_fma_f32 v0, v0, s21, 0.5
	v_cvt_pk_u8_f32 v94, v94, 0, 0
	v_max_f32_e32 v0, 1.0, v0
	v_add_f32_e32 v95, 1.0, v95
	v_rcp_f32_e32 v95, v95
	v_cvt_pk_u8_f32 v0, v0, 1, v94
	v_add_f32_e32 v94, 1.0, v96
	v_rcp_f32_e32 v94, v94
	v_mul_f32_e32 v90, 0xbfb8aa3b, v90
	v_exp_f32_e32 v90, v90
	v_mul_f32_e32 v91, 0xbfb8aa3b, v91
	v_fma_f32 v95, v95, s21, 0.5
	v_exp_f32_e32 v91, v91
	v_max_f32_e32 v95, 1.0, v95
	v_fma_f32 v94, v94, s21, 0.5
	v_cvt_pk_u8_f32 v0, v95, 2, v0
	v_max_f32_e32 v94, 1.0, v94
	v_cvt_pk_u8_f32 v0, v94, 3, v0
	v_add_f32_e32 v90, 1.0, v90
	v_rcp_f32_e32 v90, v90
	global_store_dword v[126:127], v0, off offset:2048
	v_add_f32_e32 v0, 1.0, v91
	v_rcp_f32_e32 v0, v0
	v_mul_f32_e32 v91, 0xbfb8aa3b, v92
	v_exp_f32_e32 v91, v91
	v_mul_f32_e32 v92, 0xbfb8aa3b, v93
	v_exp_f32_e32 v92, v92
	v_fma_f32 v90, v90, s21, 0.5
	v_max_f32_e32 v90, 1.0, v90
	v_fma_f32 v0, v0, s21, 0.5
	v_cvt_pk_u8_f32 v90, v90, 0, 0
	v_max_f32_e32 v0, 1.0, v0
	v_add_f32_e32 v91, 1.0, v91
	v_rcp_f32_e32 v91, v91
	v_cvt_pk_u8_f32 v0, v0, 1, v90
	v_add_f32_e32 v90, 1.0, v92
	v_rcp_f32_e32 v90, v90
	v_mul_f32_e32 v86, 0xbfb8aa3b, v86
	v_exp_f32_e32 v86, v86
	v_mul_f32_e32 v87, 0xbfb8aa3b, v87
	v_fma_f32 v91, v91, s21, 0.5
	v_exp_f32_e32 v87, v87
	v_max_f32_e32 v91, 1.0, v91
	v_fma_f32 v90, v90, s21, 0.5
	v_cvt_pk_u8_f32 v0, v91, 2, v0
	v_max_f32_e32 v90, 1.0, v90
	v_cvt_pk_u8_f32 v0, v90, 3, v0
	v_add_f32_e32 v86, 1.0, v86
	v_rcp_f32_e32 v86, v86
	global_store_dword v[126:127], v0, off offset:2304
	v_add_f32_e32 v0, 1.0, v87
	v_rcp_f32_e32 v0, v0
	v_mul_f32_e32 v87, 0xbfb8aa3b, v88
	v_exp_f32_e32 v87, v87
	v_mul_f32_e32 v88, 0xbfb8aa3b, v89
	v_exp_f32_e32 v88, v88
	v_fma_f32 v86, v86, s21, 0.5
	v_max_f32_e32 v86, 1.0, v86
	v_fma_f32 v0, v0, s21, 0.5
	v_cvt_pk_u8_f32 v86, v86, 0, 0
	v_max_f32_e32 v0, 1.0, v0
	v_add_f32_e32 v87, 1.0, v87
	v_rcp_f32_e32 v87, v87
	v_cvt_pk_u8_f32 v0, v0, 1, v86
	v_add_f32_e32 v86, 1.0, v88
	v_rcp_f32_e32 v86, v86
	v_mul_f32_e32 v82, 0xbfb8aa3b, v82
	v_exp_f32_e32 v82, v82
	v_mul_f32_e32 v83, 0xbfb8aa3b, v83
	v_fma_f32 v87, v87, s21, 0.5
	v_exp_f32_e32 v83, v83
	v_max_f32_e32 v87, 1.0, v87
	v_fma_f32 v86, v86, s21, 0.5
	v_cvt_pk_u8_f32 v0, v87, 2, v0
	v_max_f32_e32 v86, 1.0, v86
	v_cvt_pk_u8_f32 v0, v86, 3, v0
	v_add_f32_e32 v82, 1.0, v82
	v_rcp_f32_e32 v82, v82
	global_store_dword v[126:127], v0, off offset:2560
	v_add_f32_e32 v0, 1.0, v83
	v_rcp_f32_e32 v0, v0
	v_mul_f32_e32 v83, 0xbfb8aa3b, v84
	v_exp_f32_e32 v83, v83
	v_mul_f32_e32 v84, 0xbfb8aa3b, v85
	v_exp_f32_e32 v84, v84
	v_fma_f32 v82, v82, s21, 0.5
	v_max_f32_e32 v82, 1.0, v82
	v_fma_f32 v0, v0, s21, 0.5
	v_cvt_pk_u8_f32 v82, v82, 0, 0
	v_max_f32_e32 v0, 1.0, v0
	v_add_f32_e32 v83, 1.0, v83
	v_rcp_f32_e32 v83, v83
	v_cvt_pk_u8_f32 v0, v0, 1, v82
	v_add_f32_e32 v82, 1.0, v84
	v_rcp_f32_e32 v82, v82
	v_mul_f32_e32 v78, 0xbfb8aa3b, v78
	v_exp_f32_e32 v78, v78
	v_mul_f32_e32 v79, 0xbfb8aa3b, v79
	v_fma_f32 v83, v83, s21, 0.5
	v_exp_f32_e32 v79, v79
	v_max_f32_e32 v83, 1.0, v83
	v_fma_f32 v82, v82, s21, 0.5
	v_cvt_pk_u8_f32 v0, v83, 2, v0
	v_max_f32_e32 v82, 1.0, v82
	v_cvt_pk_u8_f32 v0, v82, 3, v0
	v_add_f32_e32 v78, 1.0, v78
	v_rcp_f32_e32 v78, v78
	global_store_dword v[126:127], v0, off offset:2816
	v_add_f32_e32 v0, 1.0, v79
	v_rcp_f32_e32 v0, v0
	v_mul_f32_e32 v79, 0xbfb8aa3b, v80
	v_exp_f32_e32 v79, v79
	v_mul_f32_e32 v80, 0xbfb8aa3b, v81
	v_exp_f32_e32 v80, v80
	v_fma_f32 v78, v78, s21, 0.5
	v_max_f32_e32 v78, 1.0, v78
	v_fma_f32 v0, v0, s21, 0.5
	v_cvt_pk_u8_f32 v78, v78, 0, 0
	v_max_f32_e32 v0, 1.0, v0
	v_add_f32_e32 v79, 1.0, v79
	v_rcp_f32_e32 v79, v79
	v_cvt_pk_u8_f32 v0, v0, 1, v78
	v_add_f32_e32 v78, 1.0, v80
	v_rcp_f32_e32 v78, v78
	v_mul_f32_e32 v74, 0xbfb8aa3b, v74
	v_exp_f32_e32 v74, v74
	v_mul_f32_e32 v75, 0xbfb8aa3b, v75
	v_fma_f32 v79, v79, s21, 0.5
	v_exp_f32_e32 v75, v75
	v_max_f32_e32 v79, 1.0, v79
	v_fma_f32 v78, v78, s21, 0.5
	v_cvt_pk_u8_f32 v0, v79, 2, v0
	v_max_f32_e32 v78, 1.0, v78
	v_cvt_pk_u8_f32 v0, v78, 3, v0
	v_add_f32_e32 v74, 1.0, v74
	v_rcp_f32_e32 v74, v74
	global_store_dword v[126:127], v0, off offset:3072
	v_add_f32_e32 v0, 1.0, v75
	v_rcp_f32_e32 v0, v0
	v_mul_f32_e32 v75, 0xbfb8aa3b, v76
	v_exp_f32_e32 v75, v75
	v_mul_f32_e32 v76, 0xbfb8aa3b, v77
	v_exp_f32_e32 v76, v76
	v_fma_f32 v74, v74, s21, 0.5
	v_max_f32_e32 v74, 1.0, v74
	v_fma_f32 v0, v0, s21, 0.5
	v_cvt_pk_u8_f32 v74, v74, 0, 0
	v_max_f32_e32 v0, 1.0, v0
	v_add_f32_e32 v75, 1.0, v75
	v_rcp_f32_e32 v75, v75
	v_cvt_pk_u8_f32 v0, v0, 1, v74
	v_add_f32_e32 v74, 1.0, v76
	v_rcp_f32_e32 v74, v74
	v_mul_f32_e32 v70, 0xbfb8aa3b, v70
	v_exp_f32_e32 v70, v70
	v_mul_f32_e32 v71, 0xbfb8aa3b, v71
	v_fma_f32 v75, v75, s21, 0.5
	v_exp_f32_e32 v71, v71
	v_max_f32_e32 v75, 1.0, v75
	v_fma_f32 v74, v74, s21, 0.5
	v_cvt_pk_u8_f32 v0, v75, 2, v0
	v_max_f32_e32 v74, 1.0, v74
	v_cvt_pk_u8_f32 v0, v74, 3, v0
	v_add_f32_e32 v70, 1.0, v70
	v_rcp_f32_e32 v70, v70
	global_store_dword v[126:127], v0, off offset:3328
	v_add_f32_e32 v0, 1.0, v71
	v_rcp_f32_e32 v0, v0
	v_mul_f32_e32 v71, 0xbfb8aa3b, v72
	v_exp_f32_e32 v71, v71
	v_mul_f32_e32 v72, 0xbfb8aa3b, v73
	v_exp_f32_e32 v72, v72
	v_fma_f32 v70, v70, s21, 0.5
	v_max_f32_e32 v70, 1.0, v70
	v_fma_f32 v0, v0, s21, 0.5
	v_cvt_pk_u8_f32 v70, v70, 0, 0
	v_max_f32_e32 v0, 1.0, v0
	v_add_f32_e32 v71, 1.0, v71
	v_rcp_f32_e32 v71, v71
	v_cvt_pk_u8_f32 v0, v0, 1, v70
	v_add_f32_e32 v70, 1.0, v72
	v_rcp_f32_e32 v70, v70
	v_mul_f32_e32 v66, 0xbfb8aa3b, v66
	v_exp_f32_e32 v66, v66
	v_mul_f32_e32 v67, 0xbfb8aa3b, v67
	v_fma_f32 v71, v71, s21, 0.5
	v_exp_f32_e32 v67, v67
	v_max_f32_e32 v71, 1.0, v71
	v_fma_f32 v70, v70, s21, 0.5
	v_cvt_pk_u8_f32 v0, v71, 2, v0
	v_max_f32_e32 v70, 1.0, v70
	v_cvt_pk_u8_f32 v0, v70, 3, v0
	v_add_f32_e32 v66, 1.0, v66
	v_rcp_f32_e32 v66, v66
	global_store_dword v[126:127], v0, off offset:3584
	v_add_f32_e32 v0, 1.0, v67
	v_rcp_f32_e32 v0, v0
	v_mul_f32_e32 v67, 0xbfb8aa3b, v68
	v_exp_f32_e32 v67, v67
	v_mul_f32_e32 v68, 0xbfb8aa3b, v69
	v_exp_f32_e32 v68, v68
	v_fma_f32 v66, v66, s21, 0.5
	v_max_f32_e32 v66, 1.0, v66
	v_fma_f32 v0, v0, s21, 0.5
	v_cvt_pk_u8_f32 v66, v66, 0, 0
	v_max_f32_e32 v0, 1.0, v0
	v_add_f32_e32 v67, 1.0, v67
	v_rcp_f32_e32 v67, v67
	v_cvt_pk_u8_f32 v0, v0, 1, v66
	v_add_f32_e32 v66, 1.0, v68
	v_rcp_f32_e32 v66, v66
	v_mul_f32_e32 v62, 0xbfb8aa3b, v62
	v_exp_f32_e32 v62, v62
	v_mul_f32_e32 v63, 0xbfb8aa3b, v63
	v_fma_f32 v67, v67, s21, 0.5
	v_exp_f32_e32 v63, v63
	v_max_f32_e32 v67, 1.0, v67
	v_fma_f32 v66, v66, s21, 0.5
	v_cvt_pk_u8_f32 v0, v67, 2, v0
	v_max_f32_e32 v66, 1.0, v66
	v_cvt_pk_u8_f32 v0, v66, 3, v0
	v_add_f32_e32 v62, 1.0, v62
	v_rcp_f32_e32 v62, v62
	global_store_dword v[126:127], v0, off offset:3840
	v_add_f32_e32 v0, 1.0, v63
	v_rcp_f32_e32 v0, v0
	v_mul_f32_e32 v63, 0xbfb8aa3b, v64
	v_exp_f32_e32 v63, v63
	v_mul_f32_e32 v64, 0xbfb8aa3b, v65
	v_exp_f32_e32 v64, v64
	v_fma_f32 v62, v62, s21, 0.5
	v_max_f32_e32 v62, 1.0, v62
	v_fma_f32 v0, v0, s21, 0.5
	v_cvt_pk_u8_f32 v62, v62, 0, 0
	v_max_f32_e32 v0, 1.0, v0
	v_add_f32_e32 v63, 1.0, v63
	v_rcp_f32_e32 v63, v63
	v_cvt_pk_u8_f32 v0, v0, 1, v62
	v_add_f32_e32 v62, 1.0, v64
	v_rcp_f32_e32 v62, v62
	v_mul_f32_e32 v58, 0xbfb8aa3b, v58
	v_fma_f32 v63, v63, s21, 0.5
	v_exp_f32_e32 v58, v58
	v_mul_f32_e32 v59, 0xbfb8aa3b, v59
	v_max_f32_e32 v63, 1.0, v63
	v_fma_f32 v62, v62, s21, 0.5
	v_exp_f32_e32 v59, v59
	v_cvt_pk_u8_f32 v0, v63, 2, v0
	v_max_f32_e32 v62, 1.0, v62
	v_cvt_pk_u8_f32 v0, v62, 3, v0
	v_add_co_u32_e32 v62, vcc, s77, v126
	v_add_f32_e32 v58, 1.0, v58
	s_nop 0
	v_addc_co_u32_e32 v63, vcc, 0, v127, vcc
	v_rcp_f32_e32 v58, v58
	global_store_dword v[62:63], v0, off
	v_add_f32_e32 v0, 1.0, v59
	v_rcp_f32_e32 v0, v0
	v_mul_f32_e32 v59, 0xbfb8aa3b, v60
	v_exp_f32_e32 v59, v59
	v_mul_f32_e32 v60, 0xbfb8aa3b, v61
	v_exp_f32_e32 v60, v60
	v_fma_f32 v58, v58, s21, 0.5
	v_max_f32_e32 v58, 1.0, v58
	v_fma_f32 v0, v0, s21, 0.5
	v_cvt_pk_u8_f32 v58, v58, 0, 0
	v_max_f32_e32 v0, 1.0, v0
	v_add_f32_e32 v59, 1.0, v59
	v_rcp_f32_e32 v59, v59
	v_cvt_pk_u8_f32 v0, v0, 1, v58
	v_add_f32_e32 v58, 1.0, v60
	v_rcp_f32_e32 v58, v58
	v_mul_f32_e32 v54, 0xbfb8aa3b, v54
	v_exp_f32_e32 v54, v54
	v_mul_f32_e32 v55, 0xbfb8aa3b, v55
	v_fma_f32 v59, v59, s21, 0.5
	v_exp_f32_e32 v55, v55
	v_max_f32_e32 v59, 1.0, v59
	v_fma_f32 v58, v58, s21, 0.5
	v_cvt_pk_u8_f32 v0, v59, 2, v0
	v_max_f32_e32 v58, 1.0, v58
	v_cvt_pk_u8_f32 v0, v58, 3, v0
	v_add_f32_e32 v54, 1.0, v54
	v_rcp_f32_e32 v54, v54
	global_store_dword v[62:63], v0, off offset:256
	v_add_f32_e32 v0, 1.0, v55
	v_rcp_f32_e32 v0, v0
	v_mul_f32_e32 v55, 0xbfb8aa3b, v56
	v_exp_f32_e32 v55, v55
	v_mul_f32_e32 v56, 0xbfb8aa3b, v57
	v_exp_f32_e32 v56, v56
	v_fma_f32 v54, v54, s21, 0.5
	v_max_f32_e32 v54, 1.0, v54
	v_fma_f32 v0, v0, s21, 0.5
	v_cvt_pk_u8_f32 v54, v54, 0, 0
	v_max_f32_e32 v0, 1.0, v0
	v_add_f32_e32 v55, 1.0, v55
	v_rcp_f32_e32 v55, v55
	v_cvt_pk_u8_f32 v0, v0, 1, v54
	v_add_f32_e32 v54, 1.0, v56
	v_rcp_f32_e32 v54, v54
	v_mul_f32_e32 v50, 0xbfb8aa3b, v50
	v_exp_f32_e32 v50, v50
	v_mul_f32_e32 v51, 0xbfb8aa3b, v51
	v_fma_f32 v55, v55, s21, 0.5
	v_exp_f32_e32 v51, v51
	v_max_f32_e32 v55, 1.0, v55
	v_fma_f32 v54, v54, s21, 0.5
	v_cvt_pk_u8_f32 v0, v55, 2, v0
	v_max_f32_e32 v54, 1.0, v54
	v_cvt_pk_u8_f32 v0, v54, 3, v0
	v_add_f32_e32 v50, 1.0, v50
	v_rcp_f32_e32 v50, v50
	global_store_dword v[62:63], v0, off offset:512
	v_add_f32_e32 v0, 1.0, v51
	v_rcp_f32_e32 v0, v0
	v_mul_f32_e32 v51, 0xbfb8aa3b, v52
	v_exp_f32_e32 v51, v51
	v_mul_f32_e32 v52, 0xbfb8aa3b, v53
	v_exp_f32_e32 v52, v52
	v_fma_f32 v50, v50, s21, 0.5
	v_max_f32_e32 v50, 1.0, v50
	v_fma_f32 v0, v0, s21, 0.5
	v_cvt_pk_u8_f32 v50, v50, 0, 0
	v_max_f32_e32 v0, 1.0, v0
	v_add_f32_e32 v51, 1.0, v51
	v_rcp_f32_e32 v51, v51
	v_cvt_pk_u8_f32 v0, v0, 1, v50
	v_add_f32_e32 v50, 1.0, v52
	v_rcp_f32_e32 v50, v50
	v_mul_f32_e32 v46, 0xbfb8aa3b, v46
	v_exp_f32_e32 v46, v46
	v_mul_f32_e32 v47, 0xbfb8aa3b, v47
	v_fma_f32 v51, v51, s21, 0.5
	v_exp_f32_e32 v47, v47
	v_max_f32_e32 v51, 1.0, v51
	v_fma_f32 v50, v50, s21, 0.5
	v_cvt_pk_u8_f32 v0, v51, 2, v0
	v_max_f32_e32 v50, 1.0, v50
	v_cvt_pk_u8_f32 v0, v50, 3, v0
	v_add_f32_e32 v46, 1.0, v46
	v_rcp_f32_e32 v46, v46
	global_store_dword v[62:63], v0, off offset:768
	v_add_f32_e32 v0, 1.0, v47
	v_rcp_f32_e32 v0, v0
	v_mul_f32_e32 v47, 0xbfb8aa3b, v48
	v_exp_f32_e32 v47, v47
	v_mul_f32_e32 v48, 0xbfb8aa3b, v49
	v_exp_f32_e32 v48, v48
	v_fma_f32 v46, v46, s21, 0.5
	v_max_f32_e32 v46, 1.0, v46
	v_fma_f32 v0, v0, s21, 0.5
	v_cvt_pk_u8_f32 v46, v46, 0, 0
	v_max_f32_e32 v0, 1.0, v0
	v_add_f32_e32 v47, 1.0, v47
	v_rcp_f32_e32 v47, v47
	v_cvt_pk_u8_f32 v0, v0, 1, v46
	v_add_f32_e32 v46, 1.0, v48
	v_rcp_f32_e32 v46, v46
	v_mul_f32_e32 v42, 0xbfb8aa3b, v42
	v_exp_f32_e32 v42, v42
	v_mul_f32_e32 v43, 0xbfb8aa3b, v43
	v_fma_f32 v47, v47, s21, 0.5
	v_exp_f32_e32 v43, v43
	v_max_f32_e32 v47, 1.0, v47
	v_fma_f32 v46, v46, s21, 0.5
	v_cvt_pk_u8_f32 v0, v47, 2, v0
	v_max_f32_e32 v46, 1.0, v46
	v_cvt_pk_u8_f32 v0, v46, 3, v0
	v_add_f32_e32 v42, 1.0, v42
	v_rcp_f32_e32 v42, v42
	global_store_dword v[62:63], v0, off offset:1024
	v_add_f32_e32 v0, 1.0, v43
	v_rcp_f32_e32 v0, v0
	v_mul_f32_e32 v43, 0xbfb8aa3b, v44
	v_exp_f32_e32 v43, v43
	v_mul_f32_e32 v44, 0xbfb8aa3b, v45
	v_exp_f32_e32 v44, v44
	v_fma_f32 v42, v42, s21, 0.5
	v_max_f32_e32 v42, 1.0, v42
	v_fma_f32 v0, v0, s21, 0.5
	v_cvt_pk_u8_f32 v42, v42, 0, 0
	v_max_f32_e32 v0, 1.0, v0
	v_add_f32_e32 v43, 1.0, v43
	v_rcp_f32_e32 v43, v43
	v_cvt_pk_u8_f32 v0, v0, 1, v42
	v_add_f32_e32 v42, 1.0, v44
	v_rcp_f32_e32 v42, v42
	v_mul_f32_e32 v38, 0xbfb8aa3b, v38
	v_exp_f32_e32 v38, v38
	v_mul_f32_e32 v39, 0xbfb8aa3b, v39
	v_fma_f32 v43, v43, s21, 0.5
	v_exp_f32_e32 v39, v39
	v_max_f32_e32 v43, 1.0, v43
	v_fma_f32 v42, v42, s21, 0.5
	v_cvt_pk_u8_f32 v0, v43, 2, v0
	v_max_f32_e32 v42, 1.0, v42
	v_cvt_pk_u8_f32 v0, v42, 3, v0
	v_add_f32_e32 v38, 1.0, v38
	v_rcp_f32_e32 v38, v38
	global_store_dword v[62:63], v0, off offset:1280
	v_add_f32_e32 v0, 1.0, v39
	v_rcp_f32_e32 v0, v0
	v_mul_f32_e32 v39, 0xbfb8aa3b, v40
	v_exp_f32_e32 v39, v39
	v_mul_f32_e32 v40, 0xbfb8aa3b, v41
	v_exp_f32_e32 v40, v40
	v_fma_f32 v38, v38, s21, 0.5
	v_max_f32_e32 v38, 1.0, v38
	v_fma_f32 v0, v0, s21, 0.5
	v_cvt_pk_u8_f32 v38, v38, 0, 0
	v_max_f32_e32 v0, 1.0, v0
	v_add_f32_e32 v39, 1.0, v39
	v_rcp_f32_e32 v39, v39
	v_cvt_pk_u8_f32 v0, v0, 1, v38
	v_add_f32_e32 v38, 1.0, v40
	v_rcp_f32_e32 v38, v38
	v_mul_f32_e32 v34, 0xbfb8aa3b, v34
	v_exp_f32_e32 v34, v34
	v_mul_f32_e32 v35, 0xbfb8aa3b, v35
	v_fma_f32 v39, v39, s21, 0.5
	v_exp_f32_e32 v35, v35
	v_max_f32_e32 v39, 1.0, v39
	v_fma_f32 v38, v38, s21, 0.5
	v_cvt_pk_u8_f32 v0, v39, 2, v0
	v_max_f32_e32 v38, 1.0, v38
	v_cvt_pk_u8_f32 v0, v38, 3, v0
	v_add_f32_e32 v34, 1.0, v34
	v_rcp_f32_e32 v34, v34
	global_store_dword v[62:63], v0, off offset:1536
	v_add_f32_e32 v0, 1.0, v35
	v_rcp_f32_e32 v0, v0
	v_mul_f32_e32 v35, 0xbfb8aa3b, v36
	v_exp_f32_e32 v35, v35
	v_mul_f32_e32 v36, 0xbfb8aa3b, v37
	v_exp_f32_e32 v36, v36
	v_fma_f32 v34, v34, s21, 0.5
	v_max_f32_e32 v34, 1.0, v34
	v_fma_f32 v0, v0, s21, 0.5
	v_cvt_pk_u8_f32 v34, v34, 0, 0
	v_max_f32_e32 v0, 1.0, v0
	v_add_f32_e32 v35, 1.0, v35
	v_rcp_f32_e32 v35, v35
	v_cvt_pk_u8_f32 v0, v0, 1, v34
	v_add_f32_e32 v34, 1.0, v36
	v_rcp_f32_e32 v34, v34
	v_mul_f32_e32 v30, 0xbfb8aa3b, v30
	v_exp_f32_e32 v30, v30
	v_mul_f32_e32 v31, 0xbfb8aa3b, v31
	v_fma_f32 v35, v35, s21, 0.5
	v_exp_f32_e32 v31, v31
	v_max_f32_e32 v35, 1.0, v35
	v_fma_f32 v34, v34, s21, 0.5
	v_cvt_pk_u8_f32 v0, v35, 2, v0
	v_max_f32_e32 v34, 1.0, v34
	v_cvt_pk_u8_f32 v0, v34, 3, v0
	v_add_f32_e32 v30, 1.0, v30
	v_rcp_f32_e32 v30, v30
	global_store_dword v[62:63], v0, off offset:1792
	v_add_f32_e32 v0, 1.0, v31
	v_rcp_f32_e32 v0, v0
	v_mul_f32_e32 v31, 0xbfb8aa3b, v32
	v_exp_f32_e32 v31, v31
	v_mul_f32_e32 v32, 0xbfb8aa3b, v33
	v_exp_f32_e32 v32, v32
	v_fma_f32 v30, v30, s21, 0.5
	v_max_f32_e32 v30, 1.0, v30
	v_fma_f32 v0, v0, s21, 0.5
	v_cvt_pk_u8_f32 v30, v30, 0, 0
	v_max_f32_e32 v0, 1.0, v0
	v_add_f32_e32 v31, 1.0, v31
	v_rcp_f32_e32 v31, v31
	v_cvt_pk_u8_f32 v0, v0, 1, v30
	v_add_f32_e32 v30, 1.0, v32
	v_rcp_f32_e32 v30, v30
	v_mul_f32_e32 v26, 0xbfb8aa3b, v26
	v_exp_f32_e32 v26, v26
	v_mul_f32_e32 v27, 0xbfb8aa3b, v27
	v_fma_f32 v31, v31, s21, 0.5
	v_exp_f32_e32 v27, v27
	v_max_f32_e32 v31, 1.0, v31
	v_fma_f32 v30, v30, s21, 0.5
	v_cvt_pk_u8_f32 v0, v31, 2, v0
	v_max_f32_e32 v30, 1.0, v30
	v_cvt_pk_u8_f32 v0, v30, 3, v0
	v_add_f32_e32 v26, 1.0, v26
	v_rcp_f32_e32 v26, v26
	global_store_dword v[62:63], v0, off offset:2048
	v_add_f32_e32 v0, 1.0, v27
	v_rcp_f32_e32 v0, v0
	v_mul_f32_e32 v27, 0xbfb8aa3b, v28
	v_exp_f32_e32 v27, v27
	v_mul_f32_e32 v28, 0xbfb8aa3b, v29
	v_exp_f32_e32 v28, v28
	v_fma_f32 v26, v26, s21, 0.5
	v_max_f32_e32 v26, 1.0, v26
	v_fma_f32 v0, v0, s21, 0.5
	v_cvt_pk_u8_f32 v26, v26, 0, 0
	v_max_f32_e32 v0, 1.0, v0
	v_add_f32_e32 v27, 1.0, v27
	v_rcp_f32_e32 v27, v27
	v_cvt_pk_u8_f32 v0, v0, 1, v26
	v_add_f32_e32 v26, 1.0, v28
	v_rcp_f32_e32 v26, v26
	v_mul_f32_e32 v22, 0xbfb8aa3b, v22
	v_exp_f32_e32 v22, v22
	v_mul_f32_e32 v23, 0xbfb8aa3b, v23
	v_fma_f32 v27, v27, s21, 0.5
	v_exp_f32_e32 v23, v23
	v_max_f32_e32 v27, 1.0, v27
	v_fma_f32 v26, v26, s21, 0.5
	v_cvt_pk_u8_f32 v0, v27, 2, v0
	v_max_f32_e32 v26, 1.0, v26
	v_cvt_pk_u8_f32 v0, v26, 3, v0
	v_add_f32_e32 v22, 1.0, v22
	v_rcp_f32_e32 v22, v22
	global_store_dword v[62:63], v0, off offset:2304
	v_add_f32_e32 v0, 1.0, v23
	v_rcp_f32_e32 v0, v0
	v_mul_f32_e32 v23, 0xbfb8aa3b, v24
	v_exp_f32_e32 v23, v23
	v_mul_f32_e32 v24, 0xbfb8aa3b, v25
	v_exp_f32_e32 v24, v24
	v_fma_f32 v22, v22, s21, 0.5
	v_max_f32_e32 v22, 1.0, v22
	v_fma_f32 v0, v0, s21, 0.5
	v_cvt_pk_u8_f32 v22, v22, 0, 0
	v_max_f32_e32 v0, 1.0, v0
	v_add_f32_e32 v23, 1.0, v23
	v_rcp_f32_e32 v23, v23
	v_cvt_pk_u8_f32 v0, v0, 1, v22
	v_add_f32_e32 v22, 1.0, v24
	v_rcp_f32_e32 v22, v22
	v_mul_f32_e32 v18, 0xbfb8aa3b, v18
	v_exp_f32_e32 v18, v18
	v_mul_f32_e32 v19, 0xbfb8aa3b, v19
	v_fma_f32 v23, v23, s21, 0.5
	v_exp_f32_e32 v19, v19
	v_max_f32_e32 v23, 1.0, v23
	v_fma_f32 v22, v22, s21, 0.5
	v_cvt_pk_u8_f32 v0, v23, 2, v0
	v_max_f32_e32 v22, 1.0, v22
	v_cvt_pk_u8_f32 v0, v22, 3, v0
	v_add_f32_e32 v18, 1.0, v18
	v_rcp_f32_e32 v18, v18
	global_store_dword v[62:63], v0, off offset:2560
	v_add_f32_e32 v0, 1.0, v19
	v_rcp_f32_e32 v0, v0
	v_mul_f32_e32 v19, 0xbfb8aa3b, v20
	v_exp_f32_e32 v19, v19
	v_mul_f32_e32 v20, 0xbfb8aa3b, v21
	v_exp_f32_e32 v20, v20
	v_fma_f32 v18, v18, s21, 0.5
	v_max_f32_e32 v18, 1.0, v18
	v_fma_f32 v0, v0, s21, 0.5
	v_cvt_pk_u8_f32 v18, v18, 0, 0
	v_max_f32_e32 v0, 1.0, v0
	v_add_f32_e32 v19, 1.0, v19
	v_rcp_f32_e32 v19, v19
	v_cvt_pk_u8_f32 v0, v0, 1, v18
	v_add_f32_e32 v18, 1.0, v20
	v_rcp_f32_e32 v18, v18
	v_mul_f32_e32 v14, 0xbfb8aa3b, v14
	v_exp_f32_e32 v14, v14
	v_mul_f32_e32 v15, 0xbfb8aa3b, v15
	v_fma_f32 v19, v19, s21, 0.5
	v_exp_f32_e32 v15, v15
	v_max_f32_e32 v19, 1.0, v19
	v_fma_f32 v18, v18, s21, 0.5
	v_cvt_pk_u8_f32 v0, v19, 2, v0
	v_max_f32_e32 v18, 1.0, v18
	v_cvt_pk_u8_f32 v0, v18, 3, v0
	v_add_f32_e32 v14, 1.0, v14
	v_rcp_f32_e32 v14, v14
	global_store_dword v[62:63], v0, off offset:2816
	v_add_f32_e32 v0, 1.0, v15
	v_rcp_f32_e32 v0, v0
	v_mul_f32_e32 v15, 0xbfb8aa3b, v16
	v_exp_f32_e32 v15, v15
	v_mul_f32_e32 v16, 0xbfb8aa3b, v17
	v_exp_f32_e32 v16, v16
	v_fma_f32 v14, v14, s21, 0.5
	v_max_f32_e32 v14, 1.0, v14
	v_fma_f32 v0, v0, s21, 0.5
	v_cvt_pk_u8_f32 v14, v14, 0, 0
	v_max_f32_e32 v0, 1.0, v0
	v_add_f32_e32 v15, 1.0, v15
	v_rcp_f32_e32 v15, v15
	v_cvt_pk_u8_f32 v0, v0, 1, v14
	v_add_f32_e32 v14, 1.0, v16
	v_rcp_f32_e32 v14, v14
	v_mul_f32_e32 v10, 0xbfb8aa3b, v10
	v_exp_f32_e32 v10, v10
	v_mul_f32_e32 v11, 0xbfb8aa3b, v11
	v_fma_f32 v15, v15, s21, 0.5
	v_exp_f32_e32 v11, v11
	v_max_f32_e32 v15, 1.0, v15
	v_fma_f32 v14, v14, s21, 0.5
	v_cvt_pk_u8_f32 v0, v15, 2, v0
	v_max_f32_e32 v14, 1.0, v14
	v_cvt_pk_u8_f32 v0, v14, 3, v0
	v_add_f32_e32 v10, 1.0, v10
	v_rcp_f32_e32 v10, v10
	global_store_dword v[62:63], v0, off offset:3072
	v_add_f32_e32 v0, 1.0, v11
	v_rcp_f32_e32 v0, v0
	v_mul_f32_e32 v11, 0xbfb8aa3b, v12
	v_exp_f32_e32 v11, v11
	v_mul_f32_e32 v12, 0xbfb8aa3b, v13
	v_exp_f32_e32 v12, v12
	v_fma_f32 v10, v10, s21, 0.5
	v_max_f32_e32 v10, 1.0, v10
	v_fma_f32 v0, v0, s21, 0.5
	v_cvt_pk_u8_f32 v10, v10, 0, 0
	v_max_f32_e32 v0, 1.0, v0
	v_add_f32_e32 v11, 1.0, v11
	v_rcp_f32_e32 v11, v11
	v_cvt_pk_u8_f32 v0, v0, 1, v10
	v_add_f32_e32 v10, 1.0, v12
	v_rcp_f32_e32 v10, v10
	v_mul_f32_e32 v6, 0xbfb8aa3b, v6
	v_exp_f32_e32 v6, v6
	v_mul_f32_e32 v7, 0xbfb8aa3b, v7
	v_fma_f32 v11, v11, s21, 0.5
	v_exp_f32_e32 v7, v7
	v_max_f32_e32 v11, 1.0, v11
	v_fma_f32 v10, v10, s21, 0.5
	v_cvt_pk_u8_f32 v0, v11, 2, v0
	v_max_f32_e32 v10, 1.0, v10
	v_cvt_pk_u8_f32 v0, v10, 3, v0
	v_add_f32_e32 v6, 1.0, v6
	v_rcp_f32_e32 v6, v6
	global_store_dword v[62:63], v0, off offset:3328
	v_add_f32_e32 v0, 1.0, v7
	v_rcp_f32_e32 v0, v0
	v_mul_f32_e32 v7, 0xbfb8aa3b, v8
	v_exp_f32_e32 v7, v7
	v_mul_f32_e32 v8, 0xbfb8aa3b, v9
	v_exp_f32_e32 v8, v8
	v_fma_f32 v6, v6, s21, 0.5
	v_max_f32_e32 v6, 1.0, v6
	v_fma_f32 v0, v0, s21, 0.5
	v_cvt_pk_u8_f32 v6, v6, 0, 0
	v_max_f32_e32 v0, 1.0, v0
	v_add_f32_e32 v7, 1.0, v7
	v_rcp_f32_e32 v7, v7
	v_cvt_pk_u8_f32 v0, v0, 1, v6
	v_add_f32_e32 v6, 1.0, v8
	v_rcp_f32_e32 v6, v6
	v_mul_f32_e32 v2, 0xbfb8aa3b, v2
	v_exp_f32_e32 v2, v2
	v_mul_f32_e32 v3, 0xbfb8aa3b, v3
	v_fma_f32 v7, v7, s21, 0.5
	v_exp_f32_e32 v3, v3
	v_max_f32_e32 v7, 1.0, v7
	v_fma_f32 v6, v6, s21, 0.5
	v_cvt_pk_u8_f32 v0, v7, 2, v0
	v_max_f32_e32 v6, 1.0, v6
	v_cvt_pk_u8_f32 v0, v6, 3, v0
	v_add_f32_e32 v2, 1.0, v2
	v_rcp_f32_e32 v2, v2
	global_store_dword v[62:63], v0, off offset:3584
	v_add_f32_e32 v0, 1.0, v3
	v_rcp_f32_e32 v0, v0
	v_mul_f32_e32 v3, 0xbfb8aa3b, v4
	v_exp_f32_e32 v3, v3
	v_mul_f32_e32 v4, 0xbfb8aa3b, v5
	v_exp_f32_e32 v4, v4
	v_fma_f32 v2, v2, s21, 0.5
	v_max_f32_e32 v2, 1.0, v2
	v_fma_f32 v0, v0, s21, 0.5
	v_cvt_pk_u8_f32 v2, v2, 0, 0
	v_max_f32_e32 v0, 1.0, v0
	v_add_f32_e32 v3, 1.0, v3
	v_rcp_f32_e32 v3, v3
	v_cvt_pk_u8_f32 v0, v0, 1, v2
	v_add_f32_e32 v2, 1.0, v4
	v_rcp_f32_e32 v2, v2
	v_fma_f32 v3, v3, s21, 0.5
	s_add_i32 s96, s96, 1
	v_max_f32_e32 v3, 1.0, v3
	v_fma_f32 v2, v2, s21, 0.5
	s_add_u32 s12, s12, 0x200000
	v_cvt_pk_u8_f32 v0, v3, 2, v0
	v_max_f32_e32 v2, 1.0, v2
	s_addc_u32 s13, s13, 0
	v_cvt_pk_u8_f32 v0, v2, 3, v0
	s_cmp_lg_u32 s96, 3
	s_mov_b32 s97, 0x12000
	global_store_dword v[62:63], v0, off offset:3840
	s_cbranch_scc1 .LBB0_328
	s_lshl_b64 s[2:3], s[8:9], 10
	s_add_u32 s12, s72, s18
	s_addc_u32 s13, s73, s19
	v_mov_b32_e32 v2, v1
	v_mov_b32_e32 v3, v1
	s_add_u32 s16, s72, s2
	v_mov_b32_e32 v0, v1
	v_mov_b64_e32 v[6:7], v[2:3]
	v_mov_b64_e32 v[10:11], v[2:3]
	v_mov_b64_e32 v[22:23], v[2:3]
	v_mov_b64_e32 v[26:27], v[2:3]
	v_mov_b64_e32 v[38:39], v[2:3]
	v_mov_b64_e32 v[42:43], v[2:3]
	v_mov_b64_e32 v[54:55], v[2:3]
	v_mov_b64_e32 v[58:59], v[2:3]
	v_mov_b64_e32 v[14:15], v[2:3]
	v_mov_b64_e32 v[18:19], v[2:3]
	v_mov_b64_e32 v[30:31], v[2:3]
	v_mov_b64_e32 v[34:35], v[2:3]
	v_mov_b64_e32 v[46:47], v[2:3]
	v_mov_b64_e32 v[50:51], v[2:3]
	v_mov_b64_e32 v[62:63], v[2:3]
	v_mov_b64_e32 v[66:67], v[2:3]
	v_mov_b64_e32 v[70:71], v[2:3]
	v_mov_b64_e32 v[74:75], v[2:3]
	v_mov_b64_e32 v[86:87], v[2:3]
	v_mov_b64_e32 v[90:91], v[2:3]
	v_mov_b64_e32 v[102:103], v[2:3]
	v_mov_b64_e32 v[106:107], v[2:3]
	v_mov_b64_e32 v[118:119], v[2:3]
	v_mov_b64_e32 v[122:123], v[2:3]
	v_mov_b64_e32 v[78:79], v[2:3]
	v_mov_b64_e32 v[82:83], v[2:3]
	v_mov_b64_e32 v[94:95], v[2:3]
	v_mov_b64_e32 v[98:99], v[2:3]
	v_mov_b64_e32 v[110:111], v[2:3]
	v_mov_b64_e32 v[114:115], v[2:3]
	v_mov_b64_e32 v[126:127], v[2:3]
	v_mov_b64_e32 v[130:131], v[2:3]
	s_addc_u32 s17, s73, s3
	s_mov_b32 s56, 0
	v_mov_b64_e32 v[4:5], v[0:1]
	v_mov_b64_e32 v[8:9], v[0:1]
	v_mov_b64_e32 v[20:21], v[0:1]
	v_mov_b64_e32 v[24:25], v[0:1]
	v_mov_b64_e32 v[36:37], v[0:1]
	v_mov_b64_e32 v[40:41], v[0:1]
	v_mov_b64_e32 v[52:53], v[0:1]
	v_mov_b64_e32 v[56:57], v[0:1]
	v_mov_b64_e32 v[12:13], v[0:1]
	v_mov_b64_e32 v[16:17], v[0:1]
	v_mov_b64_e32 v[28:29], v[0:1]
	v_mov_b64_e32 v[32:33], v[0:1]
	v_mov_b64_e32 v[44:45], v[0:1]
	v_mov_b64_e32 v[48:49], v[0:1]
	v_mov_b64_e32 v[60:61], v[0:1]
	v_mov_b64_e32 v[64:65], v[0:1]
	v_mov_b64_e32 v[68:69], v[0:1]
	v_mov_b64_e32 v[72:73], v[0:1]
	v_mov_b64_e32 v[84:85], v[0:1]
	v_mov_b64_e32 v[88:89], v[0:1]
	v_mov_b64_e32 v[100:101], v[0:1]
	v_mov_b64_e32 v[104:105], v[0:1]
	v_mov_b64_e32 v[116:117], v[0:1]
	v_mov_b64_e32 v[120:121], v[0:1]
	v_mov_b64_e32 v[76:77], v[0:1]
	v_mov_b64_e32 v[80:81], v[0:1]
	v_mov_b64_e32 v[92:93], v[0:1]
	v_mov_b64_e32 v[96:97], v[0:1]
	v_mov_b64_e32 v[108:109], v[0:1]
	v_mov_b64_e32 v[112:113], v[0:1]
	v_mov_b64_e32 v[124:125], v[0:1]
	v_mov_b64_e32 v[128:129], v[0:1]
	s_movk_i32 s96, 0x5000
	s_branch .LBB0_340

.LBB0_341:
	s_cmpk_eq_i32 s40, 0x400
	s_cselect_b64 s[52:53], -1, 0
	s_and_b64 s[52:53], s[2:3], s[52:53]
	s_and_b64 s[54:55], s[52:53], exec
	s_cselect_b32 s82, s63, s57
	s_add_u32 s83, s18, s40
	s_addc_u32 s87, s19, s41
	s_cmpk_eq_i32 s40, 0x400
	s_cselect_b64 s[54:55], -1, 0
	s_and_b64 s[54:55], s[54:55], exec
	s_cselect_b32 s54, s82, s83
	s_and_b64 s[82:83], s[52:53], exec
	s_cselect_b32 s55, s66, s58
	s_cmpk_eq_i32 s40, 0x400
	v_add_u32_e32 v145, s6, v143
	s_cselect_b64 s[82:83], -1, 0
	ds_read_b128 v[146:149], v145
	ds_read_b128 v[150:153], v145 offset:1024
	ds_read_b128 v[158:161], v145 offset:2048
	ds_read_b128 v[162:165], v145 offset:3072
	v_add_u32_e32 v145, s7, v143
	s_and_b64 s[94:95], s[82:83], exec
	ds_read_b128 v[196:199], v145
	ds_read_b128 v[200:203], v145 offset:1024
	ds_read_b128 v[204:207], v145 offset:2048
	ds_read_b128 v[208:211], v145 offset:3072
	s_cselect_b32 s55, s55, s87
	s_and_b64 s[82:83], s[82:83], s[8:9]
	s_and_b64 s[82:83], s[82:83], exec
	s_cselect_b32 s83, 0, s40
	s_cselect_b32 s82, 0, s41
	s_add_u32 s83, s59, s83
	s_addc_u32 s82, s62, s82
	s_and_b64 s[52:53], s[52:53], exec
	s_cselect_b32 s53, s84, s82
	s_cselect_b32 s52, s70, s83
	v_lshl_add_u64 v[154:155], v[138:139], 0, s[40:41]
	s_add_i32 s87, s85, 0
	v_lshl_add_u64 v[154:155], v[154:155], 0, s[78:79]
	s_add_i32 m0, s87, 0xc000
	ds_read_b128 v[212:215], v144
	ds_read_b128 v[216:219], v144 offset:1024
	ds_read_b128 v[220:223], v144 offset:2048
	ds_read_b128 v[224:227], v144 offset:3072
	ds_read_b128 v[228:231], v144 offset:4096
	ds_read_b128 v[232:235], v144 offset:5120
	ds_read_b128 v[236:239], v144 offset:6144
	ds_read_b128 v[240:243], v144 offset:7168
	global_load_lds_dwordx4 v[154:155], off
	v_lshl_add_u64 v[154:155], v[136:137], 0, s[40:41]
	v_lshl_add_u64 v[154:155], v[154:155], 0, s[78:79]
	s_add_i32 m0, s87, 0xe000
	s_nop 0
	global_load_lds_dwordx4 v[154:155], off
	s_waitcnt vmcnt(8)
	s_waitcnt lgkmcnt(0)
	s_barrier
	s_setprio 1
	s_waitcnt lgkmcnt(0)
	v_mfma_f32_16x16x32_bf16 v[128:131], v[146:149], v[212:215], v[128:131]
	v_mfma_f32_16x16x32_bf16 v[124:127], v[158:161], v[212:215], v[124:127]
	v_mfma_f32_16x16x32_bf16 v[112:115], v[146:149], v[220:223], v[112:115]
	v_mfma_f32_16x16x32_bf16 v[108:111], v[158:161], v[220:223], v[108:111]
	v_mfma_f32_16x16x32_bf16 v[96:99], v[146:149], v[228:231], v[96:99]
	v_mfma_f32_16x16x32_bf16 v[92:95], v[158:161], v[228:231], v[92:95]
	v_mfma_f32_16x16x32_bf16 v[80:83], v[146:149], v[236:239], v[80:83]
	v_mfma_f32_16x16x32_bf16 v[76:79], v[158:161], v[236:239], v[76:79]
	s_setprio 0
	s_setprio 1
	v_mfma_f32_16x16x32_bf16 v[128:131], v[150:153], v[216:219], v[128:131]
	v_mfma_f32_16x16x32_bf16 v[124:127], v[162:165], v[216:219], v[124:127]
	v_mfma_f32_16x16x32_bf16 v[112:115], v[150:153], v[224:227], v[112:115]
	v_mfma_f32_16x16x32_bf16 v[108:111], v[162:165], v[224:227], v[108:111]
	v_mfma_f32_16x16x32_bf16 v[96:99], v[150:153], v[232:235], v[96:99]
	v_mfma_f32_16x16x32_bf16 v[92:95], v[162:165], v[232:235], v[92:95]
	v_mfma_f32_16x16x32_bf16 v[80:83], v[150:153], v[240:243], v[80:83]
	v_mfma_f32_16x16x32_bf16 v[76:79], v[162:165], v[240:243], v[76:79]
	s_setprio 0
	s_setprio 1
	v_mfma_f32_16x16x32_bf16 v[120:123], v[196:199], v[212:215], v[120:123]
	v_mfma_f32_16x16x32_bf16 v[116:119], v[204:207], v[212:215], v[116:119]
	v_mfma_f32_16x16x32_bf16 v[104:107], v[196:199], v[220:223], v[104:107]
	v_mfma_f32_16x16x32_bf16 v[100:103], v[204:207], v[220:223], v[100:103]
	v_mfma_f32_16x16x32_bf16 v[88:91], v[196:199], v[228:231], v[88:91]
	v_mfma_f32_16x16x32_bf16 v[84:87], v[204:207], v[228:231], v[84:87]
	v_mfma_f32_16x16x32_bf16 v[72:75], v[196:199], v[236:239], v[72:75]
	v_mfma_f32_16x16x32_bf16 v[68:71], v[204:207], v[236:239], v[68:71]
	s_setprio 0
	s_setprio 1
	v_mfma_f32_16x16x32_bf16 v[120:123], v[200:203], v[216:219], v[120:123]
	v_mfma_f32_16x16x32_bf16 v[116:119], v[208:211], v[216:219], v[116:119]
	v_mfma_f32_16x16x32_bf16 v[104:107], v[200:203], v[224:227], v[104:107]
	v_mfma_f32_16x16x32_bf16 v[100:103], v[208:211], v[224:227], v[100:103]
	v_mfma_f32_16x16x32_bf16 v[88:91], v[200:203], v[232:235], v[88:91]
	v_mfma_f32_16x16x32_bf16 v[84:87], v[208:211], v[232:235], v[84:87]
	v_mfma_f32_16x16x32_bf16 v[72:75], v[200:203], v[240:243], v[72:75]
	v_mfma_f32_16x16x32_bf16 v[68:71], v[208:211], v[240:243], v[68:71]
	s_setprio 0
	s_barrier
	s_add_i32 s82, s6, s85
	v_lshl_add_u64 v[154:155], s[52:53], 0, v[132:133]
	s_mov_b32 m0, s82
	ds_read_b128 v[212:215], v144 offset:16384
	ds_read_b128 v[216:219], v144 offset:17408
	ds_read_b128 v[220:223], v144 offset:18432
	ds_read_b128 v[224:227], v144 offset:19456
	ds_read_b128 v[228:231], v144 offset:20480
	ds_read_b128 v[232:235], v144 offset:21504
	ds_read_b128 v[236:239], v144 offset:22528
	ds_read_b128 v[240:243], v144 offset:23552
	global_load_lds_dwordx4 v[154:155], off
	s_add_i32 m0, s82, 0x2000
	s_add_u32 s82, s52, 0x20000
	v_lshl_add_u64 v[176:177], s[52:53], 0, v[134:135]
	s_addc_u32 s83, s53, 0
	s_add_i32 s93, s7, s85
	global_load_lds_dwordx4 v[176:177], off
	v_lshl_add_u64 v[178:179], s[82:83], 0, v[132:133]
	s_mov_b32 m0, s93
	v_lshl_add_u64 v[194:195], s[54:55], 0, v[2:3]
	global_load_lds_dwordx4 v[178:179], off
	v_lshl_add_u64 v[178:179], s[82:83], 0, v[134:135]
	s_add_i32 m0, s93, 0x2000
	s_nop 0
	global_load_lds_dwordx4 v[178:179], off
	v_lshl_add_u64 v[178:179], s[54:55], 0, v[0:1]
	s_mov_b32 m0, s87
	s_nop 0
	global_load_lds_dwordx4 v[178:179], off
	s_add_i32 m0, s87, 0x2000
	s_nop 0
	global_load_lds_dwordx4 v[194:195], off
	s_waitcnt vmcnt(8)
	s_waitcnt lgkmcnt(0)
	s_barrier
	s_setprio 1
	s_waitcnt lgkmcnt(0)
	v_mfma_f32_16x16x32_bf16 v[64:67], v[146:149], v[212:215], v[64:67]
	v_mfma_f32_16x16x32_bf16 v[60:63], v[158:161], v[212:215], v[60:63]
	v_mfma_f32_16x16x32_bf16 v[48:51], v[146:149], v[220:223], v[48:51]
	v_mfma_f32_16x16x32_bf16 v[44:47], v[158:161], v[220:223], v[44:47]
	v_mfma_f32_16x16x32_bf16 v[32:35], v[146:149], v[228:231], v[32:35]
	v_mfma_f32_16x16x32_bf16 v[28:31], v[158:161], v[228:231], v[28:31]
	v_mfma_f32_16x16x32_bf16 v[16:19], v[146:149], v[236:239], v[16:19]
	v_mfma_f32_16x16x32_bf16 v[12:15], v[158:161], v[236:239], v[12:15]
	s_setprio 0
	s_setprio 1
	v_mfma_f32_16x16x32_bf16 v[64:67], v[150:153], v[216:219], v[64:67]
	v_mfma_f32_16x16x32_bf16 v[60:63], v[162:165], v[216:219], v[60:63]
	v_mfma_f32_16x16x32_bf16 v[48:51], v[150:153], v[224:227], v[48:51]
	v_mfma_f32_16x16x32_bf16 v[44:47], v[162:165], v[224:227], v[44:47]
	v_mfma_f32_16x16x32_bf16 v[32:35], v[150:153], v[232:235], v[32:35]
	v_mfma_f32_16x16x32_bf16 v[28:31], v[162:165], v[232:235], v[28:31]
	v_mfma_f32_16x16x32_bf16 v[16:19], v[150:153], v[240:243], v[16:19]
	v_mfma_f32_16x16x32_bf16 v[12:15], v[162:165], v[240:243], v[12:15]
	s_setprio 0
	s_setprio 1
	v_mfma_f32_16x16x32_bf16 v[56:59], v[196:199], v[212:215], v[56:59]
	v_mfma_f32_16x16x32_bf16 v[52:55], v[204:207], v[212:215], v[52:55]
	v_mfma_f32_16x16x32_bf16 v[40:43], v[196:199], v[220:223], v[40:43]
	v_mfma_f32_16x16x32_bf16 v[36:39], v[204:207], v[220:223], v[36:39]
	v_mfma_f32_16x16x32_bf16 v[24:27], v[196:199], v[228:231], v[24:27]
	v_mfma_f32_16x16x32_bf16 v[20:23], v[204:207], v[228:231], v[20:23]
	v_mfma_f32_16x16x32_bf16 v[8:11], v[196:199], v[236:239], v[8:11]
	v_mfma_f32_16x16x32_bf16 v[4:7], v[204:207], v[236:239], v[4:7]
	s_setprio 0
	s_setprio 1
	v_mfma_f32_16x16x32_bf16 v[56:59], v[200:203], v[216:219], v[56:59]
	v_mfma_f32_16x16x32_bf16 v[52:55], v[208:211], v[216:219], v[52:55]
	v_mfma_f32_16x16x32_bf16 v[40:43], v[200:203], v[224:227], v[40:43]
	v_mfma_f32_16x16x32_bf16 v[36:39], v[208:211], v[224:227], v[36:39]
	v_mfma_f32_16x16x32_bf16 v[24:27], v[200:203], v[232:235], v[24:27]
	v_mfma_f32_16x16x32_bf16 v[20:23], v[208:211], v[232:235], v[20:23]
	v_mfma_f32_16x16x32_bf16 v[8:11], v[200:203], v[240:243], v[8:11]
	v_mfma_f32_16x16x32_bf16 v[4:7], v[208:211], v[240:243], v[4:7]
	s_setprio 0
	s_barrier
	v_add_u32_e32 v145, s10, v143
	ds_read_b128 v[146:149], v145
	ds_read_b128 v[150:153], v145 offset:1024
	ds_read_b128 v[158:161], v145 offset:2048
	ds_read_b128 v[162:165], v145 offset:3072
	v_add_u32_e32 v145, s11, v143
	ds_read_b128 v[196:199], v145
	ds_read_b128 v[200:203], v145 offset:1024
	ds_read_b128 v[204:207], v145 offset:2048
	ds_read_b128 v[208:211], v145 offset:3072
	s_add_u32 s54, s54, 0x20000
	s_addc_u32 s55, s55, 0
	v_lshl_add_u64 v[244:245], s[54:55], 0, v[0:1]
	s_add_i32 m0, s87, 0x4000
	ds_read_b128 v[212:215], v144 offset:32768
	ds_read_b128 v[216:219], v144 offset:33792
	ds_read_b128 v[220:223], v144 offset:34816
	ds_read_b128 v[224:227], v144 offset:35840
	ds_read_b128 v[228:231], v144 offset:36864
	ds_read_b128 v[232:235], v144 offset:37888
	ds_read_b128 v[236:239], v144 offset:38912
	ds_read_b128 v[240:243], v144 offset:39936
	global_load_lds_dwordx4 v[244:245], off
	v_lshl_add_u64 v[244:245], s[54:55], 0, v[2:3]
	s_add_i32 m0, s87, 0x6000
	s_nop 0
	global_load_lds_dwordx4 v[244:245], off
	s_waitcnt vmcnt(8)
	s_waitcnt lgkmcnt(0)
	s_barrier
	s_setprio 1
	s_waitcnt lgkmcnt(0)
	v_mfma_f32_16x16x32_bf16 v[128:131], v[146:149], v[212:215], v[128:131]
	v_mfma_f32_16x16x32_bf16 v[124:127], v[158:161], v[212:215], v[124:127]
	v_mfma_f32_16x16x32_bf16 v[112:115], v[146:149], v[220:223], v[112:115]
	v_mfma_f32_16x16x32_bf16 v[108:111], v[158:161], v[220:223], v[108:111]
	v_mfma_f32_16x16x32_bf16 v[96:99], v[146:149], v[228:231], v[96:99]
	v_mfma_f32_16x16x32_bf16 v[92:95], v[158:161], v[228:231], v[92:95]
	v_mfma_f32_16x16x32_bf16 v[80:83], v[146:149], v[236:239], v[80:83]
	v_mfma_f32_16x16x32_bf16 v[76:79], v[158:161], v[236:239], v[76:79]
	s_setprio 0
	s_setprio 1
	v_mfma_f32_16x16x32_bf16 v[128:131], v[150:153], v[216:219], v[128:131]
	v_mfma_f32_16x16x32_bf16 v[124:127], v[162:165], v[216:219], v[124:127]
	v_mfma_f32_16x16x32_bf16 v[112:115], v[150:153], v[224:227], v[112:115]
	v_mfma_f32_16x16x32_bf16 v[108:111], v[162:165], v[224:227], v[108:111]
	v_mfma_f32_16x16x32_bf16 v[96:99], v[150:153], v[232:235], v[96:99]
	v_mfma_f32_16x16x32_bf16 v[92:95], v[162:165], v[232:235], v[92:95]
	v_mfma_f32_16x16x32_bf16 v[80:83], v[150:153], v[240:243], v[80:83]
	v_mfma_f32_16x16x32_bf16 v[76:79], v[162:165], v[240:243], v[76:79]
	s_setprio 0
	s_setprio 1
	v_mfma_f32_16x16x32_bf16 v[120:123], v[196:199], v[212:215], v[120:123]
	v_mfma_f32_16x16x32_bf16 v[116:119], v[204:207], v[212:215], v[116:119]
	v_mfma_f32_16x16x32_bf16 v[104:107], v[196:199], v[220:223], v[104:107]
	v_mfma_f32_16x16x32_bf16 v[100:103], v[204:207], v[220:223], v[100:103]
	v_mfma_f32_16x16x32_bf16 v[88:91], v[196:199], v[228:231], v[88:91]
	v_mfma_f32_16x16x32_bf16 v[84:87], v[204:207], v[228:231], v[84:87]
	v_mfma_f32_16x16x32_bf16 v[72:75], v[196:199], v[236:239], v[72:75]
	v_mfma_f32_16x16x32_bf16 v[68:71], v[204:207], v[236:239], v[68:71]
	s_setprio 0
	s_setprio 1
	v_mfma_f32_16x16x32_bf16 v[120:123], v[200:203], v[216:219], v[120:123]
	v_mfma_f32_16x16x32_bf16 v[116:119], v[208:211], v[216:219], v[116:119]
	v_mfma_f32_16x16x32_bf16 v[104:107], v[200:203], v[224:227], v[104:107]
	v_mfma_f32_16x16x32_bf16 v[100:103], v[208:211], v[224:227], v[100:103]
	v_mfma_f32_16x16x32_bf16 v[88:91], v[200:203], v[232:235], v[88:91]
	v_mfma_f32_16x16x32_bf16 v[84:87], v[208:211], v[232:235], v[84:87]
	v_mfma_f32_16x16x32_bf16 v[72:75], v[200:203], v[240:243], v[72:75]
	v_mfma_f32_16x16x32_bf16 v[68:71], v[208:211], v[240:243], v[68:71]
	s_setprio 0
	s_barrier
	s_add_i32 s54, s10, s85
	v_lshl_add_u64 v[154:155], v[154:155], 0, s[24:25]
	s_mov_b32 m0, s54
	ds_read_b128 v[212:215], v144 offset:49152
	ds_read_b128 v[216:219], v144 offset:50176
	ds_read_b128 v[220:223], v144 offset:51200
	ds_read_b128 v[224:227], v144 offset:52224
	ds_read_b128 v[228:231], v144 offset:53248
	ds_read_b128 v[232:235], v144 offset:54272
	ds_read_b128 v[236:239], v144 offset:55296
	ds_read_b128 v[240:243], v144 offset:56320
	global_load_lds_dwordx4 v[154:155], off
	s_add_i32 m0, s54, 0x2000
	s_add_u32 s52, s52, 0x20080
	v_lshl_add_u64 v[154:155], v[176:177], 0, s[24:25]
	s_addc_u32 s53, s53, 0
	s_add_i32 s54, s11, s85
	global_load_lds_dwordx4 v[154:155], off
	v_lshl_add_u64 v[154:155], s[52:53], 0, v[132:133]
	s_mov_b32 m0, s54
	s_nop 0
	global_load_lds_dwordx4 v[154:155], off
	v_lshl_add_u64 v[154:155], s[52:53], 0, v[134:135]
	s_add_i32 m0, s54, 0x2000
	s_nop 0
	global_load_lds_dwordx4 v[154:155], off
	v_lshl_add_u64 v[154:155], v[178:179], 0, s[24:25]
	s_add_i32 m0, s87, 0x8000
	s_nop 0
	global_load_lds_dwordx4 v[154:155], off
	v_lshl_add_u64 v[154:155], v[194:195], 0, s[24:25]
	s_add_i32 m0, s87, 0xa000
	s_nop 0
	global_load_lds_dwordx4 v[154:155], off
	s_waitcnt vmcnt(8)
	s_waitcnt lgkmcnt(0)
	s_barrier
	s_setprio 1
	s_waitcnt lgkmcnt(0)
	v_mfma_f32_16x16x32_bf16 v[64:67], v[146:149], v[212:215], v[64:67]
	v_mfma_f32_16x16x32_bf16 v[60:63], v[158:161], v[212:215], v[60:63]
	v_mfma_f32_16x16x32_bf16 v[48:51], v[146:149], v[220:223], v[48:51]
	v_mfma_f32_16x16x32_bf16 v[44:47], v[158:161], v[220:223], v[44:47]
	v_mfma_f32_16x16x32_bf16 v[32:35], v[146:149], v[228:231], v[32:35]
	v_mfma_f32_16x16x32_bf16 v[28:31], v[158:161], v[228:231], v[28:31]
	v_mfma_f32_16x16x32_bf16 v[16:19], v[146:149], v[236:239], v[16:19]
	v_mfma_f32_16x16x32_bf16 v[12:15], v[158:161], v[236:239], v[12:15]
	s_setprio 0
	s_setprio 1
	v_mfma_f32_16x16x32_bf16 v[64:67], v[150:153], v[216:219], v[64:67]
	v_mfma_f32_16x16x32_bf16 v[60:63], v[162:165], v[216:219], v[60:63]
	v_mfma_f32_16x16x32_bf16 v[48:51], v[150:153], v[224:227], v[48:51]
	v_mfma_f32_16x16x32_bf16 v[44:47], v[162:165], v[224:227], v[44:47]
	v_mfma_f32_16x16x32_bf16 v[32:35], v[150:153], v[232:235], v[32:35]
	v_mfma_f32_16x16x32_bf16 v[28:31], v[162:165], v[232:235], v[28:31]
	v_mfma_f32_16x16x32_bf16 v[16:19], v[150:153], v[240:243], v[16:19]
	v_mfma_f32_16x16x32_bf16 v[12:15], v[162:165], v[240:243], v[12:15]
	s_setprio 0
	s_setprio 1
	v_mfma_f32_16x16x32_bf16 v[56:59], v[196:199], v[212:215], v[56:59]
	v_mfma_f32_16x16x32_bf16 v[52:55], v[204:207], v[212:215], v[52:55]
	v_mfma_f32_16x16x32_bf16 v[40:43], v[196:199], v[220:223], v[40:43]
	v_mfma_f32_16x16x32_bf16 v[36:39], v[204:207], v[220:223], v[36:39]
	v_mfma_f32_16x16x32_bf16 v[24:27], v[196:199], v[228:231], v[24:27]
	v_mfma_f32_16x16x32_bf16 v[20:23], v[204:207], v[228:231], v[20:23]
	v_mfma_f32_16x16x32_bf16 v[8:11], v[196:199], v[236:239], v[8:11]
	v_mfma_f32_16x16x32_bf16 v[4:7], v[204:207], v[236:239], v[4:7]
	s_setprio 0
	s_setprio 1
	v_mfma_f32_16x16x32_bf16 v[56:59], v[200:203], v[216:219], v[56:59]
	v_mfma_f32_16x16x32_bf16 v[52:55], v[208:211], v[216:219], v[52:55]
	v_mfma_f32_16x16x32_bf16 v[40:43], v[200:203], v[224:227], v[40:43]
	v_mfma_f32_16x16x32_bf16 v[36:39], v[208:211], v[224:227], v[36:39]
	v_mfma_f32_16x16x32_bf16 v[24:27], v[200:203], v[232:235], v[24:27]
	v_mfma_f32_16x16x32_bf16 v[20:23], v[208:211], v[232:235], v[20:23]
	v_mfma_f32_16x16x32_bf16 v[8:11], v[200:203], v[240:243], v[8:11]
	v_mfma_f32_16x16x32_bf16 v[4:7], v[208:211], v[240:243], v[4:7]
	s_setprio 0
	s_barrier
	s_add_i32 s86, s86, 2
	s_add_u32 s40, s40, 0x100
	s_addc_u32 s41, s41, 0
	s_cmp_gt_u32 s86, 5
	s_cbranch_scc0 .LBB0_341
	s_cmp_eq_u32 s20, 2
	s_movk_i32 s58, 0x21ff
	s_mov_b64 s[8:9], 0x800
	s_mov_b64 s[18:19], 0x200
	s_cbranch_scc0 .LBB0_346
	s_waitcnt vmcnt(0)
	s_cmpk_gt_u32 s67, 0xff
	s_cbranch_scc1 .LBB0_345
	s_barrier

.LBB0_465:
	s_add_u32 s17, s18, 0xf1598080
	s_addc_u32 s20, s19, -1
	s_cmp_lg_u32 s16, 4
	s_cselect_b32 s17, s17, 0
	s_cselect_b32 s20, s20, 0
	s_add_u32 s42, s2, s17
	s_addc_u32 s43, s3, s20
	s_add_i32 s48, 0, 0x10000
	s_add_u32 s40, s8, s17
	v_add_u32_e32 v143, s48, v141
	s_addc_u32 s41, s9, s20
	s_add_i32 s17, 0, 0x14000
	ds_read_b128 v[144:147], v143
	ds_read_b128 v[148:151], v143 offset:1024
	ds_read_b128 v[152:155], v143 offset:2048
	ds_read_b128 v[158:161], v143 offset:3072
	v_add_u32_e32 v143, s17, v141
	ds_read_b128 v[162:165], v143
	ds_read_b128 v[196:199], v143 offset:1024
	ds_read_b128 v[200:203], v143 offset:2048
	ds_read_b128 v[204:207], v143 offset:3072
	v_lshl_add_u64 v[240:241], v[138:139], 0, s[18:19]
	s_add_i32 m0, s6, 0xc000
	ds_read_b128 v[208:211], v142
	ds_read_b128 v[212:215], v142 offset:1024
	ds_read_b128 v[216:219], v142 offset:2048
	ds_read_b128 v[220:223], v142 offset:3072
	ds_read_b128 v[224:227], v142 offset:4096
	ds_read_b128 v[228:231], v142 offset:5120
	ds_read_b128 v[232:235], v142 offset:6144
	ds_read_b128 v[236:239], v142 offset:7168
	global_load_lds_dwordx4 v[240:241], off
	v_lshl_add_u64 v[240:241], v[136:137], 0, s[18:19]
	s_add_i32 m0, s6, 0xe000
	s_nop 0
	global_load_lds_dwordx4 v[240:241], off
	s_waitcnt vmcnt(8)
	s_waitcnt lgkmcnt(0)
	s_barrier
	s_setprio 1
	s_waitcnt lgkmcnt(0)
	v_mfma_f32_16x16x32_bf16 v[126:129], v[144:147], v[208:211], v[126:129]
	v_mfma_f32_16x16x32_bf16 v[122:125], v[152:155], v[208:211], v[122:125]
	v_mfma_f32_16x16x32_bf16 v[110:113], v[144:147], v[216:219], v[110:113]
	v_mfma_f32_16x16x32_bf16 v[106:109], v[152:155], v[216:219], v[106:109]
	v_mfma_f32_16x16x32_bf16 v[94:97], v[144:147], v[224:227], v[94:97]
	v_mfma_f32_16x16x32_bf16 v[90:93], v[152:155], v[224:227], v[90:93]
	v_mfma_f32_16x16x32_bf16 v[78:81], v[144:147], v[232:235], v[78:81]
	v_mfma_f32_16x16x32_bf16 v[74:77], v[152:155], v[232:235], v[74:77]
	s_setprio 0
	s_setprio 1
	v_mfma_f32_16x16x32_bf16 v[126:129], v[148:151], v[212:215], v[126:129]
	v_mfma_f32_16x16x32_bf16 v[122:125], v[158:161], v[212:215], v[122:125]
	v_mfma_f32_16x16x32_bf16 v[110:113], v[148:151], v[220:223], v[110:113]
	v_mfma_f32_16x16x32_bf16 v[106:109], v[158:161], v[220:223], v[106:109]
	v_mfma_f32_16x16x32_bf16 v[94:97], v[148:151], v[228:231], v[94:97]
	v_mfma_f32_16x16x32_bf16 v[90:93], v[158:161], v[228:231], v[90:93]
	v_mfma_f32_16x16x32_bf16 v[78:81], v[148:151], v[236:239], v[78:81]
	v_mfma_f32_16x16x32_bf16 v[74:77], v[158:161], v[236:239], v[74:77]
	s_setprio 0
	s_setprio 1
	v_mfma_f32_16x16x32_bf16 v[118:121], v[162:165], v[208:211], v[118:121]
	v_mfma_f32_16x16x32_bf16 v[114:117], v[200:203], v[208:211], v[114:117]
	v_mfma_f32_16x16x32_bf16 v[102:105], v[162:165], v[216:219], v[102:105]
	v_mfma_f32_16x16x32_bf16 v[98:101], v[200:203], v[216:219], v[98:101]
	v_mfma_f32_16x16x32_bf16 v[86:89], v[162:165], v[224:227], v[86:89]
	v_mfma_f32_16x16x32_bf16 v[82:85], v[200:203], v[224:227], v[82:85]
	v_mfma_f32_16x16x32_bf16 v[70:73], v[162:165], v[232:235], v[70:73]
	v_mfma_f32_16x16x32_bf16 v[66:69], v[200:203], v[232:235], v[66:69]
	s_setprio 0
	s_setprio 1
	v_mfma_f32_16x16x32_bf16 v[118:121], v[196:199], v[212:215], v[118:121]
	v_mfma_f32_16x16x32_bf16 v[114:117], v[204:207], v[212:215], v[114:117]
	v_mfma_f32_16x16x32_bf16 v[102:105], v[196:199], v[220:223], v[102:105]
	v_mfma_f32_16x16x32_bf16 v[98:101], v[204:207], v[220:223], v[98:101]
	v_mfma_f32_16x16x32_bf16 v[86:89], v[196:199], v[228:231], v[86:89]
	v_mfma_f32_16x16x32_bf16 v[82:85], v[204:207], v[228:231], v[82:85]
	v_mfma_f32_16x16x32_bf16 v[70:73], v[196:199], v[236:239], v[70:73]
	v_mfma_f32_16x16x32_bf16 v[66:69], v[204:207], v[236:239], v[66:69]
	s_setprio 0
	s_barrier
	s_add_i32 s20, s48, s5
	v_lshl_add_u64 v[240:241], s[40:41], 0, v[0:1]
	s_mov_b32 m0, s20
	ds_read_b128 v[208:211], v142 offset:16384
	ds_read_b128 v[212:215], v142 offset:17408
	ds_read_b128 v[216:219], v142 offset:18432
	ds_read_b128 v[220:223], v142 offset:19456
	ds_read_b128 v[224:227], v142 offset:20480
	ds_read_b128 v[228:231], v142 offset:21504
	ds_read_b128 v[232:235], v142 offset:22528
	ds_read_b128 v[236:239], v142 offset:23552
	global_load_lds_dwordx4 v[240:241], off
	s_add_i32 m0, s20, 0x2000
	s_add_u32 s48, s40, 0x20000
	v_lshl_add_u64 v[242:243], s[40:41], 0, v[134:135]
	s_addc_u32 s49, s41, 0
	s_add_i32 s17, s17, s5
	global_load_lds_dwordx4 v[242:243], off
	v_lshl_add_u64 v[244:245], s[48:49], 0, v[0:1]
	s_mov_b32 m0, s17
	v_lshl_add_u64 v[246:247], s[42:43], 0, v[132:133]
	global_load_lds_dwordx4 v[244:245], off
	v_lshl_add_u64 v[244:245], s[48:49], 0, v[134:135]
	s_add_i32 m0, s17, 0x2000
	s_nop 0
	global_load_lds_dwordx4 v[244:245], off
	v_lshl_add_u64 v[244:245], s[42:43], 0, v[130:131]
	s_mov_b32 m0, s6
	s_nop 0
	global_load_lds_dwordx4 v[244:245], off
	s_mov_b32 m0, s7
	s_nop 0
	global_load_lds_dwordx4 v[246:247], off
	s_waitcnt vmcnt(8)
	s_waitcnt lgkmcnt(0)
	s_barrier
	s_setprio 1
	s_waitcnt lgkmcnt(0)
	v_mfma_f32_16x16x32_bf16 v[62:65], v[144:147], v[208:211], v[62:65]
	v_mfma_f32_16x16x32_bf16 v[58:61], v[152:155], v[208:211], v[58:61]
	v_mfma_f32_16x16x32_bf16 v[46:49], v[144:147], v[216:219], v[46:49]
	v_mfma_f32_16x16x32_bf16 v[42:45], v[152:155], v[216:219], v[42:45]
	v_mfma_f32_16x16x32_bf16 v[30:33], v[144:147], v[224:227], v[30:33]
	v_mfma_f32_16x16x32_bf16 v[26:29], v[152:155], v[224:227], v[26:29]
	v_mfma_f32_16x16x32_bf16 v[14:17], v[144:147], v[232:235], v[14:17]
	v_mfma_f32_16x16x32_bf16 v[10:13], v[152:155], v[232:235], v[10:13]
	s_setprio 0
	s_setprio 1
	v_mfma_f32_16x16x32_bf16 v[62:65], v[148:151], v[212:215], v[62:65]
	v_mfma_f32_16x16x32_bf16 v[58:61], v[158:161], v[212:215], v[58:61]
	v_mfma_f32_16x16x32_bf16 v[46:49], v[148:151], v[220:223], v[46:49]
	v_mfma_f32_16x16x32_bf16 v[42:45], v[158:161], v[220:223], v[42:45]
	v_mfma_f32_16x16x32_bf16 v[30:33], v[148:151], v[228:231], v[30:33]
	v_mfma_f32_16x16x32_bf16 v[26:29], v[158:161], v[228:231], v[26:29]
	v_mfma_f32_16x16x32_bf16 v[14:17], v[148:151], v[236:239], v[14:17]
	v_mfma_f32_16x16x32_bf16 v[10:13], v[158:161], v[236:239], v[10:13]
	s_setprio 0
	s_setprio 1
	v_mfma_f32_16x16x32_bf16 v[54:57], v[162:165], v[208:211], v[54:57]
	v_mfma_f32_16x16x32_bf16 v[50:53], v[200:203], v[208:211], v[50:53]
	v_mfma_f32_16x16x32_bf16 v[38:41], v[162:165], v[216:219], v[38:41]
	v_mfma_f32_16x16x32_bf16 v[34:37], v[200:203], v[216:219], v[34:37]
	v_mfma_f32_16x16x32_bf16 v[22:25], v[162:165], v[224:227], v[22:25]
	v_mfma_f32_16x16x32_bf16 v[18:21], v[200:203], v[224:227], v[18:21]
	v_mfma_f32_16x16x32_bf16 v[6:9], v[162:165], v[232:235], v[6:9]
	v_mfma_f32_16x16x32_bf16 v[2:5], v[200:203], v[232:235], v[2:5]
	s_setprio 0
	s_setprio 1
	v_mfma_f32_16x16x32_bf16 v[54:57], v[196:199], v[212:215], v[54:57]
	v_mfma_f32_16x16x32_bf16 v[50:53], v[204:207], v[212:215], v[50:53]
	v_mfma_f32_16x16x32_bf16 v[38:41], v[196:199], v[220:223], v[38:41]
	v_mfma_f32_16x16x32_bf16 v[34:37], v[204:207], v[220:223], v[34:37]
	v_mfma_f32_16x16x32_bf16 v[22:25], v[196:199], v[228:231], v[22:25]
	v_mfma_f32_16x16x32_bf16 v[18:21], v[204:207], v[228:231], v[18:21]
	v_mfma_f32_16x16x32_bf16 v[6:9], v[196:199], v[236:239], v[6:9]
	v_mfma_f32_16x16x32_bf16 v[2:5], v[204:207], v[236:239], v[2:5]
	s_setprio 0
	s_barrier
	s_add_i32 s17, 0, 0x18000
	v_add_u32_e32 v143, s17, v141
	s_add_i32 s20, 0, 0x1c000
	ds_read_b128 v[144:147], v143
	ds_read_b128 v[148:151], v143 offset:1024
	ds_read_b128 v[152:155], v143 offset:2048
	ds_read_b128 v[158:161], v143 offset:3072
	v_add_u32_e32 v143, s20, v141
	ds_read_b128 v[162:165], v143
	ds_read_b128 v[196:199], v143 offset:1024
	ds_read_b128 v[200:203], v143 offset:2048
	ds_read_b128 v[204:207], v143 offset:3072
	s_add_u32 s42, s42, 0x20000
	s_addc_u32 s43, s43, 0
	s_mov_b32 m0, s10
	v_lshl_add_u64 v[248:249], s[42:43], 0, v[130:131]
	ds_read_b128 v[208:211], v142 offset:32768
	ds_read_b128 v[212:215], v142 offset:33792
	ds_read_b128 v[216:219], v142 offset:34816
	ds_read_b128 v[220:223], v142 offset:35840
	ds_read_b128 v[224:227], v142 offset:36864
	ds_read_b128 v[228:231], v142 offset:37888
	ds_read_b128 v[232:235], v142 offset:38912
	ds_read_b128 v[236:239], v142 offset:39936
	global_load_lds_dwordx4 v[248:249], off
	v_lshl_add_u64 v[248:249], s[42:43], 0, v[132:133]
	s_mov_b32 m0, s11
	s_nop 0
	global_load_lds_dwordx4 v[248:249], off
	s_waitcnt vmcnt(8)
	s_waitcnt lgkmcnt(0)
	s_barrier
	s_setprio 1
	s_waitcnt lgkmcnt(0)
	v_mfma_f32_16x16x32_bf16 v[126:129], v[144:147], v[208:211], v[126:129]
	v_mfma_f32_16x16x32_bf16 v[122:125], v[152:155], v[208:211], v[122:125]
	v_mfma_f32_16x16x32_bf16 v[110:113], v[144:147], v[216:219], v[110:113]
	v_mfma_f32_16x16x32_bf16 v[106:109], v[152:155], v[216:219], v[106:109]
	v_mfma_f32_16x16x32_bf16 v[94:97], v[144:147], v[224:227], v[94:97]
	v_mfma_f32_16x16x32_bf16 v[90:93], v[152:155], v[224:227], v[90:93]
	v_mfma_f32_16x16x32_bf16 v[78:81], v[144:147], v[232:235], v[78:81]
	v_mfma_f32_16x16x32_bf16 v[74:77], v[152:155], v[232:235], v[74:77]
	s_setprio 0
	s_setprio 1
	v_mfma_f32_16x16x32_bf16 v[126:129], v[148:151], v[212:215], v[126:129]
	v_mfma_f32_16x16x32_bf16 v[122:125], v[158:161], v[212:215], v[122:125]
	v_mfma_f32_16x16x32_bf16 v[110:113], v[148:151], v[220:223], v[110:113]
	v_mfma_f32_16x16x32_bf16 v[106:109], v[158:161], v[220:223], v[106:109]
	v_mfma_f32_16x16x32_bf16 v[94:97], v[148:151], v[228:231], v[94:97]
	v_mfma_f32_16x16x32_bf16 v[90:93], v[158:161], v[228:231], v[90:93]
	v_mfma_f32_16x16x32_bf16 v[78:81], v[148:151], v[236:239], v[78:81]
	v_mfma_f32_16x16x32_bf16 v[74:77], v[158:161], v[236:239], v[74:77]
	s_setprio 0
	s_setprio 1
	v_mfma_f32_16x16x32_bf16 v[118:121], v[162:165], v[208:211], v[118:121]
	v_mfma_f32_16x16x32_bf16 v[114:117], v[200:203], v[208:211], v[114:117]
	v_mfma_f32_16x16x32_bf16 v[102:105], v[162:165], v[216:219], v[102:105]
	v_mfma_f32_16x16x32_bf16 v[98:101], v[200:203], v[216:219], v[98:101]
	v_mfma_f32_16x16x32_bf16 v[86:89], v[162:165], v[224:227], v[86:89]
	v_mfma_f32_16x16x32_bf16 v[82:85], v[200:203], v[224:227], v[82:85]
	v_mfma_f32_16x16x32_bf16 v[70:73], v[162:165], v[232:235], v[70:73]
	v_mfma_f32_16x16x32_bf16 v[66:69], v[200:203], v[232:235], v[66:69]
	s_setprio 0
	s_setprio 1
	v_mfma_f32_16x16x32_bf16 v[118:121], v[196:199], v[212:215], v[118:121]
	v_mfma_f32_16x16x32_bf16 v[114:117], v[204:207], v[212:215], v[114:117]
	v_mfma_f32_16x16x32_bf16 v[102:105], v[196:199], v[220:223], v[102:105]
	v_mfma_f32_16x16x32_bf16 v[98:101], v[204:207], v[220:223], v[98:101]
	v_mfma_f32_16x16x32_bf16 v[86:89], v[196:199], v[228:231], v[86:89]
	v_mfma_f32_16x16x32_bf16 v[82:85], v[204:207], v[228:231], v[82:85]
	v_mfma_f32_16x16x32_bf16 v[70:73], v[196:199], v[236:239], v[70:73]
	v_mfma_f32_16x16x32_bf16 v[66:69], v[204:207], v[236:239], v[66:69]
	s_setprio 0
	s_barrier
	s_add_i32 s17, s17, s5
	v_lshl_add_u64 v[240:241], v[240:241], 0, s[24:25]
	s_mov_b32 m0, s17
	ds_read_b128 v[208:211], v142 offset:49152
	ds_read_b128 v[212:215], v142 offset:50176
	ds_read_b128 v[216:219], v142 offset:51200
	ds_read_b128 v[220:223], v142 offset:52224
	ds_read_b128 v[224:227], v142 offset:53248
	ds_read_b128 v[228:231], v142 offset:54272
	ds_read_b128 v[232:235], v142 offset:55296
	ds_read_b128 v[236:239], v142 offset:56320
	global_load_lds_dwordx4 v[240:241], off
	s_add_i32 m0, s17, 0x2000
	s_add_u32 s40, s40, 0x20080
	v_lshl_add_u64 v[240:241], v[242:243], 0, s[24:25]
	s_addc_u32 s41, s41, 0
	s_add_i32 s17, s20, s5
	global_load_lds_dwordx4 v[240:241], off
	v_lshl_add_u64 v[240:241], s[40:41], 0, v[0:1]
	s_mov_b32 m0, s17
	s_nop 0
	global_load_lds_dwordx4 v[240:241], off
	v_lshl_add_u64 v[240:241], s[40:41], 0, v[134:135]
	s_add_i32 m0, s17, 0x2000
	s_nop 0
	global_load_lds_dwordx4 v[240:241], off
	v_lshl_add_u64 v[240:241], v[244:245], 0, s[24:25]
	s_mov_b32 m0, s12
	s_nop 0
	global_load_lds_dwordx4 v[240:241], off
	v_lshl_add_u64 v[240:241], v[246:247], 0, s[24:25]
	s_mov_b32 m0, s13
	s_nop 0
	global_load_lds_dwordx4 v[240:241], off
	s_waitcnt vmcnt(8)
	s_waitcnt lgkmcnt(0)
	s_barrier
	s_setprio 1
	s_waitcnt lgkmcnt(0)
	v_mfma_f32_16x16x32_bf16 v[62:65], v[144:147], v[208:211], v[62:65]
	v_mfma_f32_16x16x32_bf16 v[58:61], v[152:155], v[208:211], v[58:61]
	v_mfma_f32_16x16x32_bf16 v[46:49], v[144:147], v[216:219], v[46:49]
	v_mfma_f32_16x16x32_bf16 v[42:45], v[152:155], v[216:219], v[42:45]
	v_mfma_f32_16x16x32_bf16 v[30:33], v[144:147], v[224:227], v[30:33]
	v_mfma_f32_16x16x32_bf16 v[26:29], v[152:155], v[224:227], v[26:29]
	v_mfma_f32_16x16x32_bf16 v[14:17], v[144:147], v[232:235], v[14:17]
	v_mfma_f32_16x16x32_bf16 v[10:13], v[152:155], v[232:235], v[10:13]
	s_setprio 0
	s_setprio 1
	v_mfma_f32_16x16x32_bf16 v[62:65], v[148:151], v[212:215], v[62:65]
	v_mfma_f32_16x16x32_bf16 v[58:61], v[158:161], v[212:215], v[58:61]
	v_mfma_f32_16x16x32_bf16 v[46:49], v[148:151], v[220:223], v[46:49]
	v_mfma_f32_16x16x32_bf16 v[42:45], v[158:161], v[220:223], v[42:45]
	v_mfma_f32_16x16x32_bf16 v[30:33], v[148:151], v[228:231], v[30:33]
	v_mfma_f32_16x16x32_bf16 v[26:29], v[158:161], v[228:231], v[26:29]
	v_mfma_f32_16x16x32_bf16 v[14:17], v[148:151], v[236:239], v[14:17]
	v_mfma_f32_16x16x32_bf16 v[10:13], v[158:161], v[236:239], v[10:13]
	s_setprio 0
	s_setprio 1
	v_mfma_f32_16x16x32_bf16 v[54:57], v[162:165], v[208:211], v[54:57]
	v_mfma_f32_16x16x32_bf16 v[50:53], v[200:203], v[208:211], v[50:53]
	v_mfma_f32_16x16x32_bf16 v[38:41], v[162:165], v[216:219], v[38:41]
	v_mfma_f32_16x16x32_bf16 v[34:37], v[200:203], v[216:219], v[34:37]
	v_mfma_f32_16x16x32_bf16 v[22:25], v[162:165], v[224:227], v[22:25]
	v_mfma_f32_16x16x32_bf16 v[18:21], v[200:203], v[224:227], v[18:21]
	v_mfma_f32_16x16x32_bf16 v[6:9], v[162:165], v[232:235], v[6:9]
	v_mfma_f32_16x16x32_bf16 v[2:5], v[200:203], v[232:235], v[2:5]
	s_setprio 0
	s_setprio 1
	v_mfma_f32_16x16x32_bf16 v[54:57], v[196:199], v[212:215], v[54:57]
	v_mfma_f32_16x16x32_bf16 v[50:53], v[204:207], v[212:215], v[50:53]
	v_mfma_f32_16x16x32_bf16 v[38:41], v[196:199], v[220:223], v[38:41]
	v_mfma_f32_16x16x32_bf16 v[34:37], v[204:207], v[220:223], v[34:37]
	v_mfma_f32_16x16x32_bf16 v[22:25], v[196:199], v[228:231], v[22:25]
	v_mfma_f32_16x16x32_bf16 v[18:21], v[204:207], v[228:231], v[18:21]
	v_mfma_f32_16x16x32_bf16 v[6:9], v[196:199], v[236:239], v[6:9]
	v_mfma_f32_16x16x32_bf16 v[2:5], v[204:207], v[236:239], v[2:5]
	s_setprio 0
	s_barrier
	s_add_i32 s16, s16, 2
	s_add_u32 s18, s18, 0x100
	s_addc_u32 s19, s19, 0
	s_cmp_gt_u32 s16, 5
	s_cbranch_scc0 .LBB0_465
	s_waitcnt vmcnt(0)
	s_cmpk_lt_u32 s1, 0x100
	s_cbranch_scc0 .LBB0_461
	s_barrier
	s_branch .LBB0_461

.LBB0_476:
	s_add_i32 s6, s20, 0x100
	s_and_b64 s[4:5], s[46:47], exec
	s_cselect_b32 s6, 0, s6
	s_cselect_b32 s5, 0, 0
	s_add_u32 s50, s2, s6
	s_addc_u32 s51, s3, s5
	s_add_i32 s4, 0, 0x10000
	s_add_u32 s52, s40, s6
	s_addc_u32 s53, s41, s5
	s_add_i32 s5, 0, 0x14000
	s_add_u32 s56, s42, s20
	s_addc_u32 s57, s43, 0
	s_add_i32 s85, s4, s11
	s_add_i32 m0, s12, 0xc000
	s_add_i32 s86, s12, 0xe000
	s_add_i32 s67, s85, 0x2000
	s_add_u32 s54, s52, 0x20000
	v_add_u32_e32 v142, s4, v140
	s_addc_u32 s55, s53, 0
	s_add_i32 s84, s5, s11
	ds_read_b128 v[146:149], v142
	ds_read_b128 v[150:153], v142 offset:1024
	ds_read_b128 v[158:161], v142 offset:2048
	ds_read_b128 v[162:165], v142 offset:3072
	v_add_u32_e32 v142, s5, v140
	s_add_i32 s70, s84, 0x2000
	s_add_i32 s6, 0, 0x18000
	s_add_i32 s7, 0, 0x1c000
	ds_read_b128 v[196:199], v142
	ds_read_b128 v[200:203], v142 offset:1024
	ds_read_b128 v[204:207], v142 offset:2048
	ds_read_b128 v[208:211], v142 offset:3072
	s_add_u32 s48, s50, 0x10000
	s_addc_u32 s49, s51, 0
	s_add_i32 s66, s6, s11
	s_add_i32 s63, s66, 0x2000
	s_add_u32 s46, s52, 0x20080
	s_addc_u32 s47, s53, 0
	s_add_i32 s65, s7, s11
	s_add_i32 s20, s65, 0x2000
	v_lshl_add_u64 v[142:143], s[56:57], 0, v[26:27]
	v_lshl_add_u64 v[142:143], v[142:143], 0, s[24:25]
	ds_read_b128 v[212:215], v141
	ds_read_b128 v[216:219], v141 offset:1024
	ds_read_b128 v[220:223], v141 offset:2048
	ds_read_b128 v[224:227], v141 offset:3072
	ds_read_b128 v[228:231], v141 offset:4096
	ds_read_b128 v[232:235], v141 offset:5120
	ds_read_b128 v[236:239], v141 offset:6144
	ds_read_b128 v[240:243], v141 offset:7168
	global_load_lds_dwordx4 v[142:143], off
	v_lshl_add_u64 v[142:143], s[56:57], 0, v[28:29]
	v_lshl_add_u64 v[142:143], v[142:143], 0, s[24:25]
	s_mov_b32 m0, s86
	s_nop 0
	global_load_lds_dwordx4 v[142:143], off
	s_waitcnt vmcnt(8)
	s_waitcnt lgkmcnt(0)
	s_barrier
	s_setprio 1
	s_waitcnt lgkmcnt(0)
	v_mfma_f32_16x16x32_bf16 v[134:137], v[146:149], v[212:215], v[134:137]
	v_mfma_f32_16x16x32_bf16 v[130:133], v[158:161], v[212:215], v[130:133]
	v_mfma_f32_16x16x32_bf16 v[118:121], v[146:149], v[220:223], v[118:121]
	v_mfma_f32_16x16x32_bf16 v[114:117], v[158:161], v[220:223], v[114:117]
	v_mfma_f32_16x16x32_bf16 v[102:105], v[146:149], v[228:231], v[102:105]
	v_mfma_f32_16x16x32_bf16 v[98:101], v[158:161], v[228:231], v[98:101]
	v_mfma_f32_16x16x32_bf16 v[86:89], v[146:149], v[236:239], v[86:89]
	v_mfma_f32_16x16x32_bf16 v[82:85], v[158:161], v[236:239], v[82:85]
	s_setprio 0
	s_setprio 1
	v_mfma_f32_16x16x32_bf16 v[134:137], v[150:153], v[216:219], v[134:137]
	v_mfma_f32_16x16x32_bf16 v[130:133], v[162:165], v[216:219], v[130:133]
	v_mfma_f32_16x16x32_bf16 v[118:121], v[150:153], v[224:227], v[118:121]
	v_mfma_f32_16x16x32_bf16 v[114:117], v[162:165], v[224:227], v[114:117]
	v_mfma_f32_16x16x32_bf16 v[102:105], v[150:153], v[232:235], v[102:105]
	v_mfma_f32_16x16x32_bf16 v[98:101], v[162:165], v[232:235], v[98:101]
	v_mfma_f32_16x16x32_bf16 v[86:89], v[150:153], v[240:243], v[86:89]
	v_mfma_f32_16x16x32_bf16 v[82:85], v[162:165], v[240:243], v[82:85]
	s_setprio 0
	s_setprio 1
	v_mfma_f32_16x16x32_bf16 v[126:129], v[196:199], v[212:215], v[126:129]
	v_mfma_f32_16x16x32_bf16 v[122:125], v[204:207], v[212:215], v[122:125]
	v_mfma_f32_16x16x32_bf16 v[110:113], v[196:199], v[220:223], v[110:113]
	v_mfma_f32_16x16x32_bf16 v[106:109], v[204:207], v[220:223], v[106:109]
	v_mfma_f32_16x16x32_bf16 v[94:97], v[196:199], v[228:231], v[94:97]
	v_mfma_f32_16x16x32_bf16 v[90:93], v[204:207], v[228:231], v[90:93]
	v_mfma_f32_16x16x32_bf16 v[78:81], v[196:199], v[236:239], v[78:81]
	v_mfma_f32_16x16x32_bf16 v[74:77], v[204:207], v[236:239], v[74:77]
	s_setprio 0
	s_setprio 1
	v_mfma_f32_16x16x32_bf16 v[126:129], v[200:203], v[216:219], v[126:129]
	v_mfma_f32_16x16x32_bf16 v[122:125], v[208:211], v[216:219], v[122:125]
	v_mfma_f32_16x16x32_bf16 v[110:113], v[200:203], v[224:227], v[110:113]
	v_mfma_f32_16x16x32_bf16 v[106:109], v[208:211], v[224:227], v[106:109]
	v_mfma_f32_16x16x32_bf16 v[94:97], v[200:203], v[232:235], v[94:97]
	v_mfma_f32_16x16x32_bf16 v[90:93], v[208:211], v[232:235], v[90:93]
	v_mfma_f32_16x16x32_bf16 v[78:81], v[200:203], v[240:243], v[78:81]
	v_mfma_f32_16x16x32_bf16 v[74:77], v[208:211], v[240:243], v[74:77]
	s_setprio 0
	s_barrier
	s_mov_b32 m0, s85
	v_lshl_add_u64 v[142:143], s[52:53], 0, v[0:1]
	ds_read_b128 v[212:215], v141 offset:16384
	ds_read_b128 v[216:219], v141 offset:17408
	ds_read_b128 v[220:223], v141 offset:18432
	ds_read_b128 v[224:227], v141 offset:19456
	ds_read_b128 v[228:231], v141 offset:20480
	ds_read_b128 v[232:235], v141 offset:21504
	ds_read_b128 v[236:239], v141 offset:22528
	ds_read_b128 v[240:243], v141 offset:23552
	global_load_lds_dwordx4 v[142:143], off
	v_lshl_add_u64 v[154:155], s[52:53], 0, v[38:39]
	s_mov_b32 m0, s67
	v_lshl_add_u64 v[244:245], s[54:55], 0, v[0:1]
	global_load_lds_dwordx4 v[154:155], off
	s_mov_b32 m0, s84
	v_lshl_add_u64 v[246:247], s[50:51], 0, v[28:29]
	global_load_lds_dwordx4 v[244:245], off
	v_lshl_add_u64 v[244:245], s[54:55], 0, v[38:39]
	s_mov_b32 m0, s70
	s_nop 0
	global_load_lds_dwordx4 v[244:245], off
	v_lshl_add_u64 v[244:245], s[50:51], 0, v[26:27]
	s_mov_b32 m0, s12
	s_nop 0
	global_load_lds_dwordx4 v[244:245], off
	s_mov_b32 m0, s13
	s_nop 0
	global_load_lds_dwordx4 v[246:247], off
	s_waitcnt vmcnt(8)
	s_waitcnt lgkmcnt(0)
	s_barrier
	s_setprio 1
	s_waitcnt lgkmcnt(0)
	v_mfma_f32_16x16x32_bf16 v[70:73], v[146:149], v[212:215], v[70:73]
	v_mfma_f32_16x16x32_bf16 v[66:69], v[158:161], v[212:215], v[66:69]
	v_mfma_f32_16x16x32_bf16 v[54:57], v[146:149], v[220:223], v[54:57]
	v_mfma_f32_16x16x32_bf16 v[50:53], v[158:161], v[220:223], v[50:53]
	v_mfma_f32_16x16x32_bf16 v[34:37], v[146:149], v[228:231], v[34:37]
	v_mfma_f32_16x16x32_bf16 v[30:33], v[158:161], v[228:231], v[30:33]
	v_mfma_f32_16x16x32_bf16 v[14:17], v[146:149], v[236:239], v[14:17]
	v_mfma_f32_16x16x32_bf16 v[10:13], v[158:161], v[236:239], v[10:13]
	s_setprio 0
	s_setprio 1
	v_mfma_f32_16x16x32_bf16 v[70:73], v[150:153], v[216:219], v[70:73]
	v_mfma_f32_16x16x32_bf16 v[66:69], v[162:165], v[216:219], v[66:69]
	v_mfma_f32_16x16x32_bf16 v[54:57], v[150:153], v[224:227], v[54:57]
	v_mfma_f32_16x16x32_bf16 v[50:53], v[162:165], v[224:227], v[50:53]
	v_mfma_f32_16x16x32_bf16 v[34:37], v[150:153], v[232:235], v[34:37]
	v_mfma_f32_16x16x32_bf16 v[30:33], v[162:165], v[232:235], v[30:33]
	v_mfma_f32_16x16x32_bf16 v[14:17], v[150:153], v[240:243], v[14:17]
	v_mfma_f32_16x16x32_bf16 v[10:13], v[162:165], v[240:243], v[10:13]
	s_setprio 0
	s_setprio 1
	v_mfma_f32_16x16x32_bf16 v[62:65], v[196:199], v[212:215], v[62:65]
	v_mfma_f32_16x16x32_bf16 v[58:61], v[204:207], v[212:215], v[58:61]
	v_mfma_f32_16x16x32_bf16 v[46:49], v[196:199], v[220:223], v[46:49]
	v_mfma_f32_16x16x32_bf16 v[42:45], v[204:207], v[220:223], v[42:45]
	v_mfma_f32_16x16x32_bf16 v[22:25], v[196:199], v[228:231], v[22:25]
	v_mfma_f32_16x16x32_bf16 v[18:21], v[204:207], v[228:231], v[18:21]
	v_mfma_f32_16x16x32_bf16 v[6:9], v[196:199], v[236:239], v[6:9]
	v_mfma_f32_16x16x32_bf16 v[2:5], v[204:207], v[236:239], v[2:5]
	s_setprio 0
	s_setprio 1
	v_mfma_f32_16x16x32_bf16 v[62:65], v[200:203], v[216:219], v[62:65]
	v_mfma_f32_16x16x32_bf16 v[58:61], v[208:211], v[216:219], v[58:61]
	v_mfma_f32_16x16x32_bf16 v[46:49], v[200:203], v[224:227], v[46:49]
	v_mfma_f32_16x16x32_bf16 v[42:45], v[208:211], v[224:227], v[42:45]
	v_mfma_f32_16x16x32_bf16 v[22:25], v[200:203], v[232:235], v[22:25]
	v_mfma_f32_16x16x32_bf16 v[18:21], v[208:211], v[232:235], v[18:21]
	v_mfma_f32_16x16x32_bf16 v[6:9], v[200:203], v[240:243], v[6:9]
	v_mfma_f32_16x16x32_bf16 v[2:5], v[208:211], v[240:243], v[2:5]
	s_setprio 0
	s_barrier
	v_add_u32_e32 v145, s6, v140
	ds_read_b128 v[146:149], v145
	ds_read_b128 v[150:153], v145 offset:1024
	ds_read_b128 v[158:161], v145 offset:2048
	ds_read_b128 v[162:165], v145 offset:3072
	v_add_u32_e32 v145, s7, v140
	ds_read_b128 v[196:199], v145
	ds_read_b128 v[200:203], v145 offset:1024
	ds_read_b128 v[204:207], v145 offset:2048
	ds_read_b128 v[208:211], v145 offset:3072
	s_mov_b32 m0, s16
	v_lshl_add_u64 v[248:249], s[48:49], 0, v[26:27]
	ds_read_b128 v[212:215], v141 offset:32768
	ds_read_b128 v[216:219], v141 offset:33792
	ds_read_b128 v[220:223], v141 offset:34816
	ds_read_b128 v[224:227], v141 offset:35840
	ds_read_b128 v[228:231], v141 offset:36864
	ds_read_b128 v[232:235], v141 offset:37888
	ds_read_b128 v[236:239], v141 offset:38912
	ds_read_b128 v[240:243], v141 offset:39936
	global_load_lds_dwordx4 v[248:249], off
	v_lshl_add_u64 v[248:249], s[48:49], 0, v[28:29]
	s_mov_b32 m0, s17
	s_nop 0
	global_load_lds_dwordx4 v[248:249], off
	s_waitcnt vmcnt(8)
	s_waitcnt lgkmcnt(0)
	s_barrier
	s_setprio 1
	s_waitcnt lgkmcnt(0)
	v_mfma_f32_16x16x32_bf16 v[134:137], v[146:149], v[212:215], v[134:137]
	v_mfma_f32_16x16x32_bf16 v[130:133], v[158:161], v[212:215], v[130:133]
	v_mfma_f32_16x16x32_bf16 v[118:121], v[146:149], v[220:223], v[118:121]
	v_mfma_f32_16x16x32_bf16 v[114:117], v[158:161], v[220:223], v[114:117]
	v_mfma_f32_16x16x32_bf16 v[102:105], v[146:149], v[228:231], v[102:105]
	v_mfma_f32_16x16x32_bf16 v[98:101], v[158:161], v[228:231], v[98:101]
	v_mfma_f32_16x16x32_bf16 v[86:89], v[146:149], v[236:239], v[86:89]
	v_mfma_f32_16x16x32_bf16 v[82:85], v[158:161], v[236:239], v[82:85]
	s_setprio 0
	s_setprio 1
	v_mfma_f32_16x16x32_bf16 v[134:137], v[150:153], v[216:219], v[134:137]
	v_mfma_f32_16x16x32_bf16 v[130:133], v[162:165], v[216:219], v[130:133]
	v_mfma_f32_16x16x32_bf16 v[118:121], v[150:153], v[224:227], v[118:121]
	v_mfma_f32_16x16x32_bf16 v[114:117], v[162:165], v[224:227], v[114:117]
	v_mfma_f32_16x16x32_bf16 v[102:105], v[150:153], v[232:235], v[102:105]
	v_mfma_f32_16x16x32_bf16 v[98:101], v[162:165], v[232:235], v[98:101]
	v_mfma_f32_16x16x32_bf16 v[86:89], v[150:153], v[240:243], v[86:89]
	v_mfma_f32_16x16x32_bf16 v[82:85], v[162:165], v[240:243], v[82:85]
	s_setprio 0
	s_setprio 1
	v_mfma_f32_16x16x32_bf16 v[126:129], v[196:199], v[212:215], v[126:129]
	v_mfma_f32_16x16x32_bf16 v[122:125], v[204:207], v[212:215], v[122:125]
	v_mfma_f32_16x16x32_bf16 v[110:113], v[196:199], v[220:223], v[110:113]
	v_mfma_f32_16x16x32_bf16 v[106:109], v[204:207], v[220:223], v[106:109]
	v_mfma_f32_16x16x32_bf16 v[94:97], v[196:199], v[228:231], v[94:97]
	v_mfma_f32_16x16x32_bf16 v[90:93], v[204:207], v[228:231], v[90:93]
	v_mfma_f32_16x16x32_bf16 v[78:81], v[196:199], v[236:239], v[78:81]
	v_mfma_f32_16x16x32_bf16 v[74:77], v[204:207], v[236:239], v[74:77]
	s_setprio 0
	s_setprio 1
	v_mfma_f32_16x16x32_bf16 v[126:129], v[200:203], v[216:219], v[126:129]
	v_mfma_f32_16x16x32_bf16 v[122:125], v[208:211], v[216:219], v[122:125]
	v_mfma_f32_16x16x32_bf16 v[110:113], v[200:203], v[224:227], v[110:113]
	v_mfma_f32_16x16x32_bf16 v[106:109], v[208:211], v[224:227], v[106:109]
	v_mfma_f32_16x16x32_bf16 v[94:97], v[200:203], v[232:235], v[94:97]
	v_mfma_f32_16x16x32_bf16 v[90:93], v[208:211], v[232:235], v[90:93]
	v_mfma_f32_16x16x32_bf16 v[78:81], v[200:203], v[240:243], v[78:81]
	v_mfma_f32_16x16x32_bf16 v[74:77], v[208:211], v[240:243], v[74:77]
	s_setprio 0
	s_barrier
	s_mov_b32 m0, s66
	v_lshl_add_u64 v[142:143], v[142:143], 0, s[24:25]
	ds_read_b128 v[212:215], v141 offset:49152
	ds_read_b128 v[216:219], v141 offset:50176
	ds_read_b128 v[220:223], v141 offset:51200
	ds_read_b128 v[224:227], v141 offset:52224
	ds_read_b128 v[228:231], v141 offset:53248
	ds_read_b128 v[232:235], v141 offset:54272
	ds_read_b128 v[236:239], v141 offset:55296
	ds_read_b128 v[240:243], v141 offset:56320
	global_load_lds_dwordx4 v[142:143], off
	v_lshl_add_u64 v[142:143], v[154:155], 0, s[24:25]
	s_mov_b32 m0, s63
	s_nop 0
	global_load_lds_dwordx4 v[142:143], off
	v_lshl_add_u64 v[142:143], s[46:47], 0, v[0:1]
	s_mov_b32 m0, s65
	s_nop 0
	global_load_lds_dwordx4 v[142:143], off
	v_lshl_add_u64 v[142:143], s[46:47], 0, v[38:39]
	s_mov_b32 m0, s20
	s_nop 0
	global_load_lds_dwordx4 v[142:143], off
	v_lshl_add_u64 v[142:143], v[244:245], 0, s[24:25]
	s_mov_b32 m0, s19
	s_nop 0
	global_load_lds_dwordx4 v[142:143], off
	v_lshl_add_u64 v[142:143], v[246:247], 0, s[24:25]
	s_mov_b32 m0, s62
	s_nop 0
	global_load_lds_dwordx4 v[142:143], off
	s_waitcnt vmcnt(8)
	s_waitcnt lgkmcnt(0)
	s_barrier
	s_setprio 1
	s_waitcnt lgkmcnt(0)
	v_mfma_f32_16x16x32_bf16 v[70:73], v[146:149], v[212:215], v[70:73]
	v_mfma_f32_16x16x32_bf16 v[66:69], v[158:161], v[212:215], v[66:69]
	v_mfma_f32_16x16x32_bf16 v[54:57], v[146:149], v[220:223], v[54:57]
	v_mfma_f32_16x16x32_bf16 v[50:53], v[158:161], v[220:223], v[50:53]
	v_mfma_f32_16x16x32_bf16 v[34:37], v[146:149], v[228:231], v[34:37]
	v_mfma_f32_16x16x32_bf16 v[30:33], v[158:161], v[228:231], v[30:33]
	v_mfma_f32_16x16x32_bf16 v[14:17], v[146:149], v[236:239], v[14:17]
	v_mfma_f32_16x16x32_bf16 v[10:13], v[158:161], v[236:239], v[10:13]
	s_setprio 0
	s_setprio 1
	v_mfma_f32_16x16x32_bf16 v[70:73], v[150:153], v[216:219], v[70:73]
	v_mfma_f32_16x16x32_bf16 v[66:69], v[162:165], v[216:219], v[66:69]
	v_mfma_f32_16x16x32_bf16 v[54:57], v[150:153], v[224:227], v[54:57]
	v_mfma_f32_16x16x32_bf16 v[50:53], v[162:165], v[224:227], v[50:53]
	v_mfma_f32_16x16x32_bf16 v[34:37], v[150:153], v[232:235], v[34:37]
	v_mfma_f32_16x16x32_bf16 v[30:33], v[162:165], v[232:235], v[30:33]
	v_mfma_f32_16x16x32_bf16 v[14:17], v[150:153], v[240:243], v[14:17]
	v_mfma_f32_16x16x32_bf16 v[10:13], v[162:165], v[240:243], v[10:13]
	s_setprio 0
	s_setprio 1
	v_mfma_f32_16x16x32_bf16 v[62:65], v[196:199], v[212:215], v[62:65]
	v_mfma_f32_16x16x32_bf16 v[58:61], v[204:207], v[212:215], v[58:61]
	v_mfma_f32_16x16x32_bf16 v[46:49], v[196:199], v[220:223], v[46:49]
	v_mfma_f32_16x16x32_bf16 v[42:45], v[204:207], v[220:223], v[42:45]
	v_mfma_f32_16x16x32_bf16 v[22:25], v[196:199], v[228:231], v[22:25]
	v_mfma_f32_16x16x32_bf16 v[18:21], v[204:207], v[228:231], v[18:21]
	v_mfma_f32_16x16x32_bf16 v[6:9], v[196:199], v[236:239], v[6:9]
	v_mfma_f32_16x16x32_bf16 v[2:5], v[204:207], v[236:239], v[2:5]
	s_setprio 0
	s_setprio 1
	v_mfma_f32_16x16x32_bf16 v[62:65], v[200:203], v[216:219], v[62:65]
	v_mfma_f32_16x16x32_bf16 v[58:61], v[208:211], v[216:219], v[58:61]
	v_mfma_f32_16x16x32_bf16 v[46:49], v[200:203], v[224:227], v[46:49]
	v_mfma_f32_16x16x32_bf16 v[42:45], v[208:211], v[224:227], v[42:45]
	v_mfma_f32_16x16x32_bf16 v[22:25], v[200:203], v[232:235], v[22:25]
	v_mfma_f32_16x16x32_bf16 v[18:21], v[208:211], v[232:235], v[18:21]
	v_mfma_f32_16x16x32_bf16 v[6:9], v[200:203], v[240:243], v[6:9]
	v_mfma_f32_16x16x32_bf16 v[2:5], v[208:211], v[240:243], v[2:5]
	s_setprio 0
	s_barrier
	s_andn2_b64 vcc, exec, s[44:45]
	s_mov_b64 s[46:47], -1
	s_mov_b64 s[44:45], 0
	s_movk_i32 s20, 0x100
	s_cbranch_vccz .LBB0_476
	s_waitcnt vmcnt(0)
	s_cmpk_lt_u32 s10, 0x100
	s_cbranch_scc0 .LBB0_479
	s_barrier

.LBB0_482:
	s_add_i32 s48, s20, 0x100
	s_and_b64 s[46:47], s[46:47], exec
	s_cselect_b32 s47, 0, s48
	s_cselect_b32 s46, 0, 0
	s_add_u32 s50, s2, s47
	s_addc_u32 s51, s3, s46
	s_add_u32 s52, s40, s47
	s_addc_u32 s53, s41, s46
	s_add_u32 s66, s42, s20
	s_addc_u32 s67, s43, 0
	s_add_i32 s65, s4, s10
	s_add_i32 m0, s11, 0xc000
	s_add_i32 s63, s11, 0xe000
	s_add_i32 s70, s65, 0x2000
	s_add_u32 s54, s52, 0x20200
	v_add_u32_e32 v142, s4, v40
	s_addc_u32 s55, s53, 0
	s_add_i32 s82, s5, s10
	ds_read_b128 v[138:141], v142
	ds_read_b128 v[146:149], v142 offset:1024
	ds_read_b128 v[150:153], v142 offset:2048
	ds_read_b128 v[158:161], v142 offset:3072
	v_add_u32_e32 v142, s5, v40
	s_add_i32 s83, s82, 0x2000
	ds_read_b128 v[162:165], v142
	ds_read_b128 v[196:199], v142 offset:1024
	ds_read_b128 v[200:203], v142 offset:2048
	ds_read_b128 v[204:207], v142 offset:3072
	s_add_u32 s48, s50, 0x10000
	s_addc_u32 s49, s51, 0
	s_add_i32 s62, s6, s10
	s_add_i32 s56, s62, 0x2000
	s_add_u32 s46, s52, 0x20280
	s_addc_u32 s47, s53, 0
	s_add_i32 s57, s7, s10
	s_add_i32 s20, s57, 0x2000
	v_lshl_add_u64 v[142:143], s[66:67], 0, v[26:27]
	v_lshl_add_u64 v[142:143], v[142:143], 0, s[24:25]
	ds_read_b128 v[208:211], v41
	ds_read_b128 v[212:215], v41 offset:1024
	ds_read_b128 v[216:219], v41 offset:2048
	ds_read_b128 v[220:223], v41 offset:3072
	ds_read_b128 v[224:227], v41 offset:4096
	ds_read_b128 v[228:231], v41 offset:5120
	ds_read_b128 v[232:235], v41 offset:6144
	ds_read_b128 v[236:239], v41 offset:7168
	global_load_lds_dwordx4 v[142:143], off
	v_lshl_add_u64 v[142:143], s[66:67], 0, v[28:29]
	v_lshl_add_u64 v[142:143], v[142:143], 0, s[24:25]
	s_mov_b32 m0, s63
	s_nop 0
	global_load_lds_dwordx4 v[142:143], off
	s_waitcnt vmcnt(8)
	s_waitcnt lgkmcnt(0)
	s_barrier
	s_setprio 1
	s_waitcnt lgkmcnt(0)
	v_mfma_f32_16x16x32_bf16 v[134:137], v[138:141], v[208:211], v[134:137]
	v_mfma_f32_16x16x32_bf16 v[130:133], v[150:153], v[208:211], v[130:133]
	v_mfma_f32_16x16x32_bf16 v[118:121], v[138:141], v[216:219], v[118:121]
	v_mfma_f32_16x16x32_bf16 v[114:117], v[150:153], v[216:219], v[114:117]
	v_mfma_f32_16x16x32_bf16 v[102:105], v[138:141], v[224:227], v[102:105]
	v_mfma_f32_16x16x32_bf16 v[98:101], v[150:153], v[224:227], v[98:101]
	v_mfma_f32_16x16x32_bf16 v[86:89], v[138:141], v[232:235], v[86:89]
	v_mfma_f32_16x16x32_bf16 v[82:85], v[150:153], v[232:235], v[82:85]
	s_setprio 0
	s_setprio 1
	v_mfma_f32_16x16x32_bf16 v[134:137], v[146:149], v[212:215], v[134:137]
	v_mfma_f32_16x16x32_bf16 v[130:133], v[158:161], v[212:215], v[130:133]
	v_mfma_f32_16x16x32_bf16 v[118:121], v[146:149], v[220:223], v[118:121]
	v_mfma_f32_16x16x32_bf16 v[114:117], v[158:161], v[220:223], v[114:117]
	v_mfma_f32_16x16x32_bf16 v[102:105], v[146:149], v[228:231], v[102:105]
	v_mfma_f32_16x16x32_bf16 v[98:101], v[158:161], v[228:231], v[98:101]
	v_mfma_f32_16x16x32_bf16 v[86:89], v[146:149], v[236:239], v[86:89]
	v_mfma_f32_16x16x32_bf16 v[82:85], v[158:161], v[236:239], v[82:85]
	s_setprio 0
	s_setprio 1
	v_mfma_f32_16x16x32_bf16 v[126:129], v[162:165], v[208:211], v[126:129]
	v_mfma_f32_16x16x32_bf16 v[122:125], v[200:203], v[208:211], v[122:125]
	v_mfma_f32_16x16x32_bf16 v[110:113], v[162:165], v[216:219], v[110:113]
	v_mfma_f32_16x16x32_bf16 v[106:109], v[200:203], v[216:219], v[106:109]
	v_mfma_f32_16x16x32_bf16 v[94:97], v[162:165], v[224:227], v[94:97]
	v_mfma_f32_16x16x32_bf16 v[90:93], v[200:203], v[224:227], v[90:93]
	v_mfma_f32_16x16x32_bf16 v[78:81], v[162:165], v[232:235], v[78:81]
	v_mfma_f32_16x16x32_bf16 v[74:77], v[200:203], v[232:235], v[74:77]
	s_setprio 0
	s_setprio 1
	v_mfma_f32_16x16x32_bf16 v[126:129], v[196:199], v[212:215], v[126:129]
	v_mfma_f32_16x16x32_bf16 v[122:125], v[204:207], v[212:215], v[122:125]
	v_mfma_f32_16x16x32_bf16 v[110:113], v[196:199], v[220:223], v[110:113]
	v_mfma_f32_16x16x32_bf16 v[106:109], v[204:207], v[220:223], v[106:109]
	v_mfma_f32_16x16x32_bf16 v[94:97], v[196:199], v[228:231], v[94:97]
	v_mfma_f32_16x16x32_bf16 v[90:93], v[204:207], v[228:231], v[90:93]
	v_mfma_f32_16x16x32_bf16 v[78:81], v[196:199], v[236:239], v[78:81]
	v_mfma_f32_16x16x32_bf16 v[74:77], v[204:207], v[236:239], v[74:77]
	s_setprio 0
	s_barrier
	v_lshl_add_u64 v[142:143], s[52:53], 0, v[0:1]
	s_mov_b32 m0, s65
	v_lshl_add_u64 v[154:155], v[142:143], 0, s[84:85]
	ds_read_b128 v[208:211], v41 offset:16384
	ds_read_b128 v[212:215], v41 offset:17408
	ds_read_b128 v[216:219], v41 offset:18432
	ds_read_b128 v[220:223], v41 offset:19456
	ds_read_b128 v[224:227], v41 offset:20480
	ds_read_b128 v[228:231], v41 offset:21504
	ds_read_b128 v[232:235], v41 offset:22528
	ds_read_b128 v[236:239], v41 offset:23552
	global_load_lds_dwordx4 v[154:155], off
	v_lshl_add_u64 v[154:155], s[52:53], 0, v[38:39]
	v_lshl_add_u64 v[240:241], v[154:155], 0, s[84:85]
	s_mov_b32 m0, s70
	v_lshl_add_u64 v[242:243], s[50:51], 0, v[28:29]
	global_load_lds_dwordx4 v[240:241], off
	v_lshl_add_u64 v[240:241], s[54:55], 0, v[0:1]
	s_mov_b32 m0, s82
	s_nop 0
	global_load_lds_dwordx4 v[240:241], off
	v_lshl_add_u64 v[240:241], s[54:55], 0, v[38:39]
	s_mov_b32 m0, s83
	s_nop 0
	global_load_lds_dwordx4 v[240:241], off
	v_lshl_add_u64 v[240:241], s[50:51], 0, v[26:27]
	s_mov_b32 m0, s11
	s_nop 0
	global_load_lds_dwordx4 v[240:241], off
	s_mov_b32 m0, s12
	s_nop 0
	global_load_lds_dwordx4 v[242:243], off
	s_waitcnt vmcnt(8)
	s_waitcnt lgkmcnt(0)
	s_barrier
	s_setprio 1
	s_waitcnt lgkmcnt(0)
	v_mfma_f32_16x16x32_bf16 v[70:73], v[138:141], v[208:211], v[70:73]
	v_mfma_f32_16x16x32_bf16 v[66:69], v[150:153], v[208:211], v[66:69]
	v_mfma_f32_16x16x32_bf16 v[54:57], v[138:141], v[216:219], v[54:57]
	v_mfma_f32_16x16x32_bf16 v[50:53], v[150:153], v[216:219], v[50:53]
	v_mfma_f32_16x16x32_bf16 v[34:37], v[138:141], v[224:227], v[34:37]
	v_mfma_f32_16x16x32_bf16 v[30:33], v[150:153], v[224:227], v[30:33]
	v_mfma_f32_16x16x32_bf16 v[14:17], v[138:141], v[232:235], v[14:17]
	v_mfma_f32_16x16x32_bf16 v[10:13], v[150:153], v[232:235], v[10:13]
	s_setprio 0
	s_setprio 1
	v_mfma_f32_16x16x32_bf16 v[70:73], v[146:149], v[212:215], v[70:73]
	v_mfma_f32_16x16x32_bf16 v[66:69], v[158:161], v[212:215], v[66:69]
	v_mfma_f32_16x16x32_bf16 v[54:57], v[146:149], v[220:223], v[54:57]
	v_mfma_f32_16x16x32_bf16 v[50:53], v[158:161], v[220:223], v[50:53]
	v_mfma_f32_16x16x32_bf16 v[34:37], v[146:149], v[228:231], v[34:37]
	v_mfma_f32_16x16x32_bf16 v[30:33], v[158:161], v[228:231], v[30:33]
	v_mfma_f32_16x16x32_bf16 v[14:17], v[146:149], v[236:239], v[14:17]
	v_mfma_f32_16x16x32_bf16 v[10:13], v[158:161], v[236:239], v[10:13]
	s_setprio 0
	s_setprio 1
	v_mfma_f32_16x16x32_bf16 v[62:65], v[162:165], v[208:211], v[62:65]
	v_mfma_f32_16x16x32_bf16 v[58:61], v[200:203], v[208:211], v[58:61]
	v_mfma_f32_16x16x32_bf16 v[46:49], v[162:165], v[216:219], v[46:49]
	v_mfma_f32_16x16x32_bf16 v[42:45], v[200:203], v[216:219], v[42:45]
	v_mfma_f32_16x16x32_bf16 v[22:25], v[162:165], v[224:227], v[22:25]
	v_mfma_f32_16x16x32_bf16 v[18:21], v[200:203], v[224:227], v[18:21]
	v_mfma_f32_16x16x32_bf16 v[6:9], v[162:165], v[232:235], v[6:9]
	v_mfma_f32_16x16x32_bf16 v[2:5], v[200:203], v[232:235], v[2:5]
	s_setprio 0
	s_setprio 1
	v_mfma_f32_16x16x32_bf16 v[62:65], v[196:199], v[212:215], v[62:65]
	v_mfma_f32_16x16x32_bf16 v[58:61], v[204:207], v[212:215], v[58:61]
	v_mfma_f32_16x16x32_bf16 v[46:49], v[196:199], v[220:223], v[46:49]
	v_mfma_f32_16x16x32_bf16 v[42:45], v[204:207], v[220:223], v[42:45]
	v_mfma_f32_16x16x32_bf16 v[22:25], v[196:199], v[228:231], v[22:25]
	v_mfma_f32_16x16x32_bf16 v[18:21], v[204:207], v[228:231], v[18:21]
	v_mfma_f32_16x16x32_bf16 v[6:9], v[196:199], v[236:239], v[6:9]
	v_mfma_f32_16x16x32_bf16 v[2:5], v[204:207], v[236:239], v[2:5]
	s_setprio 0
	s_barrier
	v_add_u32_e32 v145, s6, v40
	ds_read_b128 v[138:141], v145
	ds_read_b128 v[146:149], v145 offset:1024
	ds_read_b128 v[150:153], v145 offset:2048
	ds_read_b128 v[158:161], v145 offset:3072
	v_add_u32_e32 v145, s7, v40
	ds_read_b128 v[162:165], v145
	ds_read_b128 v[196:199], v145 offset:1024
	ds_read_b128 v[200:203], v145 offset:2048
	ds_read_b128 v[204:207], v145 offset:3072
	s_mov_b32 m0, s13
	v_lshl_add_u64 v[244:245], s[48:49], 0, v[26:27]
	ds_read_b128 v[208:211], v41 offset:32768
	ds_read_b128 v[212:215], v41 offset:33792
	ds_read_b128 v[216:219], v41 offset:34816
	ds_read_b128 v[220:223], v41 offset:35840
	ds_read_b128 v[224:227], v41 offset:36864
	ds_read_b128 v[228:231], v41 offset:37888
	ds_read_b128 v[232:235], v41 offset:38912
	ds_read_b128 v[236:239], v41 offset:39936
	global_load_lds_dwordx4 v[244:245], off
	v_lshl_add_u64 v[244:245], s[48:49], 0, v[28:29]
	s_mov_b32 m0, s16
	s_mov_b64 s[48:49], 0x280
	global_load_lds_dwordx4 v[244:245], off
	s_waitcnt vmcnt(8)
	s_waitcnt lgkmcnt(0)
	s_barrier
	s_setprio 1
	s_waitcnt lgkmcnt(0)
	v_mfma_f32_16x16x32_bf16 v[134:137], v[138:141], v[208:211], v[134:137]
	v_mfma_f32_16x16x32_bf16 v[130:133], v[150:153], v[208:211], v[130:133]
	v_mfma_f32_16x16x32_bf16 v[118:121], v[138:141], v[216:219], v[118:121]
	v_mfma_f32_16x16x32_bf16 v[114:117], v[150:153], v[216:219], v[114:117]
	v_mfma_f32_16x16x32_bf16 v[102:105], v[138:141], v[224:227], v[102:105]
	v_mfma_f32_16x16x32_bf16 v[98:101], v[150:153], v[224:227], v[98:101]
	v_mfma_f32_16x16x32_bf16 v[86:89], v[138:141], v[232:235], v[86:89]
	v_mfma_f32_16x16x32_bf16 v[82:85], v[150:153], v[232:235], v[82:85]
	s_setprio 0
	s_setprio 1
	v_mfma_f32_16x16x32_bf16 v[134:137], v[146:149], v[212:215], v[134:137]
	v_mfma_f32_16x16x32_bf16 v[130:133], v[158:161], v[212:215], v[130:133]
	v_mfma_f32_16x16x32_bf16 v[118:121], v[146:149], v[220:223], v[118:121]
	v_mfma_f32_16x16x32_bf16 v[114:117], v[158:161], v[220:223], v[114:117]
	v_mfma_f32_16x16x32_bf16 v[102:105], v[146:149], v[228:231], v[102:105]
	v_mfma_f32_16x16x32_bf16 v[98:101], v[158:161], v[228:231], v[98:101]
	v_mfma_f32_16x16x32_bf16 v[86:89], v[146:149], v[236:239], v[86:89]
	v_mfma_f32_16x16x32_bf16 v[82:85], v[158:161], v[236:239], v[82:85]
	s_setprio 0
	s_setprio 1
	v_mfma_f32_16x16x32_bf16 v[126:129], v[162:165], v[208:211], v[126:129]
	v_mfma_f32_16x16x32_bf16 v[122:125], v[200:203], v[208:211], v[122:125]
	v_mfma_f32_16x16x32_bf16 v[110:113], v[162:165], v[216:219], v[110:113]
	v_mfma_f32_16x16x32_bf16 v[106:109], v[200:203], v[216:219], v[106:109]
	v_mfma_f32_16x16x32_bf16 v[94:97], v[162:165], v[224:227], v[94:97]
	v_mfma_f32_16x16x32_bf16 v[90:93], v[200:203], v[224:227], v[90:93]
	v_mfma_f32_16x16x32_bf16 v[78:81], v[162:165], v[232:235], v[78:81]
	v_mfma_f32_16x16x32_bf16 v[74:77], v[200:203], v[232:235], v[74:77]
	s_setprio 0
	s_setprio 1
	v_mfma_f32_16x16x32_bf16 v[126:129], v[196:199], v[212:215], v[126:129]
	v_mfma_f32_16x16x32_bf16 v[122:125], v[204:207], v[212:215], v[122:125]
	v_mfma_f32_16x16x32_bf16 v[110:113], v[196:199], v[220:223], v[110:113]
	v_mfma_f32_16x16x32_bf16 v[106:109], v[204:207], v[220:223], v[106:109]
	v_mfma_f32_16x16x32_bf16 v[94:97], v[196:199], v[228:231], v[94:97]
	v_mfma_f32_16x16x32_bf16 v[90:93], v[204:207], v[228:231], v[90:93]
	v_mfma_f32_16x16x32_bf16 v[78:81], v[196:199], v[236:239], v[78:81]
	v_mfma_f32_16x16x32_bf16 v[74:77], v[204:207], v[236:239], v[74:77]
	s_setprio 0
	s_barrier
	s_mov_b32 m0, s62
	v_lshl_add_u64 v[142:143], v[142:143], 0, s[48:49]
	ds_read_b128 v[208:211], v41 offset:49152
	ds_read_b128 v[212:215], v41 offset:50176
	ds_read_b128 v[216:219], v41 offset:51200
	ds_read_b128 v[220:223], v41 offset:52224
	ds_read_b128 v[224:227], v41 offset:53248
	ds_read_b128 v[228:231], v41 offset:54272
	ds_read_b128 v[232:235], v41 offset:55296
	ds_read_b128 v[236:239], v41 offset:56320
	global_load_lds_dwordx4 v[142:143], off
	v_lshl_add_u64 v[142:143], v[154:155], 0, s[48:49]
	s_mov_b32 m0, s56
	s_nop 0
	global_load_lds_dwordx4 v[142:143], off
	v_lshl_add_u64 v[142:143], s[46:47], 0, v[0:1]
	s_mov_b32 m0, s57
	s_nop 0
	global_load_lds_dwordx4 v[142:143], off
	v_lshl_add_u64 v[142:143], s[46:47], 0, v[38:39]
	s_mov_b32 m0, s20
	s_nop 0
	global_load_lds_dwordx4 v[142:143], off
	v_lshl_add_u64 v[142:143], v[240:241], 0, s[24:25]
	s_mov_b32 m0, s17
	s_nop 0
	global_load_lds_dwordx4 v[142:143], off
	v_lshl_add_u64 v[142:143], v[242:243], 0, s[24:25]
	s_mov_b32 m0, s19
	s_nop 0
	global_load_lds_dwordx4 v[142:143], off
	s_waitcnt vmcnt(8)
	s_waitcnt lgkmcnt(0)
	s_barrier
	s_setprio 1
	s_waitcnt lgkmcnt(0)
	v_mfma_f32_16x16x32_bf16 v[70:73], v[138:141], v[208:211], v[70:73]
	v_mfma_f32_16x16x32_bf16 v[66:69], v[150:153], v[208:211], v[66:69]
	v_mfma_f32_16x16x32_bf16 v[54:57], v[138:141], v[216:219], v[54:57]
	v_mfma_f32_16x16x32_bf16 v[50:53], v[150:153], v[216:219], v[50:53]
	v_mfma_f32_16x16x32_bf16 v[34:37], v[138:141], v[224:227], v[34:37]
	v_mfma_f32_16x16x32_bf16 v[30:33], v[150:153], v[224:227], v[30:33]
	v_mfma_f32_16x16x32_bf16 v[14:17], v[138:141], v[232:235], v[14:17]
	v_mfma_f32_16x16x32_bf16 v[10:13], v[150:153], v[232:235], v[10:13]
	s_setprio 0
	s_setprio 1
	v_mfma_f32_16x16x32_bf16 v[70:73], v[146:149], v[212:215], v[70:73]
	v_mfma_f32_16x16x32_bf16 v[66:69], v[158:161], v[212:215], v[66:69]
	v_mfma_f32_16x16x32_bf16 v[54:57], v[146:149], v[220:223], v[54:57]
	v_mfma_f32_16x16x32_bf16 v[50:53], v[158:161], v[220:223], v[50:53]
	v_mfma_f32_16x16x32_bf16 v[34:37], v[146:149], v[228:231], v[34:37]
	v_mfma_f32_16x16x32_bf16 v[30:33], v[158:161], v[228:231], v[30:33]
	v_mfma_f32_16x16x32_bf16 v[14:17], v[146:149], v[236:239], v[14:17]
	v_mfma_f32_16x16x32_bf16 v[10:13], v[158:161], v[236:239], v[10:13]
	s_setprio 0
	s_setprio 1
	v_mfma_f32_16x16x32_bf16 v[62:65], v[162:165], v[208:211], v[62:65]
	v_mfma_f32_16x16x32_bf16 v[58:61], v[200:203], v[208:211], v[58:61]
	v_mfma_f32_16x16x32_bf16 v[46:49], v[162:165], v[216:219], v[46:49]
	v_mfma_f32_16x16x32_bf16 v[42:45], v[200:203], v[216:219], v[42:45]
	v_mfma_f32_16x16x32_bf16 v[22:25], v[162:165], v[224:227], v[22:25]
	v_mfma_f32_16x16x32_bf16 v[18:21], v[200:203], v[224:227], v[18:21]
	v_mfma_f32_16x16x32_bf16 v[6:9], v[162:165], v[232:235], v[6:9]
	v_mfma_f32_16x16x32_bf16 v[2:5], v[200:203], v[232:235], v[2:5]
	s_setprio 0
	s_setprio 1
	v_mfma_f32_16x16x32_bf16 v[62:65], v[196:199], v[212:215], v[62:65]
	v_mfma_f32_16x16x32_bf16 v[58:61], v[204:207], v[212:215], v[58:61]
	v_mfma_f32_16x16x32_bf16 v[46:49], v[196:199], v[220:223], v[46:49]
	v_mfma_f32_16x16x32_bf16 v[42:45], v[204:207], v[220:223], v[42:45]
	v_mfma_f32_16x16x32_bf16 v[22:25], v[196:199], v[228:231], v[22:25]
	v_mfma_f32_16x16x32_bf16 v[18:21], v[204:207], v[228:231], v[18:21]
	v_mfma_f32_16x16x32_bf16 v[6:9], v[196:199], v[236:239], v[6:9]
	v_mfma_f32_16x16x32_bf16 v[2:5], v[204:207], v[236:239], v[2:5]
	s_setprio 0
	s_barrier
	s_andn2_b64 vcc, exec, s[44:45]
	s_mov_b64 s[46:47], -1
	s_mov_b64 s[44:45], 0
	s_movk_i32 s20, 0x100
	s_cbranch_vccz .LBB0_482
	s_waitcnt vmcnt(0)
	s_cmpk_lt_u32 s9, 0x100
	s_movk_i32 s83, 0x2000
	s_movk_i32 s86, 0x1fff
	s_cbranch_scc0 .LBB0_485
	s_barrier

.LBB0_1254:
	s_add_i32 s44, s20, 0x100
	s_and_b64 s[42:43], s[42:43], exec
	s_cselect_b32 s43, 0, s44
	s_cselect_b32 s42, 0, 0
	s_add_u32 s46, s2, s43
	s_addc_u32 s47, s3, s42
	s_add_i32 s70, 0, 0x10000
	s_add_u32 s52, s8, s43
	s_addc_u32 s53, s9, s42
	s_add_i32 s43, 0, 0x14000
	s_add_u32 s56, s18, s20
	s_addc_u32 s57, s19, 0
	s_add_i32 s67, s70, s10
	s_add_i32 m0, s11, 0xc000
	s_add_i32 s82, s11, 0xe000
	s_add_i32 s63, s67, 0x2000
	v_add_u32_e32 v139, s70, v137
	s_add_u32 s54, s52, 0x10000
	ds_read_b128 v[140:143], v139
	ds_read_b128 v[144:147], v139 offset:1024
	ds_read_b128 v[148:151], v139 offset:2048
	ds_read_b128 v[152:155], v139 offset:3072
	v_add_u32_e32 v139, s43, v137
	s_addc_u32 s55, s53, 0
	s_add_i32 s66, s43, s10
	ds_read_b128 v[158:161], v139
	ds_read_b128 v[162:165], v139 offset:1024
	ds_read_b128 v[196:199], v139 offset:2048
	ds_read_b128 v[200:203], v139 offset:3072
	s_add_i32 s65, s66, 0x2000
	s_add_i32 s62, 0, 0x18000
	s_add_i32 s59, 0, 0x1c000
	s_add_u32 s44, s46, 0x10000
	s_addc_u32 s45, s47, 0
	s_add_i32 s58, s62, s10
	s_add_i32 s20, s58, 0x2000
	s_add_u32 s42, s52, 0x10080
	s_addc_u32 s43, s53, 0
	s_add_i32 s84, s59, s10
	s_add_i32 s70, s84, 0x2000
	v_lshl_add_u64 v[236:237], s[56:57], 0, v[130:131]
	v_lshl_add_u64 v[236:237], v[236:237], 0, s[24:25]
	ds_read_b128 v[204:207], v138
	ds_read_b128 v[208:211], v138 offset:1024
	ds_read_b128 v[212:215], v138 offset:2048
	ds_read_b128 v[216:219], v138 offset:3072
	ds_read_b128 v[220:223], v138 offset:4096
	ds_read_b128 v[224:227], v138 offset:5120
	ds_read_b128 v[228:231], v138 offset:6144
	ds_read_b128 v[232:235], v138 offset:7168
	global_load_lds_dwordx4 v[236:237], off
	v_lshl_add_u64 v[236:237], s[56:57], 0, v[132:133]
	v_lshl_add_u64 v[236:237], v[236:237], 0, s[24:25]
	s_mov_b32 m0, s82
	s_nop 0
	global_load_lds_dwordx4 v[236:237], off
	s_waitcnt vmcnt(8)
	s_waitcnt lgkmcnt(0)
	s_barrier
	s_setprio 1
	s_waitcnt lgkmcnt(0)
	v_mfma_f32_16x16x32_bf16 v[126:129], v[140:143], v[204:207], v[126:129]
	v_mfma_f32_16x16x32_bf16 v[122:125], v[148:151], v[204:207], v[122:125]
	v_mfma_f32_16x16x32_bf16 v[118:121], v[140:143], v[212:215], v[118:121]
	v_mfma_f32_16x16x32_bf16 v[114:117], v[148:151], v[212:215], v[114:117]
	v_mfma_f32_16x16x32_bf16 v[102:105], v[140:143], v[220:223], v[102:105]
	v_mfma_f32_16x16x32_bf16 v[98:101], v[148:151], v[220:223], v[98:101]
	v_mfma_f32_16x16x32_bf16 v[86:89], v[140:143], v[228:231], v[86:89]
	v_mfma_f32_16x16x32_bf16 v[82:85], v[148:151], v[228:231], v[82:85]
	s_setprio 0
	s_setprio 1
	v_mfma_f32_16x16x32_bf16 v[126:129], v[144:147], v[208:211], v[126:129]
	v_mfma_f32_16x16x32_bf16 v[122:125], v[152:155], v[208:211], v[122:125]
	v_mfma_f32_16x16x32_bf16 v[118:121], v[144:147], v[216:219], v[118:121]
	v_mfma_f32_16x16x32_bf16 v[114:117], v[152:155], v[216:219], v[114:117]
	v_mfma_f32_16x16x32_bf16 v[102:105], v[144:147], v[224:227], v[102:105]
	v_mfma_f32_16x16x32_bf16 v[98:101], v[152:155], v[224:227], v[98:101]
	v_mfma_f32_16x16x32_bf16 v[86:89], v[144:147], v[232:235], v[86:89]
	v_mfma_f32_16x16x32_bf16 v[82:85], v[152:155], v[232:235], v[82:85]
	s_setprio 0
	s_setprio 1
	v_mfma_f32_16x16x32_bf16 v[110:113], v[158:161], v[204:207], v[110:113]
	v_mfma_f32_16x16x32_bf16 v[106:109], v[196:199], v[204:207], v[106:109]
	v_mfma_f32_16x16x32_bf16 v[94:97], v[158:161], v[212:215], v[94:97]
	v_mfma_f32_16x16x32_bf16 v[90:93], v[196:199], v[212:215], v[90:93]
	v_mfma_f32_16x16x32_bf16 v[78:81], v[158:161], v[220:223], v[78:81]
	v_mfma_f32_16x16x32_bf16 v[74:77], v[196:199], v[220:223], v[74:77]
	v_mfma_f32_16x16x32_bf16 v[70:73], v[158:161], v[228:231], v[70:73]
	v_mfma_f32_16x16x32_bf16 v[66:69], v[196:199], v[228:231], v[66:69]
	s_setprio 0
	s_setprio 1
	v_mfma_f32_16x16x32_bf16 v[110:113], v[162:165], v[208:211], v[110:113]
	v_mfma_f32_16x16x32_bf16 v[106:109], v[200:203], v[208:211], v[106:109]
	v_mfma_f32_16x16x32_bf16 v[94:97], v[162:165], v[216:219], v[94:97]
	v_mfma_f32_16x16x32_bf16 v[90:93], v[200:203], v[216:219], v[90:93]
	v_mfma_f32_16x16x32_bf16 v[78:81], v[162:165], v[224:227], v[78:81]
	v_mfma_f32_16x16x32_bf16 v[74:77], v[200:203], v[224:227], v[74:77]
	v_mfma_f32_16x16x32_bf16 v[70:73], v[162:165], v[232:235], v[70:73]
	v_mfma_f32_16x16x32_bf16 v[66:69], v[200:203], v[232:235], v[66:69]
	s_setprio 0
	s_barrier
	s_mov_b32 m0, s67
	v_lshl_add_u64 v[236:237], s[52:53], 0, v[0:1]
	ds_read_b128 v[204:207], v138 offset:16384
	ds_read_b128 v[208:211], v138 offset:17408
	ds_read_b128 v[212:215], v138 offset:18432
	ds_read_b128 v[216:219], v138 offset:19456
	ds_read_b128 v[220:223], v138 offset:20480
	ds_read_b128 v[224:227], v138 offset:21504
	ds_read_b128 v[228:231], v138 offset:22528
	ds_read_b128 v[232:235], v138 offset:23552
	global_load_lds_dwordx4 v[236:237], off
	v_lshl_add_u64 v[238:239], s[52:53], 0, v[134:135]
	s_mov_b32 m0, s63
	v_lshl_add_u64 v[240:241], s[54:55], 0, v[0:1]
	global_load_lds_dwordx4 v[238:239], off
	s_mov_b32 m0, s66
	v_lshl_add_u64 v[242:243], s[46:47], 0, v[132:133]
	global_load_lds_dwordx4 v[240:241], off
	v_lshl_add_u64 v[240:241], s[54:55], 0, v[134:135]
	s_mov_b32 m0, s65
	s_nop 0
	global_load_lds_dwordx4 v[240:241], off
	v_lshl_add_u64 v[240:241], s[46:47], 0, v[130:131]
	s_mov_b32 m0, s11
	s_nop 0
	global_load_lds_dwordx4 v[240:241], off
	s_mov_b32 m0, s12
	s_nop 0
	global_load_lds_dwordx4 v[242:243], off
	s_waitcnt vmcnt(8)
	s_waitcnt lgkmcnt(0)
	s_barrier
	s_setprio 1
	s_waitcnt lgkmcnt(0)
	v_mfma_f32_16x16x32_bf16 v[62:65], v[140:143], v[204:207], v[62:65]
	v_mfma_f32_16x16x32_bf16 v[58:61], v[148:151], v[204:207], v[58:61]
	v_mfma_f32_16x16x32_bf16 v[54:57], v[140:143], v[212:215], v[54:57]
	v_mfma_f32_16x16x32_bf16 v[50:53], v[148:151], v[212:215], v[50:53]
	v_mfma_f32_16x16x32_bf16 v[38:41], v[140:143], v[220:223], v[38:41]
	v_mfma_f32_16x16x32_bf16 v[34:37], v[148:151], v[220:223], v[34:37]
	v_mfma_f32_16x16x32_bf16 v[22:25], v[140:143], v[228:231], v[22:25]
	v_mfma_f32_16x16x32_bf16 v[18:21], v[148:151], v[228:231], v[18:21]
	s_setprio 0
	s_setprio 1
	v_mfma_f32_16x16x32_bf16 v[62:65], v[144:147], v[208:211], v[62:65]
	v_mfma_f32_16x16x32_bf16 v[58:61], v[152:155], v[208:211], v[58:61]
	v_mfma_f32_16x16x32_bf16 v[54:57], v[144:147], v[216:219], v[54:57]
	v_mfma_f32_16x16x32_bf16 v[50:53], v[152:155], v[216:219], v[50:53]
	v_mfma_f32_16x16x32_bf16 v[38:41], v[144:147], v[224:227], v[38:41]
	v_mfma_f32_16x16x32_bf16 v[34:37], v[152:155], v[224:227], v[34:37]
	v_mfma_f32_16x16x32_bf16 v[22:25], v[144:147], v[232:235], v[22:25]
	v_mfma_f32_16x16x32_bf16 v[18:21], v[152:155], v[232:235], v[18:21]
	s_setprio 0
	s_setprio 1
	v_mfma_f32_16x16x32_bf16 v[46:49], v[158:161], v[204:207], v[46:49]
	v_mfma_f32_16x16x32_bf16 v[42:45], v[196:199], v[204:207], v[42:45]
	v_mfma_f32_16x16x32_bf16 v[30:33], v[158:161], v[212:215], v[30:33]
	v_mfma_f32_16x16x32_bf16 v[26:29], v[196:199], v[212:215], v[26:29]
	v_mfma_f32_16x16x32_bf16 v[14:17], v[158:161], v[220:223], v[14:17]
	v_mfma_f32_16x16x32_bf16 v[10:13], v[196:199], v[220:223], v[10:13]
	v_mfma_f32_16x16x32_bf16 v[6:9], v[158:161], v[228:231], v[6:9]
	v_mfma_f32_16x16x32_bf16 v[2:5], v[196:199], v[228:231], v[2:5]
	s_setprio 0
	s_setprio 1
	v_mfma_f32_16x16x32_bf16 v[46:49], v[162:165], v[208:211], v[46:49]
	v_mfma_f32_16x16x32_bf16 v[42:45], v[200:203], v[208:211], v[42:45]
	v_mfma_f32_16x16x32_bf16 v[30:33], v[162:165], v[216:219], v[30:33]
	v_mfma_f32_16x16x32_bf16 v[26:29], v[200:203], v[216:219], v[26:29]
	v_mfma_f32_16x16x32_bf16 v[14:17], v[162:165], v[224:227], v[14:17]
	v_mfma_f32_16x16x32_bf16 v[10:13], v[200:203], v[224:227], v[10:13]
	v_mfma_f32_16x16x32_bf16 v[6:9], v[162:165], v[232:235], v[6:9]
	v_mfma_f32_16x16x32_bf16 v[2:5], v[200:203], v[232:235], v[2:5]
	s_setprio 0
	s_barrier
	v_add_u32_e32 v139, s62, v137
	ds_read_b128 v[140:143], v139
	ds_read_b128 v[144:147], v139 offset:1024
	ds_read_b128 v[148:151], v139 offset:2048
	ds_read_b128 v[152:155], v139 offset:3072
	v_add_u32_e32 v139, s59, v137
	ds_read_b128 v[158:161], v139
	ds_read_b128 v[162:165], v139 offset:1024
	ds_read_b128 v[196:199], v139 offset:2048
	ds_read_b128 v[200:203], v139 offset:3072
	s_mov_b32 m0, s13
	v_lshl_add_u64 v[244:245], s[44:45], 0, v[130:131]
	ds_read_b128 v[204:207], v138 offset:32768
	ds_read_b128 v[208:211], v138 offset:33792
	ds_read_b128 v[212:215], v138 offset:34816
	ds_read_b128 v[216:219], v138 offset:35840
	ds_read_b128 v[220:223], v138 offset:36864
	ds_read_b128 v[224:227], v138 offset:37888
	ds_read_b128 v[228:231], v138 offset:38912
	ds_read_b128 v[232:235], v138 offset:39936
	global_load_lds_dwordx4 v[244:245], off
	v_lshl_add_u64 v[244:245], s[44:45], 0, v[132:133]
	s_mov_b32 m0, s16
	s_nop 0
	global_load_lds_dwordx4 v[244:245], off
	s_waitcnt vmcnt(8)
	s_waitcnt lgkmcnt(0)
	s_barrier
	s_setprio 1
	s_waitcnt lgkmcnt(0)
	v_mfma_f32_16x16x32_bf16 v[126:129], v[140:143], v[204:207], v[126:129]
	v_mfma_f32_16x16x32_bf16 v[122:125], v[148:151], v[204:207], v[122:125]
	v_mfma_f32_16x16x32_bf16 v[118:121], v[140:143], v[212:215], v[118:121]
	v_mfma_f32_16x16x32_bf16 v[114:117], v[148:151], v[212:215], v[114:117]
	v_mfma_f32_16x16x32_bf16 v[102:105], v[140:143], v[220:223], v[102:105]
	v_mfma_f32_16x16x32_bf16 v[98:101], v[148:151], v[220:223], v[98:101]
	v_mfma_f32_16x16x32_bf16 v[86:89], v[140:143], v[228:231], v[86:89]
	v_mfma_f32_16x16x32_bf16 v[82:85], v[148:151], v[228:231], v[82:85]
	s_setprio 0
	s_setprio 1
	v_mfma_f32_16x16x32_bf16 v[126:129], v[144:147], v[208:211], v[126:129]
	v_mfma_f32_16x16x32_bf16 v[122:125], v[152:155], v[208:211], v[122:125]
	v_mfma_f32_16x16x32_bf16 v[118:121], v[144:147], v[216:219], v[118:121]
	v_mfma_f32_16x16x32_bf16 v[114:117], v[152:155], v[216:219], v[114:117]
	v_mfma_f32_16x16x32_bf16 v[102:105], v[144:147], v[224:227], v[102:105]
	v_mfma_f32_16x16x32_bf16 v[98:101], v[152:155], v[224:227], v[98:101]
	v_mfma_f32_16x16x32_bf16 v[86:89], v[144:147], v[232:235], v[86:89]
	v_mfma_f32_16x16x32_bf16 v[82:85], v[152:155], v[232:235], v[82:85]
	s_setprio 0
	s_setprio 1
	v_mfma_f32_16x16x32_bf16 v[110:113], v[158:161], v[204:207], v[110:113]
	v_mfma_f32_16x16x32_bf16 v[106:109], v[196:199], v[204:207], v[106:109]
	v_mfma_f32_16x16x32_bf16 v[94:97], v[158:161], v[212:215], v[94:97]
	v_mfma_f32_16x16x32_bf16 v[90:93], v[196:199], v[212:215], v[90:93]
	v_mfma_f32_16x16x32_bf16 v[78:81], v[158:161], v[220:223], v[78:81]
	v_mfma_f32_16x16x32_bf16 v[74:77], v[196:199], v[220:223], v[74:77]
	v_mfma_f32_16x16x32_bf16 v[70:73], v[158:161], v[228:231], v[70:73]
	v_mfma_f32_16x16x32_bf16 v[66:69], v[196:199], v[228:231], v[66:69]
	s_setprio 0
	s_setprio 1
	v_mfma_f32_16x16x32_bf16 v[110:113], v[162:165], v[208:211], v[110:113]
	v_mfma_f32_16x16x32_bf16 v[106:109], v[200:203], v[208:211], v[106:109]
	v_mfma_f32_16x16x32_bf16 v[94:97], v[162:165], v[216:219], v[94:97]
	v_mfma_f32_16x16x32_bf16 v[90:93], v[200:203], v[216:219], v[90:93]
	v_mfma_f32_16x16x32_bf16 v[78:81], v[162:165], v[224:227], v[78:81]
	v_mfma_f32_16x16x32_bf16 v[74:77], v[200:203], v[224:227], v[74:77]
	v_mfma_f32_16x16x32_bf16 v[70:73], v[162:165], v[232:235], v[70:73]
	v_mfma_f32_16x16x32_bf16 v[66:69], v[200:203], v[232:235], v[66:69]
	s_setprio 0
	s_barrier
	s_mov_b32 m0, s58
	v_lshl_add_u64 v[236:237], v[236:237], 0, s[24:25]
	ds_read_b128 v[204:207], v138 offset:49152
	ds_read_b128 v[208:211], v138 offset:50176
	ds_read_b128 v[212:215], v138 offset:51200
	ds_read_b128 v[216:219], v138 offset:52224
	ds_read_b128 v[220:223], v138 offset:53248
	ds_read_b128 v[224:227], v138 offset:54272
	ds_read_b128 v[228:231], v138 offset:55296
	ds_read_b128 v[232:235], v138 offset:56320
	global_load_lds_dwordx4 v[236:237], off
	v_lshl_add_u64 v[236:237], v[238:239], 0, s[24:25]
	s_mov_b32 m0, s20
	s_nop 0
	global_load_lds_dwordx4 v[236:237], off
	v_lshl_add_u64 v[236:237], s[42:43], 0, v[0:1]
	s_mov_b32 m0, s84
	s_nop 0
	global_load_lds_dwordx4 v[236:237], off
	v_lshl_add_u64 v[236:237], s[42:43], 0, v[134:135]
	s_mov_b32 m0, s70
	s_nop 0
	global_load_lds_dwordx4 v[236:237], off
	v_lshl_add_u64 v[236:237], v[240:241], 0, s[24:25]
	s_mov_b32 m0, s17
	s_nop 0
	global_load_lds_dwordx4 v[236:237], off
	v_lshl_add_u64 v[236:237], v[242:243], 0, s[24:25]
	s_mov_b32 m0, s28
	s_nop 0
	global_load_lds_dwordx4 v[236:237], off
	s_waitcnt vmcnt(8)
	s_waitcnt lgkmcnt(0)
	s_barrier
	s_setprio 1
	s_waitcnt lgkmcnt(0)
	v_mfma_f32_16x16x32_bf16 v[62:65], v[140:143], v[204:207], v[62:65]
	v_mfma_f32_16x16x32_bf16 v[58:61], v[148:151], v[204:207], v[58:61]
	v_mfma_f32_16x16x32_bf16 v[54:57], v[140:143], v[212:215], v[54:57]
	v_mfma_f32_16x16x32_bf16 v[50:53], v[148:151], v[212:215], v[50:53]
	v_mfma_f32_16x16x32_bf16 v[38:41], v[140:143], v[220:223], v[38:41]
	v_mfma_f32_16x16x32_bf16 v[34:37], v[148:151], v[220:223], v[34:37]
	v_mfma_f32_16x16x32_bf16 v[22:25], v[140:143], v[228:231], v[22:25]
	v_mfma_f32_16x16x32_bf16 v[18:21], v[148:151], v[228:231], v[18:21]
	s_setprio 0
	s_setprio 1
	v_mfma_f32_16x16x32_bf16 v[62:65], v[144:147], v[208:211], v[62:65]
	v_mfma_f32_16x16x32_bf16 v[58:61], v[152:155], v[208:211], v[58:61]
	v_mfma_f32_16x16x32_bf16 v[54:57], v[144:147], v[216:219], v[54:57]
	v_mfma_f32_16x16x32_bf16 v[50:53], v[152:155], v[216:219], v[50:53]
	v_mfma_f32_16x16x32_bf16 v[38:41], v[144:147], v[224:227], v[38:41]
	v_mfma_f32_16x16x32_bf16 v[34:37], v[152:155], v[224:227], v[34:37]
	v_mfma_f32_16x16x32_bf16 v[22:25], v[144:147], v[232:235], v[22:25]
	v_mfma_f32_16x16x32_bf16 v[18:21], v[152:155], v[232:235], v[18:21]
	s_setprio 0
	s_setprio 1
	v_mfma_f32_16x16x32_bf16 v[46:49], v[158:161], v[204:207], v[46:49]
	v_mfma_f32_16x16x32_bf16 v[42:45], v[196:199], v[204:207], v[42:45]
	v_mfma_f32_16x16x32_bf16 v[30:33], v[158:161], v[212:215], v[30:33]
	v_mfma_f32_16x16x32_bf16 v[26:29], v[196:199], v[212:215], v[26:29]
	v_mfma_f32_16x16x32_bf16 v[14:17], v[158:161], v[220:223], v[14:17]
	v_mfma_f32_16x16x32_bf16 v[10:13], v[196:199], v[220:223], v[10:13]
	v_mfma_f32_16x16x32_bf16 v[6:9], v[158:161], v[228:231], v[6:9]
	v_mfma_f32_16x16x32_bf16 v[2:5], v[196:199], v[228:231], v[2:5]
	s_setprio 0
	s_setprio 1
	v_mfma_f32_16x16x32_bf16 v[46:49], v[162:165], v[208:211], v[46:49]
	v_mfma_f32_16x16x32_bf16 v[42:45], v[200:203], v[208:211], v[42:45]
	v_mfma_f32_16x16x32_bf16 v[30:33], v[162:165], v[216:219], v[30:33]
	v_mfma_f32_16x16x32_bf16 v[26:29], v[200:203], v[216:219], v[26:29]
	v_mfma_f32_16x16x32_bf16 v[14:17], v[162:165], v[224:227], v[14:17]
	v_mfma_f32_16x16x32_bf16 v[10:13], v[200:203], v[224:227], v[10:13]
	v_mfma_f32_16x16x32_bf16 v[6:9], v[162:165], v[232:235], v[6:9]
	v_mfma_f32_16x16x32_bf16 v[2:5], v[200:203], v[232:235], v[2:5]
	s_setprio 0
	s_barrier
	s_andn2_b64 vcc, exec, s[40:41]
	s_mov_b64 s[42:43], -1
	s_mov_b64 s[40:41], 0
	s_movk_i32 s20, 0x100
	s_cbranch_vccz .LBB0_1254
	s_waitcnt vmcnt(0)
	s_cmpk_lt_u32 s7, 0x100
	s_cbranch_scc0 .LBB0_1257
	s_barrier

.LBB0_1302:
	s_add_u32 s17, s40, 0xfce78080
	s_addc_u32 s20, s41, -1
	s_cmp_lg_u32 s16, 12
	s_cselect_b32 s17, s17, 0
	s_cselect_b32 s20, s20, 0
	s_add_u32 s44, s6, s17
	s_addc_u32 s45, s7, s20
	s_add_i32 s46, 0, 0x10000
	s_add_u32 s42, s8, s17
	v_add_u32_e32 v143, s46, v141
	s_addc_u32 s43, s9, s20
	s_add_i32 s17, 0, 0x14000
	ds_read_b128 v[144:147], v143
	ds_read_b128 v[148:151], v143 offset:1024
	ds_read_b128 v[152:155], v143 offset:2048
	ds_read_b128 v[158:161], v143 offset:3072
	v_add_u32_e32 v143, s17, v141
	ds_read_b128 v[162:165], v143
	ds_read_b128 v[196:199], v143 offset:1024
	ds_read_b128 v[200:203], v143 offset:2048
	ds_read_b128 v[204:207], v143 offset:3072
	v_lshl_add_u64 v[240:241], v[138:139], 0, s[40:41]
	s_add_i32 m0, s4, 0xc000
	ds_read_b128 v[208:211], v142
	ds_read_b128 v[212:215], v142 offset:1024
	ds_read_b128 v[216:219], v142 offset:2048
	ds_read_b128 v[220:223], v142 offset:3072
	ds_read_b128 v[224:227], v142 offset:4096
	ds_read_b128 v[228:231], v142 offset:5120
	ds_read_b128 v[232:235], v142 offset:6144
	ds_read_b128 v[236:239], v142 offset:7168
	global_load_lds_dwordx4 v[240:241], off
	v_lshl_add_u64 v[240:241], v[136:137], 0, s[40:41]
	s_add_i32 m0, s4, 0xe000
	s_nop 0
	global_load_lds_dwordx4 v[240:241], off
	s_waitcnt vmcnt(8)
	s_waitcnt lgkmcnt(0)
	s_barrier
	s_setprio 1
	s_waitcnt lgkmcnt(0)
	v_mfma_f32_16x16x32_bf16 v[126:129], v[144:147], v[208:211], v[126:129]
	v_mfma_f32_16x16x32_bf16 v[122:125], v[152:155], v[208:211], v[122:125]
	v_mfma_f32_16x16x32_bf16 v[110:113], v[144:147], v[216:219], v[110:113]
	v_mfma_f32_16x16x32_bf16 v[106:109], v[152:155], v[216:219], v[106:109]
	v_mfma_f32_16x16x32_bf16 v[94:97], v[144:147], v[224:227], v[94:97]
	v_mfma_f32_16x16x32_bf16 v[90:93], v[152:155], v[224:227], v[90:93]
	v_mfma_f32_16x16x32_bf16 v[78:81], v[144:147], v[232:235], v[78:81]
	v_mfma_f32_16x16x32_bf16 v[74:77], v[152:155], v[232:235], v[74:77]
	s_setprio 0
	s_setprio 1
	v_mfma_f32_16x16x32_bf16 v[126:129], v[148:151], v[212:215], v[126:129]
	v_mfma_f32_16x16x32_bf16 v[122:125], v[158:161], v[212:215], v[122:125]
	v_mfma_f32_16x16x32_bf16 v[110:113], v[148:151], v[220:223], v[110:113]
	v_mfma_f32_16x16x32_bf16 v[106:109], v[158:161], v[220:223], v[106:109]
	v_mfma_f32_16x16x32_bf16 v[94:97], v[148:151], v[228:231], v[94:97]
	v_mfma_f32_16x16x32_bf16 v[90:93], v[158:161], v[228:231], v[90:93]
	v_mfma_f32_16x16x32_bf16 v[78:81], v[148:151], v[236:239], v[78:81]
	v_mfma_f32_16x16x32_bf16 v[74:77], v[158:161], v[236:239], v[74:77]
	s_setprio 0
	s_setprio 1
	v_mfma_f32_16x16x32_bf16 v[118:121], v[162:165], v[208:211], v[118:121]
	v_mfma_f32_16x16x32_bf16 v[114:117], v[200:203], v[208:211], v[114:117]
	v_mfma_f32_16x16x32_bf16 v[102:105], v[162:165], v[216:219], v[102:105]
	v_mfma_f32_16x16x32_bf16 v[98:101], v[200:203], v[216:219], v[98:101]
	v_mfma_f32_16x16x32_bf16 v[86:89], v[162:165], v[224:227], v[86:89]
	v_mfma_f32_16x16x32_bf16 v[82:85], v[200:203], v[224:227], v[82:85]
	v_mfma_f32_16x16x32_bf16 v[70:73], v[162:165], v[232:235], v[70:73]
	v_mfma_f32_16x16x32_bf16 v[66:69], v[200:203], v[232:235], v[66:69]
	s_setprio 0
	s_setprio 1
	v_mfma_f32_16x16x32_bf16 v[118:121], v[196:199], v[212:215], v[118:121]
	v_mfma_f32_16x16x32_bf16 v[114:117], v[204:207], v[212:215], v[114:117]
	v_mfma_f32_16x16x32_bf16 v[102:105], v[196:199], v[220:223], v[102:105]
	v_mfma_f32_16x16x32_bf16 v[98:101], v[204:207], v[220:223], v[98:101]
	v_mfma_f32_16x16x32_bf16 v[86:89], v[196:199], v[228:231], v[86:89]
	v_mfma_f32_16x16x32_bf16 v[82:85], v[204:207], v[228:231], v[82:85]
	v_mfma_f32_16x16x32_bf16 v[70:73], v[196:199], v[236:239], v[70:73]
	v_mfma_f32_16x16x32_bf16 v[66:69], v[204:207], v[236:239], v[66:69]
	s_setprio 0
	s_barrier
	s_add_i32 s20, s46, s3
	v_lshl_add_u64 v[240:241], s[42:43], 0, v[0:1]
	s_mov_b32 m0, s20
	ds_read_b128 v[208:211], v142 offset:16384
	ds_read_b128 v[212:215], v142 offset:17408
	ds_read_b128 v[216:219], v142 offset:18432
	ds_read_b128 v[220:223], v142 offset:19456
	ds_read_b128 v[224:227], v142 offset:20480
	ds_read_b128 v[228:231], v142 offset:21504
	ds_read_b128 v[232:235], v142 offset:22528
	ds_read_b128 v[236:239], v142 offset:23552
	global_load_lds_dwordx4 v[240:241], off
	s_add_i32 m0, s20, 0x2000
	s_add_u32 s46, s42, 0x10000
	v_lshl_add_u64 v[242:243], s[42:43], 0, v[134:135]
	s_addc_u32 s47, s43, 0
	s_add_i32 s17, s17, s3
	global_load_lds_dwordx4 v[242:243], off
	v_lshl_add_u64 v[244:245], s[46:47], 0, v[0:1]
	s_mov_b32 m0, s17
	v_lshl_add_u64 v[246:247], s[44:45], 0, v[132:133]
	global_load_lds_dwordx4 v[244:245], off
	v_lshl_add_u64 v[244:245], s[46:47], 0, v[134:135]
	s_add_i32 m0, s17, 0x2000
	s_nop 0
	global_load_lds_dwordx4 v[244:245], off
	v_lshl_add_u64 v[244:245], s[44:45], 0, v[130:131]
	s_mov_b32 m0, s4
	s_nop 0
	global_load_lds_dwordx4 v[244:245], off
	s_mov_b32 m0, s5
	s_nop 0
	global_load_lds_dwordx4 v[246:247], off
	s_waitcnt vmcnt(8)
	s_waitcnt lgkmcnt(0)
	s_barrier
	s_setprio 1
	s_waitcnt lgkmcnt(0)
	v_mfma_f32_16x16x32_bf16 v[62:65], v[144:147], v[208:211], v[62:65]
	v_mfma_f32_16x16x32_bf16 v[58:61], v[152:155], v[208:211], v[58:61]
	v_mfma_f32_16x16x32_bf16 v[46:49], v[144:147], v[216:219], v[46:49]
	v_mfma_f32_16x16x32_bf16 v[42:45], v[152:155], v[216:219], v[42:45]
	v_mfma_f32_16x16x32_bf16 v[30:33], v[144:147], v[224:227], v[30:33]
	v_mfma_f32_16x16x32_bf16 v[26:29], v[152:155], v[224:227], v[26:29]
	v_mfma_f32_16x16x32_bf16 v[14:17], v[144:147], v[232:235], v[14:17]
	v_mfma_f32_16x16x32_bf16 v[10:13], v[152:155], v[232:235], v[10:13]
	s_setprio 0
	s_setprio 1
	v_mfma_f32_16x16x32_bf16 v[62:65], v[148:151], v[212:215], v[62:65]
	v_mfma_f32_16x16x32_bf16 v[58:61], v[158:161], v[212:215], v[58:61]
	v_mfma_f32_16x16x32_bf16 v[46:49], v[148:151], v[220:223], v[46:49]
	v_mfma_f32_16x16x32_bf16 v[42:45], v[158:161], v[220:223], v[42:45]
	v_mfma_f32_16x16x32_bf16 v[30:33], v[148:151], v[228:231], v[30:33]
	v_mfma_f32_16x16x32_bf16 v[26:29], v[158:161], v[228:231], v[26:29]
	v_mfma_f32_16x16x32_bf16 v[14:17], v[148:151], v[236:239], v[14:17]
	v_mfma_f32_16x16x32_bf16 v[10:13], v[158:161], v[236:239], v[10:13]
	s_setprio 0
	s_setprio 1
	v_mfma_f32_16x16x32_bf16 v[54:57], v[162:165], v[208:211], v[54:57]
	v_mfma_f32_16x16x32_bf16 v[50:53], v[200:203], v[208:211], v[50:53]
	v_mfma_f32_16x16x32_bf16 v[38:41], v[162:165], v[216:219], v[38:41]
	v_mfma_f32_16x16x32_bf16 v[34:37], v[200:203], v[216:219], v[34:37]
	v_mfma_f32_16x16x32_bf16 v[22:25], v[162:165], v[224:227], v[22:25]
	v_mfma_f32_16x16x32_bf16 v[18:21], v[200:203], v[224:227], v[18:21]
	v_mfma_f32_16x16x32_bf16 v[6:9], v[162:165], v[232:235], v[6:9]
	v_mfma_f32_16x16x32_bf16 v[2:5], v[200:203], v[232:235], v[2:5]
	s_setprio 0
	s_setprio 1
	v_mfma_f32_16x16x32_bf16 v[54:57], v[196:199], v[212:215], v[54:57]
	v_mfma_f32_16x16x32_bf16 v[50:53], v[204:207], v[212:215], v[50:53]
	v_mfma_f32_16x16x32_bf16 v[38:41], v[196:199], v[220:223], v[38:41]
	v_mfma_f32_16x16x32_bf16 v[34:37], v[204:207], v[220:223], v[34:37]
	v_mfma_f32_16x16x32_bf16 v[22:25], v[196:199], v[228:231], v[22:25]
	v_mfma_f32_16x16x32_bf16 v[18:21], v[204:207], v[228:231], v[18:21]
	v_mfma_f32_16x16x32_bf16 v[6:9], v[196:199], v[236:239], v[6:9]
	v_mfma_f32_16x16x32_bf16 v[2:5], v[204:207], v[236:239], v[2:5]
	s_setprio 0
	s_barrier
	s_add_i32 s17, 0, 0x18000
	v_add_u32_e32 v143, s17, v141
	s_add_i32 s20, 0, 0x1c000
	ds_read_b128 v[144:147], v143
	ds_read_b128 v[148:151], v143 offset:1024
	ds_read_b128 v[152:155], v143 offset:2048
	ds_read_b128 v[158:161], v143 offset:3072
	v_add_u32_e32 v143, s20, v141
	ds_read_b128 v[162:165], v143
	ds_read_b128 v[196:199], v143 offset:1024
	ds_read_b128 v[200:203], v143 offset:2048
	ds_read_b128 v[204:207], v143 offset:3072
	s_add_u32 s44, s44, 0x40000
	s_addc_u32 s45, s45, 0
	s_mov_b32 m0, s10
	v_lshl_add_u64 v[248:249], s[44:45], 0, v[130:131]
	ds_read_b128 v[208:211], v142 offset:32768
	ds_read_b128 v[212:215], v142 offset:33792
	ds_read_b128 v[216:219], v142 offset:34816
	ds_read_b128 v[220:223], v142 offset:35840
	ds_read_b128 v[224:227], v142 offset:36864
	ds_read_b128 v[228:231], v142 offset:37888
	ds_read_b128 v[232:235], v142 offset:38912
	ds_read_b128 v[236:239], v142 offset:39936
	global_load_lds_dwordx4 v[248:249], off
	v_lshl_add_u64 v[248:249], s[44:45], 0, v[132:133]
	s_mov_b32 m0, s11
	s_nop 0
	global_load_lds_dwordx4 v[248:249], off
	s_waitcnt vmcnt(8)
	s_waitcnt lgkmcnt(0)
	s_barrier
	s_setprio 1
	s_waitcnt lgkmcnt(0)
	v_mfma_f32_16x16x32_bf16 v[126:129], v[144:147], v[208:211], v[126:129]
	v_mfma_f32_16x16x32_bf16 v[122:125], v[152:155], v[208:211], v[122:125]
	v_mfma_f32_16x16x32_bf16 v[110:113], v[144:147], v[216:219], v[110:113]
	v_mfma_f32_16x16x32_bf16 v[106:109], v[152:155], v[216:219], v[106:109]
	v_mfma_f32_16x16x32_bf16 v[94:97], v[144:147], v[224:227], v[94:97]
	v_mfma_f32_16x16x32_bf16 v[90:93], v[152:155], v[224:227], v[90:93]
	v_mfma_f32_16x16x32_bf16 v[78:81], v[144:147], v[232:235], v[78:81]
	v_mfma_f32_16x16x32_bf16 v[74:77], v[152:155], v[232:235], v[74:77]
	s_setprio 0
	s_setprio 1
	v_mfma_f32_16x16x32_bf16 v[126:129], v[148:151], v[212:215], v[126:129]
	v_mfma_f32_16x16x32_bf16 v[122:125], v[158:161], v[212:215], v[122:125]
	v_mfma_f32_16x16x32_bf16 v[110:113], v[148:151], v[220:223], v[110:113]
	v_mfma_f32_16x16x32_bf16 v[106:109], v[158:161], v[220:223], v[106:109]
	v_mfma_f32_16x16x32_bf16 v[94:97], v[148:151], v[228:231], v[94:97]
	v_mfma_f32_16x16x32_bf16 v[90:93], v[158:161], v[228:231], v[90:93]
	v_mfma_f32_16x16x32_bf16 v[78:81], v[148:151], v[236:239], v[78:81]
	v_mfma_f32_16x16x32_bf16 v[74:77], v[158:161], v[236:239], v[74:77]
	s_setprio 0
	s_setprio 1
	v_mfma_f32_16x16x32_bf16 v[118:121], v[162:165], v[208:211], v[118:121]
	v_mfma_f32_16x16x32_bf16 v[114:117], v[200:203], v[208:211], v[114:117]
	v_mfma_f32_16x16x32_bf16 v[102:105], v[162:165], v[216:219], v[102:105]
	v_mfma_f32_16x16x32_bf16 v[98:101], v[200:203], v[216:219], v[98:101]
	v_mfma_f32_16x16x32_bf16 v[86:89], v[162:165], v[224:227], v[86:89]
	v_mfma_f32_16x16x32_bf16 v[82:85], v[200:203], v[224:227], v[82:85]
	v_mfma_f32_16x16x32_bf16 v[70:73], v[162:165], v[232:235], v[70:73]
	v_mfma_f32_16x16x32_bf16 v[66:69], v[200:203], v[232:235], v[66:69]
	s_setprio 0
	s_setprio 1
	v_mfma_f32_16x16x32_bf16 v[118:121], v[196:199], v[212:215], v[118:121]
	v_mfma_f32_16x16x32_bf16 v[114:117], v[204:207], v[212:215], v[114:117]
	v_mfma_f32_16x16x32_bf16 v[102:105], v[196:199], v[220:223], v[102:105]
	v_mfma_f32_16x16x32_bf16 v[98:101], v[204:207], v[220:223], v[98:101]
	v_mfma_f32_16x16x32_bf16 v[86:89], v[196:199], v[228:231], v[86:89]
	v_mfma_f32_16x16x32_bf16 v[82:85], v[204:207], v[228:231], v[82:85]
	v_mfma_f32_16x16x32_bf16 v[70:73], v[196:199], v[236:239], v[70:73]
	v_mfma_f32_16x16x32_bf16 v[66:69], v[204:207], v[236:239], v[66:69]
	s_setprio 0
	s_barrier
	s_add_i32 s17, s17, s3
	v_lshl_add_u64 v[240:241], v[240:241], 0, s[24:25]
	s_mov_b32 m0, s17
	ds_read_b128 v[208:211], v142 offset:49152
	ds_read_b128 v[212:215], v142 offset:50176
	ds_read_b128 v[216:219], v142 offset:51200
	ds_read_b128 v[220:223], v142 offset:52224
	ds_read_b128 v[224:227], v142 offset:53248
	ds_read_b128 v[228:231], v142 offset:54272
	ds_read_b128 v[232:235], v142 offset:55296
	ds_read_b128 v[236:239], v142 offset:56320
	global_load_lds_dwordx4 v[240:241], off
	s_add_i32 m0, s17, 0x2000
	s_add_u32 s42, s42, 0x10080
	v_lshl_add_u64 v[240:241], v[242:243], 0, s[24:25]
	s_addc_u32 s43, s43, 0
	s_add_i32 s17, s20, s3
	global_load_lds_dwordx4 v[240:241], off
	v_lshl_add_u64 v[240:241], s[42:43], 0, v[0:1]
	s_mov_b32 m0, s17
	s_nop 0
	global_load_lds_dwordx4 v[240:241], off
	v_lshl_add_u64 v[240:241], s[42:43], 0, v[134:135]
	s_add_i32 m0, s17, 0x2000
	s_nop 0
	global_load_lds_dwordx4 v[240:241], off
	v_lshl_add_u64 v[240:241], v[244:245], 0, s[24:25]
	s_mov_b32 m0, s12
	s_nop 0
	global_load_lds_dwordx4 v[240:241], off
	v_lshl_add_u64 v[240:241], v[246:247], 0, s[24:25]
	s_mov_b32 m0, s13
	s_nop 0
	global_load_lds_dwordx4 v[240:241], off
	s_waitcnt vmcnt(8)
	s_waitcnt lgkmcnt(0)
	s_barrier
	s_setprio 1
	s_waitcnt lgkmcnt(0)
	v_mfma_f32_16x16x32_bf16 v[62:65], v[144:147], v[208:211], v[62:65]
	v_mfma_f32_16x16x32_bf16 v[58:61], v[152:155], v[208:211], v[58:61]
	v_mfma_f32_16x16x32_bf16 v[46:49], v[144:147], v[216:219], v[46:49]
	v_mfma_f32_16x16x32_bf16 v[42:45], v[152:155], v[216:219], v[42:45]
	v_mfma_f32_16x16x32_bf16 v[30:33], v[144:147], v[224:227], v[30:33]
	v_mfma_f32_16x16x32_bf16 v[26:29], v[152:155], v[224:227], v[26:29]
	v_mfma_f32_16x16x32_bf16 v[14:17], v[144:147], v[232:235], v[14:17]
	v_mfma_f32_16x16x32_bf16 v[10:13], v[152:155], v[232:235], v[10:13]
	s_setprio 0
	s_setprio 1
	v_mfma_f32_16x16x32_bf16 v[62:65], v[148:151], v[212:215], v[62:65]
	v_mfma_f32_16x16x32_bf16 v[58:61], v[158:161], v[212:215], v[58:61]
	v_mfma_f32_16x16x32_bf16 v[46:49], v[148:151], v[220:223], v[46:49]
	v_mfma_f32_16x16x32_bf16 v[42:45], v[158:161], v[220:223], v[42:45]
	v_mfma_f32_16x16x32_bf16 v[30:33], v[148:151], v[228:231], v[30:33]
	v_mfma_f32_16x16x32_bf16 v[26:29], v[158:161], v[228:231], v[26:29]
	v_mfma_f32_16x16x32_bf16 v[14:17], v[148:151], v[236:239], v[14:17]
	v_mfma_f32_16x16x32_bf16 v[10:13], v[158:161], v[236:239], v[10:13]
	s_setprio 0
	s_setprio 1
	v_mfma_f32_16x16x32_bf16 v[54:57], v[162:165], v[208:211], v[54:57]
	v_mfma_f32_16x16x32_bf16 v[50:53], v[200:203], v[208:211], v[50:53]
	v_mfma_f32_16x16x32_bf16 v[38:41], v[162:165], v[216:219], v[38:41]
	v_mfma_f32_16x16x32_bf16 v[34:37], v[200:203], v[216:219], v[34:37]
	v_mfma_f32_16x16x32_bf16 v[22:25], v[162:165], v[224:227], v[22:25]
	v_mfma_f32_16x16x32_bf16 v[18:21], v[200:203], v[224:227], v[18:21]
	v_mfma_f32_16x16x32_bf16 v[6:9], v[162:165], v[232:235], v[6:9]
	v_mfma_f32_16x16x32_bf16 v[2:5], v[200:203], v[232:235], v[2:5]
	s_setprio 0
	s_setprio 1
	v_mfma_f32_16x16x32_bf16 v[54:57], v[196:199], v[212:215], v[54:57]
	v_mfma_f32_16x16x32_bf16 v[50:53], v[204:207], v[212:215], v[50:53]
	v_mfma_f32_16x16x32_bf16 v[38:41], v[196:199], v[220:223], v[38:41]
	v_mfma_f32_16x16x32_bf16 v[34:37], v[204:207], v[220:223], v[34:37]
	v_mfma_f32_16x16x32_bf16 v[22:25], v[196:199], v[228:231], v[22:25]
	v_mfma_f32_16x16x32_bf16 v[18:21], v[204:207], v[228:231], v[18:21]
	v_mfma_f32_16x16x32_bf16 v[6:9], v[196:199], v[236:239], v[6:9]
	v_mfma_f32_16x16x32_bf16 v[2:5], v[204:207], v[236:239], v[2:5]
	s_setprio 0
	s_barrier
	s_add_i32 s16, s16, 2
	s_add_u32 s40, s40, 0x100
	s_addc_u32 s41, s41, 0
	s_cmp_gt_u32 s16, 13
	s_cbranch_scc0 .LBB0_1302
	s_waitcnt vmcnt(0)
	s_mov_b32 s12, s58
	s_cmpk_lt_u32 s1, 0x100
	s_cbranch_scc0 .LBB0_1305
	s_barrier
